# speedup vs baseline: 1.0135x; 1.0135x over previous
; #define MFMA(a, b, c) __builtin_amdgcn_mfma_f32_16x16x32_bf16((a), (b), (c), 0, 0, 0)
; template <int AMODE>
; __device__ __forceinline__ void gemm_kloop(f32x4 (&acc)[4][4], const u16* __restrict__ A, int lda,
;                                            const u16* __restrict__ Bt, int ldb, int K, char* smem,
;                                            const float* __restrict__ ssq_rows) {
;     ...
;     for (int kt = 0; kt < nk; ++kt) {
;         const int buf = kt & 1;
;         if (kt + 1 < nk) GLOAD(kt + 1, buf ^ 1);
;         const char* ab = As + buf * 16384 + (wr * 64 + r) * 128;
;         const char* bb = Bs + buf * 16384 + (wc * 64 + r) * 128;
;         bf16x8 af[2][4], bfr[2][4];
; #pragma unroll
;         for (int ks = 0; ks < 2; ++ks) {
;             const int co = ((ks * 4 + g4) ^ (r & 7)) << 4;
; #pragma unroll
;             for (int i = 0; i < 4; ++i) af[ks][i] = ld_frag(ab + i * 2048 + co);
; #pragma unroll
;             for (int j = 0; j < 4; ++j) bfr[ks][j] = ld_frag(bb + j * 2048 + co);
;         }
;         __builtin_amdgcn_sched_barrier(0);
;         __builtin_amdgcn_s_setprio(1);
; #pragma unroll
;         for (int ks = 0; ks < 2; ++ks)
; #pragma unroll
;             for (int i = 0; i < 4; ++i)
; #pragma unroll
;                 for (int j = 0; j < 4; ++j) acc[i][j] = MFMA(bfr[ks][j], af[ks][i], acc[i][j]);
;         __builtin_amdgcn_s_setprio(0);
;         __builtin_amdgcn_sched_barrier(0);
;         if (kt + 1 < nk) LSTORE(buf ^ 1);
;         asm volatile("s_waitcnt vmcnt(0)" ::: "memory");
;         __syncthreads();
;     }
.LBB0_152:
	s_setprio 1
	v_add_u32_e32 v0, s2, v73
	v_or_b32_e32 v77, s2, v72
	v_add_u32_e32 v90, v0, v76
	v_add_u32_e32 v102, v77, v76
	v_add_u32_e32 v0, v0, v74
	s_xor_b32 s4, s2, 0x4000
	s_add_u32 s4, s4, s5
	s_add_u32 s100, s100, 0x80
	s_addc_u32 s101, s101, 0
	s_add_u32 s98, s98, 0x80
	s_addc_u32 s99, s99, 0
	s_add_u32 m0, s4, 0x8000
	ds_read_b128 v[78:81], v90
	global_load_lds_dwordx4 v216, s[100:101]
	ds_read_b128 v[82:85], v90 offset:2048
	s_add_u32 m0, s4, 0x0
	ds_read_b128 v[86:89], v90 offset:4096
	global_load_lds_dwordx4 v216, s[98:99]
	ds_read_b128 v[90:93], v90 offset:6144
	s_add_u32 m0, s4, 0x9000
	ds_read_b128 v[94:97], v102 offset:32768
	global_load_lds_dwordx4 v217, s[100:101]
	ds_read_b128 v[98:101], v102 offset:34816
	s_add_u32 m0, s4, 0x1000
	ds_read_b128 v[110:113], v102 offset:36864
	global_load_lds_dwordx4 v217, s[98:99]
	ds_read_b128 v[114:117], v102 offset:38912
	s_add_u32 m0, s4, 0xa000
	ds_read_b128 v[118:121], v0
	global_load_lds_dwordx4 v218, s[100:101]
	ds_read_b128 v[122:125], v0 offset:2048
	s_add_u32 m0, s4, 0x2000
	ds_read_b128 v[126:129], v0 offset:4096
	global_load_lds_dwordx4 v218, s[98:99]
	ds_read_b128 v[130:133], v0 offset:6144
	s_add_u32 m0, s4, 0xb000
	v_add_u32_e32 v0, v77, v74
	global_load_lds_dwordx4 v219, s[100:101]
	ds_read_b128 v[134:137], v0 offset:32768
	s_add_u32 m0, s4, 0x3000
	ds_read_b128 v[142:145], v0 offset:34816
	global_load_lds_dwordx4 v219, s[98:99]
	ds_read_b128 v[146:149], v0 offset:36864
	ds_read_b128 v[150:153], v0 offset:38912
	s_setprio 0
	s_waitcnt lgkmcnt(11)
	v_mfma_f32_16x16x32_bf16 v[62:65], v[94:97], v[78:81], v[62:65]
	s_waitcnt lgkmcnt(10)
	v_mfma_f32_16x16x32_bf16 v[58:61], v[98:101], v[78:81], v[58:61]
	s_waitcnt lgkmcnt(9)
	v_mfma_f32_16x16x32_bf16 v[54:57], v[110:113], v[78:81], v[54:57]
	s_waitcnt lgkmcnt(8)
	v_mfma_f32_16x16x32_bf16 v[50:53], v[114:117], v[78:81], v[50:53]
	v_mfma_f32_16x16x32_bf16 v[46:49], v[94:97], v[82:85], v[46:49]
	v_mfma_f32_16x16x32_bf16 v[42:45], v[98:101], v[82:85], v[42:45]
	v_mfma_f32_16x16x32_bf16 v[38:41], v[110:113], v[82:85], v[38:41]
	v_mfma_f32_16x16x32_bf16 v[34:37], v[114:117], v[82:85], v[34:37]
	v_mfma_f32_16x16x32_bf16 v[30:33], v[94:97], v[86:89], v[30:33]
	v_mfma_f32_16x16x32_bf16 v[26:29], v[98:101], v[86:89], v[26:29]
	v_mfma_f32_16x16x32_bf16 v[22:25], v[110:113], v[86:89], v[22:25]
	v_mfma_f32_16x16x32_bf16 v[18:21], v[114:117], v[86:89], v[18:21]
	v_mfma_f32_16x16x32_bf16 v[14:17], v[94:97], v[90:93], v[14:17]
	v_mfma_f32_16x16x32_bf16 v[10:13], v[98:101], v[90:93], v[10:13]
	v_mfma_f32_16x16x32_bf16 v[6:9], v[110:113], v[90:93], v[6:9]
	v_mfma_f32_16x16x32_bf16 v[2:5], v[114:117], v[90:93], v[2:5]
	s_waitcnt lgkmcnt(3)
	v_mfma_f32_16x16x32_bf16 v[62:65], v[134:137], v[118:121], v[62:65]
	s_waitcnt lgkmcnt(2)
	v_mfma_f32_16x16x32_bf16 v[58:61], v[142:145], v[118:121], v[58:61]
	s_waitcnt lgkmcnt(1)
	v_mfma_f32_16x16x32_bf16 v[54:57], v[146:149], v[118:121], v[54:57]
	s_waitcnt lgkmcnt(0)
	v_mfma_f32_16x16x32_bf16 v[50:53], v[150:153], v[118:121], v[50:53]
	v_mfma_f32_16x16x32_bf16 v[46:49], v[134:137], v[122:125], v[46:49]
	v_mfma_f32_16x16x32_bf16 v[42:45], v[142:145], v[122:125], v[42:45]
	v_mfma_f32_16x16x32_bf16 v[38:41], v[146:149], v[122:125], v[38:41]
	v_mfma_f32_16x16x32_bf16 v[34:37], v[150:153], v[122:125], v[34:37]
	v_mfma_f32_16x16x32_bf16 v[30:33], v[134:137], v[126:129], v[30:33]
	v_mfma_f32_16x16x32_bf16 v[26:29], v[142:145], v[126:129], v[26:29]
	v_mfma_f32_16x16x32_bf16 v[22:25], v[146:149], v[126:129], v[22:25]
	v_mfma_f32_16x16x32_bf16 v[18:21], v[150:153], v[126:129], v[18:21]
	v_mfma_f32_16x16x32_bf16 v[14:17], v[134:137], v[130:133], v[14:17]
	v_mfma_f32_16x16x32_bf16 v[10:13], v[142:145], v[130:133], v[10:13]
	v_mfma_f32_16x16x32_bf16 v[6:9], v[146:149], v[130:133], v[6:9]
	v_mfma_f32_16x16x32_bf16 v[2:5], v[150:153], v[130:133], v[2:5]
	s_nop 0
	s_xor_b32 s2, s2, 0x4000
	s_add_i32 s0, s0, 1
	s_cmp_eq_u32 s0, 15
	s_waitcnt vmcnt(0)
	s_barrier
	s_cbranch_scc0 .LBB0_152
	v_add_u32_e32 v0, v73, v76
	ds_read_b128 v[66:69], v0 offset:16384
	ds_read_b128 v[78:81], v0 offset:18432
	ds_read_b128 v[82:85], v0 offset:20480
	ds_read_b128 v[86:89], v0 offset:22528
	v_add_u32_e32 v0, v72, v76
	ds_read_b128 v[90:93], v0 offset:49152
	ds_read_b128 v[98:101], v0 offset:51200
	ds_read_b128 v[110:113], v0 offset:53248
	ds_read_b128 v[114:117], v0 offset:55296
	v_add_u32_e32 v0, v73, v74
	ds_read_b128 v[118:121], v0 offset:16384
	ds_read_b128 v[122:125], v0 offset:18432
	ds_read_b128 v[126:129], v0 offset:20480
	ds_read_b128 v[130:133], v0 offset:22528
	v_add_u32_e32 v0, v72, v74
	ds_read_b128 v[134:137], v0 offset:49152
	ds_read_b128 v[142:145], v0 offset:51200
	ds_read_b128 v[146:149], v0 offset:53248
	ds_read_b128 v[150:153], v0 offset:55296
	v_ashrrev_i32_e32 v96, 7, v70
	v_and_b32_e32 v72, 15, v70
	v_bfe_u32 v74, v70, 6, 1
	v_bfe_u32 v73, v70, 4, 2
	s_setprio 1
	s_waitcnt lgkmcnt(11)
	v_mfma_f32_16x16x32_bf16 v[62:65], v[90:93], v[66:69], v[62:65]
	s_waitcnt lgkmcnt(10)
	v_mfma_f32_16x16x32_bf16 v[58:61], v[98:101], v[66:69], v[58:61]
	s_waitcnt lgkmcnt(9)
	v_mfma_f32_16x16x32_bf16 v[54:57], v[110:113], v[66:69], v[54:57]
	s_waitcnt lgkmcnt(8)
	v_mfma_f32_16x16x32_bf16 v[50:53], v[114:117], v[66:69], v[50:53]
	v_mfma_f32_16x16x32_bf16 v[46:49], v[90:93], v[78:81], v[46:49]
	v_mfma_f32_16x16x32_bf16 v[42:45], v[98:101], v[78:81], v[42:45]
	v_mfma_f32_16x16x32_bf16 v[38:41], v[110:113], v[78:81], v[38:41]
	v_mfma_f32_16x16x32_bf16 v[34:37], v[114:117], v[78:81], v[34:37]
	v_mfma_f32_16x16x32_bf16 v[30:33], v[90:93], v[82:85], v[30:33]
	v_mfma_f32_16x16x32_bf16 v[26:29], v[98:101], v[82:85], v[26:29]
	v_mfma_f32_16x16x32_bf16 v[22:25], v[110:113], v[82:85], v[22:25]
	v_mfma_f32_16x16x32_bf16 v[18:21], v[114:117], v[82:85], v[18:21]
	v_mfma_f32_16x16x32_bf16 v[14:17], v[90:93], v[86:89], v[14:17]
	v_mfma_f32_16x16x32_bf16 v[10:13], v[98:101], v[86:89], v[10:13]
	v_mfma_f32_16x16x32_bf16 v[6:9], v[110:113], v[86:89], v[6:9]
	v_mfma_f32_16x16x32_bf16 v[2:5], v[114:117], v[86:89], v[2:5]
	s_waitcnt lgkmcnt(3)
; __device__ __forceinline__ float softplusf(float x) { return fmaxf(x, 0.f) + log1pf(__expf(-fabsf(x))); }
; #define MFMA(a, b, c) __builtin_amdgcn_mfma_f32_16x16x32_bf16((a), (b), (c), 0, 0, 0)
; template <int AMODE>
; __device__ __forceinline__ void gemm_kloop(f32x4 (&acc)[4][4], const u16* __restrict__ A, int lda,
;                                            const u16* __restrict__ Bt, int ldb, int K, char* smem,
;                                            const float* __restrict__ ssq_rows) {
;     ...
;         for (int ks = 0; ks < 2; ++ks)
; #pragma unroll
;             for (int i = 0; i < 4; ++i)
; #pragma unroll
;                 for (int j = 0; j < 4; ++j) acc[i][j] = MFMA(bfr[ks][j], af[ks][i], acc[i][j]);
;         __builtin_amdgcn_s_setprio(0);
;         __builtin_amdgcn_sched_barrier(0);
;         if (kt + 1 < nk) LSTORE(buf ^ 1);
;         asm volatile("s_waitcnt vmcnt(0)" ::: "memory");
;         __syncthreads();
;     }
; __device__ void phaseA_tile(const Params& p, int l, int mt, int nt, char* smem) {
;     ...
;     } else {
;         float* lf_s = (float*)smem;
;         if (wc == 0) {
; #pragma unroll
;             for (int i = 0; i < 4; ++i) {
;                 const int rl = wr * 64 + i * 16 + r;
;                 const int row = m0 + rl;
; #pragma unroll
;                 for (int j = 0; j < 2; ++j) {
;                     const int c = j * 16 + g4 * 4;
;                     const float4 db = *(const float4*)(p.dt_bias + l * 32 + c);
;                     const f32x4 v = acc[i][j];
;                     *(float4*)(p.dtb + (size_t)row * 32 + c) =
;                         make_float4(softplusf(v[0] + db.x), softplusf(v[1] + db.y), softplusf(v[2] + db.z), softplusf(v[3] + db.w));
	v_mfma_f32_16x16x32_bf16 v[62:65], v[134:137], v[118:121], v[62:65]
	s_waitcnt lgkmcnt(2)
	v_mfma_f32_16x16x32_bf16 v[58:61], v[142:145], v[118:121], v[58:61]
	s_waitcnt lgkmcnt(1)
	v_mfma_f32_16x16x32_bf16 v[54:57], v[146:149], v[118:121], v[54:57]
	s_waitcnt lgkmcnt(0)
	v_mfma_f32_16x16x32_bf16 v[50:53], v[150:153], v[118:121], v[50:53]
	v_mfma_f32_16x16x32_bf16 v[46:49], v[134:137], v[122:125], v[46:49]
	v_mfma_f32_16x16x32_bf16 v[42:45], v[142:145], v[122:125], v[42:45]
	v_mfma_f32_16x16x32_bf16 v[38:41], v[146:149], v[122:125], v[38:41]
	v_mfma_f32_16x16x32_bf16 v[34:37], v[150:153], v[122:125], v[34:37]
	v_mfma_f32_16x16x32_bf16 v[30:33], v[134:137], v[126:129], v[30:33]
	v_mfma_f32_16x16x32_bf16 v[26:29], v[142:145], v[126:129], v[26:29]
	v_mfma_f32_16x16x32_bf16 v[22:25], v[146:149], v[126:129], v[22:25]
	v_mfma_f32_16x16x32_bf16 v[18:21], v[150:153], v[126:129], v[18:21]
	v_mfma_f32_16x16x32_bf16 v[14:17], v[134:137], v[130:133], v[14:17]
	v_mfma_f32_16x16x32_bf16 v[10:13], v[142:145], v[130:133], v[10:13]
	v_mfma_f32_16x16x32_bf16 v[6:9], v[146:149], v[130:133], v[6:9]
	v_mfma_f32_16x16x32_bf16 v[2:5], v[150:153], v[130:133], v[2:5]
	s_setprio 0
	s_waitcnt vmcnt(0)
	s_cmpk_eq_i32 s52, 0x100
	s_cselect_b64 s[60:61], -1, 0
	s_cmpk_lg_i32 s52, 0x100
	s_cselect_b64 s[24:25], -1, 0
	s_cmpk_gt_i32 s53, 0x5f
	s_mov_b64 s[0:1], -1
	s_barrier
	s_cbranch_scc0 .LBB0_182
	v_cmp_eq_u32_e32 vcc, 0, v74
	s_and_saveexec_b64 s[4:5], vcc
	s_cbranch_execz .LBB0_156
	v_lshlrev_b32_e32 v0, 4, v73
	global_load_dwordx4 v[66:69], v0, s[74:75]
	s_mov_b32 s2, 0xbfb8aa3b
	s_mov_b32 s26, 0x3f2aaaab
	s_mov_b32 s0, 0x3ecc95a3
	s_mov_b32 s28, 0x3e9b6dac
	s_mov_b32 s30, 0x3f2aaada
	v_lshl_or_b32 v71, v96, 6, v72
	v_add_u32_e32 v76, s54, v71
	v_ashrrev_i32_e32 v77, 31, v76
	v_readlane_b32 s8, v213, 4
	v_lshlrev_b64 v[80:81], 7, v[76:77]
	v_readlane_b32 s10, v213, 6
	v_readlane_b32 s11, v213, 7
	v_readlane_b32 s12, v213, 8
	v_readlane_b32 s13, v213, 9
	s_mov_b32 s12, 0x3f317218
	v_readlane_b32 s14, v213, 10
	v_readlane_b32 s15, v213, 11
	s_mov_b32 s14, 0xb102e308
	s_mov_b32 s8, 0x7f800000
	v_readlane_b32 s9, v213, 5
	s_mov_b32 s9, 0x33800000
	v_readlane_b32 s16, v213, 12
	v_readlane_b32 s17, v213, 13
	v_readlane_b32 s18, v213, 14
	v_readlane_b32 s19, v213, 15
	v_readlane_b32 s20, v213, 16
	v_readlane_b32 s21, v213, 17
	v_readlane_b32 s22, v213, 18
	v_readlane_b32 s23, v213, 19
	s_waitcnt vmcnt(0)
	v_add_f32_e32 v66, v62, v66
	v_max_f32_e32 v78, 0, v66
	v_mul_f32_e64 v66, |v66|, s2
	v_exp_f32_e32 v97, v66
	v_add_f32_e32 v67, v63, v67
	v_add_f32_e32 v68, v64, v68
	v_add_f32_e32 v69, v65, v69
	v_add_f32_e32 v66, 1.0, v97
	v_add_f32_e32 v79, -1.0, v66
	v_sub_f32_e32 v82, v79, v66
	v_add_f32_e32 v82, 1.0, v82
	v_sub_f32_e32 v79, v97, v79
	v_add_f32_e32 v79, v79, v82
	v_frexp_mant_f32_e32 v82, v66
	v_cmp_gt_f32_e32 vcc, s26, v82
	v_cvt_f64_f32_e32 v[82:83], v66
	v_frexp_exp_i32_f64_e32 v82, v[82:83]
	v_subbrev_co_u32_e32 v88, vcc, 0, v82, vcc
	v_sub_u32_e32 v82, 0, v88
	v_ldexp_f32 v66, v66, v82
	v_ldexp_f32 v82, v79, v82
	v_max_f32_e32 v79, 0, v67
	v_mul_f32_e64 v67, |v67|, s2
	v_exp_f32_e32 v98, v67
	s_nop 0
	v_add_f32_e32 v67, 1.0, v98
	v_add_f32_e32 v83, -1.0, v67
	v_sub_f32_e32 v84, v83, v67
	v_add_f32_e32 v84, 1.0, v84
	v_sub_f32_e32 v83, v98, v83
	v_add_f32_e32 v83, v83, v84
	v_frexp_mant_f32_e32 v84, v67
	v_cmp_gt_f32_e32 vcc, s26, v84
	v_cvt_f64_f32_e32 v[84:85], v67
	v_frexp_exp_i32_f64_e32 v84, v[84:85]
	v_subbrev_co_u32_e32 v99, vcc, 0, v84, vcc
	v_sub_u32_e32 v84, 0, v99
	v_ldexp_f32 v67, v67, v84
	v_ldexp_f32 v83, v83, v84
	v_pk_add_f32 v[84:85], v[66:67], 1.0 op_sel_hi:[1,0]
	v_pk_add_f32 v[94:95], v[66:67], -1.0 op_sel_hi:[1,0]
	v_pk_add_f32 v[86:87], v[84:85], -1.0 op_sel_hi:[1,0]
	v_pk_add_f32 v[100:101], v[94:95], 1.0 op_sel_hi:[1,0]
	v_pk_add_f32 v[86:87], v[66:67], v[86:87] neg_lo:[0,1] neg_hi:[0,1]
	v_pk_add_f32 v[66:67], v[66:67], v[100:101] neg_lo:[0,1] neg_hi:[0,1]
	v_pk_add_f32 v[86:87], v[82:83], v[86:87]
	v_pk_add_f32 v[66:67], v[82:83], v[66:67]
	v_pk_add_f32 v[90:91], v[84:85], v[86:87]
	v_pk_add_f32 v[82:83], v[94:95], v[66:67]
	v_rcp_f32_e32 v92, v90
	v_rcp_f32_e32 v93, v91
	v_pk_add_f32 v[84:85], v[90:91], v[84:85] neg_lo:[0,1] neg_hi:[0,1]
	v_pk_add_f32 v[94:95], v[82:83], v[94:95] neg_lo:[0,1] neg_hi:[0,1]
	v_pk_add_f32 v[84:85], v[86:87], v[84:85] neg_lo:[0,1] neg_hi:[0,1]
	v_pk_mul_f32 v[86:87], v[82:83], v[92:93]
	v_pk_add_f32 v[66:67], v[66:67], v[94:95] neg_lo:[0,1] neg_hi:[0,1]
	v_pk_mul_f32 v[94:95], v[90:91], v[86:87]
	s_nop 0
	v_pk_fma_f32 v[100:101], v[86:87], v[90:91], v[94:95] neg_lo:[0,0,1] neg_hi:[0,0,1]
	s_nop 0
	v_pk_fma_f32 v[100:101], v[86:87], v[84:85], v[100:101]
	s_nop 0
	v_pk_add_f32 v[102:103], v[94:95], v[100:101]
	s_nop 0
	v_pk_add_f32 v[110:111], v[82:83], v[102:103] neg_lo:[0,1] neg_hi:[0,1]
	v_pk_add_f32 v[94:95], v[102:103], v[94:95] neg_lo:[0,1] neg_hi:[0,1]
	v_pk_add_f32 v[82:83], v[82:83], v[110:111] neg_lo:[0,1] neg_hi:[0,1]
	s_nop 0
	v_pk_add_f32 v[82:83], v[82:83], v[102:103] neg_lo:[0,1] neg_hi:[0,1]
	s_nop 0
	v_pk_add_f32 v[66:67], v[66:67], v[82:83]
	v_pk_add_f32 v[82:83], v[94:95], v[100:101] neg_lo:[0,1] neg_hi:[0,1]
	s_nop 0
	v_pk_add_f32 v[66:67], v[82:83], v[66:67]
	s_nop 0
	v_pk_add_f32 v[82:83], v[110:111], v[66:67]
	s_nop 0
	v_pk_mul_f32 v[94:95], v[92:93], v[82:83]
	s_nop 0
	v_pk_mul_f32 v[100:101], v[90:91], v[94:95]
	s_nop 0
	v_pk_fma_f32 v[90:91], v[94:95], v[90:91], v[100:101] neg_lo:[0,0,1] neg_hi:[0,0,1]
	s_nop 0
	v_pk_fma_f32 v[84:85], v[94:95], v[84:85], v[90:91]
	v_pk_add_f32 v[90:91], v[110:111], v[82:83] neg_lo:[0,1] neg_hi:[0,1]
	s_nop 0
	v_pk_add_f32 v[66:67], v[66:67], v[90:91]
; __device__ __forceinline__ float softplusf(float x) { return fmaxf(x, 0.f) + log1pf(__expf(-fabsf(x))); }
; __device__ void phaseA_tile(const Params& p, int l, int mt, int nt, char* smem) {
;     ...
;                 for (int j = 0; j < 2; ++j) {
;                     const int c = j * 16 + g4 * 4;
;                     const float4 db = *(const float4*)(p.dt_bias + l * 32 + c);
;                     const f32x4 v = acc[i][j];
;                     *(float4*)(p.dtb + (size_t)row * 32 + c) =
;                         make_float4(softplusf(v[0] + db.x), softplusf(v[1] + db.y), softplusf(v[2] + db.z), softplusf(v[3] + db.w));
	v_pk_add_f32 v[90:91], v[100:101], v[84:85]
	s_nop 0
	v_pk_add_f32 v[102:103], v[82:83], v[90:91] neg_lo:[0,1] neg_hi:[0,1]
	v_pk_add_f32 v[100:101], v[90:91], v[100:101] neg_lo:[0,1] neg_hi:[0,1]
	v_pk_add_f32 v[82:83], v[82:83], v[102:103] neg_lo:[0,1] neg_hi:[0,1]
	s_nop 0
	v_pk_add_f32 v[82:83], v[82:83], v[90:91] neg_lo:[0,1] neg_hi:[0,1]
	s_nop 0
	v_pk_add_f32 v[66:67], v[66:67], v[82:83]
	v_pk_add_f32 v[82:83], v[100:101], v[84:85] neg_lo:[0,1] neg_hi:[0,1]
	s_nop 0
	v_pk_add_f32 v[66:67], v[82:83], v[66:67]
	v_pk_add_f32 v[82:83], v[86:87], v[94:95]
	v_pk_add_f32 v[66:67], v[102:103], v[66:67]
	v_pk_add_f32 v[84:85], v[82:83], v[86:87] neg_lo:[0,1] neg_hi:[0,1]
	v_pk_mul_f32 v[66:67], v[92:93], v[66:67]
	v_pk_add_f32 v[84:85], v[94:95], v[84:85] neg_lo:[0,1] neg_hi:[0,1]
	s_nop 0
	v_pk_add_f32 v[66:67], v[84:85], v[66:67]
	s_nop 0
	v_pk_add_f32 v[86:87], v[82:83], v[66:67]
	s_nop 0
	v_pk_add_f32 v[82:83], v[86:87], v[82:83] neg_lo:[0,1] neg_hi:[0,1]
	v_pk_mul_f32 v[92:93], v[86:87], v[86:87]
	v_pk_add_f32 v[82:83], v[66:67], v[82:83] neg_lo:[0,1] neg_hi:[0,1]
	v_mov_b64_e32 v[66:67], s[0:1]
	v_pk_fma_f32 v[90:91], v[92:93], s[28:29], v[66:67] op_sel_hi:[1,0,0]
	v_ldexp_f32 v84, v86, 1
	v_pk_fma_f32 v[90:91], v[92:93], v[90:91], s[30:31] op_sel_hi:[1,1,0]
	v_pk_mul_f32 v[92:93], v[86:87], v[92:93]
	v_max_f32_e32 v86, 0, v68
	v_mul_f32_e64 v68, |v68|, s2
	v_exp_f32_e32 v100, v68
	v_ldexp_f32 v89, v83, 1
	v_ldexp_f32 v85, v87, 1
	v_pk_mul_f32 v[90:91], v[92:93], v[90:91]
	v_add_f32_e32 v68, 1.0, v100
	v_add_f32_e32 v83, -1.0, v68
	v_sub_f32_e32 v87, v83, v68
	v_add_f32_e32 v87, 1.0, v87
	v_sub_f32_e32 v83, v100, v83
	v_add_f32_e32 v83, v83, v87
	v_frexp_mant_f32_e32 v87, v68
	v_cvt_f64_f32_e32 v[94:95], v68
	v_cmp_gt_f32_e32 vcc, s26, v87
	v_frexp_exp_i32_f64_e32 v87, v[94:95]
	v_pk_add_f32 v[92:93], v[84:85], v[90:91]
	v_subbrev_co_u32_e32 v102, vcc, 0, v87, vcc
	v_sub_u32_e32 v87, 0, v102
	v_ldexp_f32 v94, v68, v87
	v_ldexp_f32 v68, v83, v87
	v_max_f32_e32 v87, 0, v69
	v_mul_f32_e64 v69, |v69|, s2
	v_exp_f32_e32 v101, v69
	v_pk_add_f32 v[84:85], v[92:93], v[84:85] neg_lo:[0,1] neg_hi:[0,1]
	v_ldexp_f32 v82, v82, 1
	v_pk_add_f32 v[84:85], v[90:91], v[84:85] neg_lo:[0,1] neg_hi:[0,1]
	v_add_f32_e32 v69, 1.0, v101
	v_add_f32_e32 v83, -1.0, v69
	v_sub_f32_e32 v95, v83, v69
	v_add_f32_e32 v95, 1.0, v95
	v_sub_f32_e32 v83, v101, v83
	v_add_f32_e32 v83, v83, v95
	v_frexp_mant_f32_e32 v95, v69
	v_cvt_f64_f32_e32 v[110:111], v69
	v_cmp_gt_f32_e32 vcc, s26, v95
	v_frexp_exp_i32_f64_e32 v95, v[110:111]
	v_mov_b32_e32 v91, v85
	v_subbrev_co_u32_e32 v132, vcc, 0, v95, vcc
	v_sub_u32_e32 v103, 0, v132
	v_ldexp_f32 v95, v69, v103
	v_pk_add_f32 v[110:111], v[94:95], 1.0 op_sel_hi:[1,0]
	v_ldexp_f32 v69, v83, v103
	v_pk_add_f32 v[112:113], v[110:111], -1.0 op_sel_hi:[1,0]
	v_pk_add_f32 v[118:119], v[94:95], -1.0 op_sel_hi:[1,0]
	v_pk_add_f32 v[112:113], v[94:95], v[112:113] neg_lo:[0,1] neg_hi:[0,1]
	v_pk_add_f32 v[120:121], v[118:119], 1.0 op_sel_hi:[1,0]
	v_pk_add_f32 v[112:113], v[68:69], v[112:113]
	v_pk_add_f32 v[94:95], v[94:95], v[120:121] neg_lo:[0,1] neg_hi:[0,1]
	v_pk_add_f32 v[114:115], v[110:111], v[112:113]
	v_pk_add_f32 v[68:69], v[68:69], v[94:95]
	v_rcp_f32_e32 v116, v114
	v_rcp_f32_e32 v117, v115
	v_pk_add_f32 v[94:95], v[118:119], v[68:69]
	v_pk_add_f32 v[110:111], v[114:115], v[110:111] neg_lo:[0,1] neg_hi:[0,1]
	v_pk_add_f32 v[118:119], v[94:95], v[118:119] neg_lo:[0,1] neg_hi:[0,1]
	v_pk_add_f32 v[110:111], v[112:113], v[110:111] neg_lo:[0,1] neg_hi:[0,1]
	v_pk_mul_f32 v[112:113], v[94:95], v[116:117]
	v_pk_add_f32 v[68:69], v[68:69], v[118:119] neg_lo:[0,1] neg_hi:[0,1]
	v_pk_mul_f32 v[118:119], v[114:115], v[112:113]
	v_mov_b32_e32 v83, v89
	v_pk_fma_f32 v[120:121], v[112:113], v[114:115], v[118:119] neg_lo:[0,0,1] neg_hi:[0,0,1]
	v_mov_b32_e32 v128, v92
	v_pk_fma_f32 v[120:121], v[112:113], v[110:111], v[120:121]
	v_cmp_neq_f32_e32 vcc, s8, v97
	v_pk_add_f32 v[122:123], v[118:119], v[120:121]
	v_cmp_lt_f32_e64 s[0:1], |v98|, s9
	v_pk_add_f32 v[124:125], v[94:95], v[122:123] neg_lo:[0,1] neg_hi:[0,1]
	v_pk_add_f32 v[118:119], v[122:123], v[118:119] neg_lo:[0,1] neg_hi:[0,1]
	v_pk_add_f32 v[94:95], v[94:95], v[124:125] neg_lo:[0,1] neg_hi:[0,1]
	s_nop 0
	v_pk_add_f32 v[94:95], v[94:95], v[122:123] neg_lo:[0,1] neg_hi:[0,1]
	s_nop 0
	v_pk_add_f32 v[68:69], v[68:69], v[94:95]
	v_pk_add_f32 v[94:95], v[118:119], v[120:121] neg_lo:[0,1] neg_hi:[0,1]
	s_nop 0
	v_pk_add_f32 v[68:69], v[94:95], v[68:69]
	s_nop 0
	v_pk_add_f32 v[94:95], v[124:125], v[68:69]
	s_nop 0
	v_pk_mul_f32 v[118:119], v[116:117], v[94:95]
	s_nop 0
	v_pk_mul_f32 v[120:121], v[114:115], v[118:119]
	s_nop 0
	v_pk_fma_f32 v[114:115], v[118:119], v[114:115], v[120:121] neg_lo:[0,0,1] neg_hi:[0,0,1]
	s_nop 0
	v_pk_fma_f32 v[110:111], v[118:119], v[110:111], v[114:115]
	v_pk_add_f32 v[114:115], v[124:125], v[94:95] neg_lo:[0,1] neg_hi:[0,1]
	s_nop 0
	v_pk_add_f32 v[68:69], v[68:69], v[114:115]
	v_pk_add_f32 v[114:115], v[120:121], v[110:111]
	s_nop 0
	v_pk_add_f32 v[122:123], v[94:95], v[114:115] neg_lo:[0,1] neg_hi:[0,1]
	v_pk_add_f32 v[120:121], v[114:115], v[120:121] neg_lo:[0,1] neg_hi:[0,1]
	v_pk_add_f32 v[94:95], v[94:95], v[122:123] neg_lo:[0,1] neg_hi:[0,1]
	s_nop 0
	v_pk_add_f32 v[94:95], v[94:95], v[114:115] neg_lo:[0,1] neg_hi:[0,1]
	s_nop 0
	v_pk_add_f32 v[68:69], v[68:69], v[94:95]
	v_pk_add_f32 v[94:95], v[120:121], v[110:111] neg_lo:[0,1] neg_hi:[0,1]
	s_nop 0
	v_pk_add_f32 v[68:69], v[94:95], v[68:69]
	v_pk_add_f32 v[94:95], v[112:113], v[118:119]
	v_pk_add_f32 v[68:69], v[122:123], v[68:69]
	v_pk_add_f32 v[110:111], v[94:95], v[112:113] neg_lo:[0,1] neg_hi:[0,1]
; __device__ __forceinline__ float softplusf(float x) { return fmaxf(x, 0.f) + log1pf(__expf(-fabsf(x))); }
; __device__ void phaseA_tile(const Params& p, int l, int mt, int nt, char* smem) {
;     ...
;                 for (int j = 0; j < 2; ++j) {
;                     const int c = j * 16 + g4 * 4;
;                     const float4 db = *(const float4*)(p.dt_bias + l * 32 + c);
;                     const f32x4 v = acc[i][j];
;                     *(float4*)(p.dtb + (size_t)row * 32 + c) =
;                         make_float4(softplusf(v[0] + db.x), softplusf(v[1] + db.y), softplusf(v[2] + db.z), softplusf(v[3] + db.w));
	v_pk_mul_f32 v[68:69], v[116:117], v[68:69]
	v_pk_add_f32 v[110:111], v[118:119], v[110:111] neg_lo:[0,1] neg_hi:[0,1]
	s_nop 0
	v_pk_add_f32 v[68:69], v[110:111], v[68:69]
	s_nop 0
	v_pk_add_f32 v[110:111], v[94:95], v[68:69]
	s_nop 0
	v_pk_add_f32 v[94:95], v[110:111], v[94:95] neg_lo:[0,1] neg_hi:[0,1]
	v_pk_mul_f32 v[114:115], v[110:111], v[110:111]
	v_pk_add_f32 v[68:69], v[68:69], v[94:95] neg_lo:[0,1] neg_hi:[0,1]
	v_pk_fma_f32 v[116:117], v[114:115], s[28:29], v[66:67] op_sel_hi:[1,0,0]
	v_ldexp_f32 v112, v68, 1
	v_ldexp_f32 v103, v69, 1
	v_lshl_add_u64 v[68:69], s[10:11], 0, v[80:81]
	v_cvt_f32_i32_e32 v81, v99
	v_cvt_f32_i32_e32 v80, v88
	v_ldexp_f32 v94, v110, 1
	v_pk_fma_f32 v[116:117], v[114:115], v[116:117], s[30:31] op_sel_hi:[1,1,0]
	v_ldexp_f32 v95, v111, 1
	v_pk_mul_f32 v[110:111], v[110:111], v[114:115]
	v_pk_mul_f32 v[114:115], v[80:81], s[12:13] op_sel_hi:[1,0]
	v_mov_b32_e32 v113, v103
	v_pk_fma_f32 v[118:119], v[80:81], s[12:13], v[114:115] op_sel_hi:[1,0,1] neg_lo:[0,0,1] neg_hi:[0,0,1]
	v_mov_b32_e32 v90, v114
	v_pk_fma_f32 v[80:81], v[80:81], s[14:15], v[118:119] op_sel_hi:[1,0,1]
	v_mov_b32_e32 v125, v115
	v_mov_b32_e32 v88, v80
	v_pk_add_f32 v[90:91], v[90:91], v[88:89]
	v_pk_add_f32 v[88:89], v[82:83], v[84:85]
	v_mov_b32_e32 v85, v93
	v_mov_b32_e32 v83, v89
	v_pk_add_f32 v[118:119], v[114:115], v[80:81]
	v_pk_add_f32 v[82:83], v[82:83], v[84:85]
	v_pk_add_f32 v[84:85], v[92:93], v[88:89]
	v_mov_b32_e32 v129, v119
	v_pk_add_f32 v[120:121], v[118:119], v[84:85]
	v_mov_b32_e32 v126, v84
	v_mov_b32_e32 v127, v121
	v_pk_add_f32 v[126:127], v[126:127], v[128:129] neg_lo:[0,1] neg_hi:[0,1]
	v_mov_b32_e32 v122, v120
	v_mov_b32_e32 v123, v119
	v_mov_b32_e32 v124, v118
	v_mov_b32_e32 v128, v118
	v_mov_b32_e32 v129, v121
	v_mov_b32_e32 v115, v127
	v_pk_add_f32 v[122:123], v[122:123], v[124:125] neg_lo:[0,1] neg_hi:[0,1]
	v_mov_b32_e32 v124, v84
	v_mov_b32_e32 v125, v81
	v_pk_add_f32 v[114:115], v[128:129], v[114:115] neg_lo:[0,1] neg_hi:[0,1]
	v_pk_add_f32 v[124:125], v[124:125], v[122:123] neg_lo:[0,1] neg_hi:[0,1]
	v_mov_b32_e32 v128, v114
	v_mov_b32_e32 v129, v123
	v_mov_b32_e32 v130, v120
	v_mov_b32_e32 v131, v85
	v_mov_b32_e32 v123, v93
	v_pk_add_f32 v[128:129], v[80:81], v[128:129] neg_lo:[0,1] neg_hi:[0,1]
	v_pk_add_f32 v[122:123], v[130:131], v[122:123] neg_lo:[0,1] neg_hi:[0,1]
	v_mov_b32_e32 v81, v119
	v_pk_add_f32 v[84:85], v[84:85], v[92:93] neg_lo:[0,1] neg_hi:[0,1]
	v_pk_add_f32 v[90:91], v[90:91], v[122:123] neg_lo:[0,1] neg_hi:[0,1]
	v_pk_add_f32 v[80:81], v[80:81], v[114:115] neg_lo:[0,1] neg_hi:[0,1]
	v_pk_add_f32 v[82:83], v[82:83], v[126:127] neg_lo:[0,1] neg_hi:[0,1]
	v_pk_add_f32 v[84:85], v[88:89], v[84:85] neg_lo:[0,1] neg_hi:[0,1]
	v_pk_add_f32 v[88:89], v[82:83], v[80:81]
	v_mov_b32_e32 v81, v125
	v_mov_b32_e32 v83, v91
	v_pk_add_f32 v[92:93], v[124:125], v[90:91]
	v_pk_add_f32 v[82:83], v[80:81], v[82:83]
	v_mov_b32_e32 v90, v88
	v_pk_add_f32 v[82:83], v[82:83], v[128:129] neg_lo:[0,1] neg_hi:[0,1]
	v_mov_b32_e32 v91, v93
	v_pk_add_f32 v[90:91], v[90:91], v[82:83] neg_lo:[0,1] neg_hi:[0,1]
	v_pk_add_f32 v[82:83], v[84:85], v[82:83] neg_lo:[0,1] neg_hi:[0,1]
	v_pk_add_f32 v[80:81], v[80:81], v[90:91] neg_lo:[0,1] neg_hi:[0,1]
	v_lshl_add_u64 v[68:69], v[68:69], 0, v[0:1]
	v_pk_add_f32 v[80:81], v[82:83], v[80:81]
	v_pk_add_f32 v[82:83], v[92:93], v[88:89]
	s_nop 0
	v_pk_add_f32 v[84:85], v[120:121], v[82:83]
	s_nop 0
	v_pk_add_f32 v[88:89], v[84:85], v[120:121] neg_lo:[0,1] neg_hi:[0,1]
	s_nop 0
	v_pk_add_f32 v[82:83], v[82:83], v[88:89] neg_lo:[0,1] neg_hi:[0,1]
	s_nop 0
	v_pk_add_f32 v[80:81], v[80:81], v[82:83]
	s_nop 0
	v_pk_add_f32 v[80:81], v[84:85], v[80:81]
	v_pk_mul_f32 v[84:85], v[110:111], v[116:117]
	v_cndmask_b32_e32 v80, v160, v80, vcc
	v_cmp_neq_f32_e32 vcc, s8, v98
	v_pk_add_f32 v[88:89], v[94:95], v[84:85]
	s_nop 0
	v_cndmask_b32_e32 v81, v160, v81, vcc
	v_cmp_ngt_f32_e32 vcc, -1.0, v98
	v_pk_add_f32 v[92:93], v[88:89], v[94:95] neg_lo:[0,1] neg_hi:[0,1]
	v_mov_b32_e32 v116, v88
	v_cndmask_b32_e32 v81, v161, v81, vcc
	v_cmp_ngt_f32_e32 vcc, -1.0, v97
	v_pk_add_f32 v[84:85], v[84:85], v[92:93] neg_lo:[0,1] neg_hi:[0,1]
	s_nop 0
	v_cndmask_b32_e32 v80, v161, v80, vcc
	v_cmp_neq_f32_e32 vcc, -1.0, v97
	v_pk_add_f32 v[94:95], v[112:113], v[84:85]
	v_mov_b32_e32 v93, v85
	v_cndmask_b32_e32 v80, v162, v80, vcc
	v_cmp_neq_f32_e32 vcc, -1.0, v98
	v_mov_b32_e32 v113, v95
	v_mov_b32_e32 v85, v89
	v_cndmask_b32_e32 v81, v162, v81, vcc
	v_cmp_lt_f32_e64 vcc, |v97|, s9
	v_cndmask_b32_e64 v81, v81, v98, s[0:1]
	v_pk_add_f32 v[98:99], v[88:89], v[94:95]
	v_cndmask_b32_e32 v80, v80, v97, vcc
	v_pk_add_f32 v[78:79], v[78:79], v[80:81]
	v_cvt_f32_i32_e32 v81, v132
	v_cvt_f32_i32_e32 v80, v102
	v_mov_b32_e32 v114, v98
	v_pk_add_f32 v[84:85], v[112:113], v[84:85]
	v_mov_b32_e32 v119, v99
	v_pk_mul_f32 v[82:83], v[80:81], s[12:13] op_sel_hi:[1,0]
	v_cmp_neq_f32_e32 vcc, s8, v100
	v_pk_fma_f32 v[90:91], v[80:81], s[12:13], v[82:83] op_sel_hi:[1,0,1] neg_lo:[0,0,1] neg_hi:[0,0,1]
	v_mov_b32_e32 v92, v82
	v_pk_fma_f32 v[80:81], v[80:81], s[14:15], v[90:91] op_sel_hi:[1,0,1]
	v_mov_b32_e32 v113, v83
	v_pk_add_f32 v[90:91], v[82:83], v[80:81]
	v_mov_b32_e32 v102, v80
	v_pk_add_f32 v[92:93], v[92:93], v[102:103]
	v_pk_add_f32 v[102:103], v[90:91], v[98:99]
	v_mov_b32_e32 v117, v91
	v_mov_b32_e32 v115, v103
	v_pk_add_f32 v[114:115], v[114:115], v[116:117] neg_lo:[0,1] neg_hi:[0,1]
	v_mov_b32_e32 v110, v102
	v_mov_b32_e32 v111, v91
	v_mov_b32_e32 v112, v90
	v_mov_b32_e32 v116, v90
	v_mov_b32_e32 v117, v103
	v_mov_b32_e32 v83, v115
	v_pk_add_f32 v[110:111], v[110:111], v[112:113] neg_lo:[0,1] neg_hi:[0,1]
; __device__ __forceinline__ float softplusf(float x) { return fmaxf(x, 0.f) + log1pf(__expf(-fabsf(x))); }
; __device__ void phaseA_tile(const Params& p, int l, int mt, int nt, char* smem) {
;     ...
;                 for (int j = 0; j < 2; ++j) {
;                     const int c = j * 16 + g4 * 4;
;                     const float4 db = *(const float4*)(p.dt_bias + l * 32 + c);
;                     const f32x4 v = acc[i][j];
;                     *(float4*)(p.dtb + (size_t)row * 32 + c) =
;                         make_float4(softplusf(v[0] + db.x), softplusf(v[1] + db.y), softplusf(v[2] + db.z), softplusf(v[3] + db.w));
	v_mov_b32_e32 v112, v98
	v_mov_b32_e32 v113, v81
	v_pk_add_f32 v[82:83], v[116:117], v[82:83] neg_lo:[0,1] neg_hi:[0,1]
	v_pk_add_f32 v[112:113], v[112:113], v[110:111] neg_lo:[0,1] neg_hi:[0,1]
	v_mov_b32_e32 v116, v82
	v_mov_b32_e32 v117, v111
	v_mov_b32_e32 v118, v102
	v_mov_b32_e32 v111, v89
	v_pk_add_f32 v[116:117], v[80:81], v[116:117] neg_lo:[0,1] neg_hi:[0,1]
	v_pk_add_f32 v[110:111], v[118:119], v[110:111] neg_lo:[0,1] neg_hi:[0,1]
	v_mov_b32_e32 v81, v91
	v_pk_add_f32 v[92:93], v[92:93], v[110:111] neg_lo:[0,1] neg_hi:[0,1]
	v_pk_add_f32 v[80:81], v[80:81], v[82:83] neg_lo:[0,1] neg_hi:[0,1]
	v_pk_add_f32 v[82:83], v[84:85], v[114:115] neg_lo:[0,1] neg_hi:[0,1]
	v_pk_add_f32 v[90:91], v[112:113], v[92:93]
	v_pk_add_f32 v[84:85], v[82:83], v[80:81]
	v_mov_b32_e32 v81, v113
	v_mov_b32_e32 v83, v93
	v_pk_add_f32 v[82:83], v[80:81], v[82:83]
	v_pk_add_f32 v[88:89], v[98:99], v[88:89] neg_lo:[0,1] neg_hi:[0,1]
	v_pk_add_f32 v[82:83], v[82:83], v[116:117] neg_lo:[0,1] neg_hi:[0,1]
	v_mov_b32_e32 v92, v84
	v_mov_b32_e32 v93, v91
	v_pk_add_f32 v[88:89], v[94:95], v[88:89] neg_lo:[0,1] neg_hi:[0,1]
	v_pk_add_f32 v[92:93], v[92:93], v[82:83] neg_lo:[0,1] neg_hi:[0,1]
	v_pk_add_f32 v[82:83], v[88:89], v[82:83] neg_lo:[0,1] neg_hi:[0,1]
	v_pk_add_f32 v[80:81], v[80:81], v[92:93] neg_lo:[0,1] neg_hi:[0,1]
	v_cmp_lt_f32_e64 s[0:1], |v101|, s9
	v_pk_add_f32 v[80:81], v[82:83], v[80:81]
	v_pk_add_f32 v[82:83], v[90:91], v[84:85]
	s_nop 0
	v_pk_add_f32 v[84:85], v[102:103], v[82:83]
	s_nop 0
	v_pk_add_f32 v[88:89], v[84:85], v[102:103] neg_lo:[0,1] neg_hi:[0,1]
	s_nop 0
	v_pk_add_f32 v[82:83], v[82:83], v[88:89] neg_lo:[0,1] neg_hi:[0,1]
	s_nop 0
	v_pk_add_f32 v[80:81], v[80:81], v[82:83]
	s_nop 0
	v_pk_add_f32 v[80:81], v[84:85], v[80:81]
	s_nop 0
	v_cndmask_b32_e32 v80, v160, v80, vcc
	v_cmp_neq_f32_e32 vcc, s8, v101
	s_nop 1
	v_cndmask_b32_e32 v81, v160, v81, vcc
	v_cmp_ngt_f32_e32 vcc, -1.0, v101
	s_nop 1
	v_cndmask_b32_e32 v81, v161, v81, vcc
	v_cmp_ngt_f32_e32 vcc, -1.0, v100
	s_nop 1
	v_cndmask_b32_e32 v80, v161, v80, vcc
	v_cmp_neq_f32_e32 vcc, -1.0, v100
	s_nop 1
	v_cndmask_b32_e32 v80, v162, v80, vcc
	v_cmp_neq_f32_e32 vcc, -1.0, v101
	s_nop 1
	v_cndmask_b32_e32 v81, v162, v81, vcc
	v_cmp_lt_f32_e64 vcc, |v100|, s9
	v_cndmask_b32_e64 v81, v81, v101, s[0:1]
	s_nop 0
	v_cndmask_b32_e32 v80, v80, v100, vcc
	v_pk_add_f32 v[80:81], v[86:87], v[80:81]
	global_store_dwordx4 v[68:69], v[78:81], off
	global_load_dwordx4 v[78:81], v0, s[74:75] offset:64
	s_waitcnt vmcnt(0)
	v_add_f32_e32 v82, v58, v78
	v_max_f32_e32 v78, 0, v82
	v_mul_f32_e64 v82, |v82|, s2
	v_exp_f32_e32 v97, v82
	s_nop 0
	v_add_f32_e32 v84, 1.0, v97
	v_add_f32_e32 v82, -1.0, v84
	v_sub_f32_e32 v83, v82, v84
	v_add_f32_e32 v83, 1.0, v83
	v_sub_f32_e32 v82, v97, v82
	v_add_f32_e32 v85, v82, v83
	v_frexp_mant_f32_e32 v82, v84
	v_cmp_gt_f32_e32 vcc, s26, v82
	v_cvt_f64_f32_e32 v[82:83], v84
	v_frexp_exp_i32_f64_e32 v82, v[82:83]
	v_subbrev_co_u32_e32 v120, vcc, 0, v82, vcc
	v_sub_u32_e32 v83, 0, v120
	v_ldexp_f32 v82, v84, v83
	v_ldexp_f32 v84, v85, v83
	v_add_f32_e32 v83, v59, v79
	v_max_f32_e32 v79, 0, v83
	v_mul_f32_e64 v83, |v83|, s2
	v_exp_f32_e32 v128, v83
	s_nop 0
	v_add_f32_e32 v83, 1.0, v128
	v_add_f32_e32 v85, -1.0, v83
	v_sub_f32_e32 v86, v85, v83
	v_add_f32_e32 v86, 1.0, v86
	v_sub_f32_e32 v85, v128, v85
	v_add_f32_e32 v85, v85, v86
	v_frexp_mant_f32_e32 v86, v83
	v_cmp_gt_f32_e32 vcc, s26, v86
	v_cvt_f64_f32_e32 v[86:87], v83
	v_frexp_exp_i32_f64_e32 v86, v[86:87]
	v_subbrev_co_u32_e32 v121, vcc, 0, v86, vcc
	v_sub_u32_e32 v86, 0, v121
	v_ldexp_f32 v83, v83, v86
	v_ldexp_f32 v85, v85, v86
	v_pk_add_f32 v[86:87], v[82:83], 1.0 op_sel_hi:[1,0]
	v_pk_add_f32 v[94:95], v[82:83], -1.0 op_sel_hi:[1,0]
	v_pk_add_f32 v[88:89], v[86:87], -1.0 op_sel_hi:[1,0]
	v_pk_add_f32 v[98:99], v[94:95], 1.0 op_sel_hi:[1,0]
	v_pk_add_f32 v[88:89], v[82:83], v[88:89] neg_lo:[0,1] neg_hi:[0,1]
	v_pk_add_f32 v[82:83], v[82:83], v[98:99] neg_lo:[0,1] neg_hi:[0,1]
	v_pk_add_f32 v[88:89], v[84:85], v[88:89]
	v_pk_add_f32 v[82:83], v[84:85], v[82:83]
	v_pk_add_f32 v[90:91], v[86:87], v[88:89]
	v_pk_add_f32 v[84:85], v[94:95], v[82:83]
	v_rcp_f32_e32 v92, v90
	v_rcp_f32_e32 v93, v91
	v_pk_add_f32 v[86:87], v[90:91], v[86:87] neg_lo:[0,1] neg_hi:[0,1]
	v_pk_add_f32 v[94:95], v[84:85], v[94:95] neg_lo:[0,1] neg_hi:[0,1]
	v_pk_add_f32 v[86:87], v[88:89], v[86:87] neg_lo:[0,1] neg_hi:[0,1]
	v_pk_mul_f32 v[88:89], v[84:85], v[92:93]
	v_pk_add_f32 v[82:83], v[82:83], v[94:95] neg_lo:[0,1] neg_hi:[0,1]
	v_pk_mul_f32 v[94:95], v[90:91], v[88:89]
	v_cmp_lt_f32_e64 s[0:1], |v128|, s9
	v_pk_fma_f32 v[98:99], v[88:89], v[90:91], v[94:95] neg_lo:[0,0,1] neg_hi:[0,0,1]
	s_nop 0
	v_pk_fma_f32 v[98:99], v[88:89], v[86:87], v[98:99]
	s_nop 0
	v_pk_add_f32 v[100:101], v[94:95], v[98:99]
	s_nop 0
	v_pk_add_f32 v[102:103], v[84:85], v[100:101] neg_lo:[0,1] neg_hi:[0,1]
	v_pk_add_f32 v[94:95], v[100:101], v[94:95] neg_lo:[0,1] neg_hi:[0,1]
	v_pk_add_f32 v[84:85], v[84:85], v[102:103] neg_lo:[0,1] neg_hi:[0,1]
	s_nop 0
	v_pk_add_f32 v[84:85], v[84:85], v[100:101] neg_lo:[0,1] neg_hi:[0,1]
	s_nop 0
	v_pk_add_f32 v[82:83], v[82:83], v[84:85]
	v_pk_add_f32 v[84:85], v[94:95], v[98:99] neg_lo:[0,1] neg_hi:[0,1]
	s_nop 0
	v_pk_add_f32 v[82:83], v[84:85], v[82:83]
	s_nop 0
	v_pk_add_f32 v[84:85], v[102:103], v[82:83]
	s_nop 0
	v_pk_mul_f32 v[94:95], v[92:93], v[84:85]
	s_nop 0
	v_pk_mul_f32 v[98:99], v[90:91], v[94:95]
	s_nop 0
	v_pk_fma_f32 v[90:91], v[94:95], v[90:91], v[98:99] neg_lo:[0,0,1] neg_hi:[0,0,1]
	s_nop 0
	v_pk_fma_f32 v[86:87], v[94:95], v[86:87], v[90:91]
	v_pk_add_f32 v[90:91], v[102:103], v[84:85] neg_lo:[0,1] neg_hi:[0,1]
; __device__ __forceinline__ float softplusf(float x) { return fmaxf(x, 0.f) + log1pf(__expf(-fabsf(x))); }
; __device__ void phaseA_tile(const Params& p, int l, int mt, int nt, char* smem) {
;     ...
;                 for (int j = 0; j < 2; ++j) {
;                     const int c = j * 16 + g4 * 4;
;                     const float4 db = *(const float4*)(p.dt_bias + l * 32 + c);
;                     const f32x4 v = acc[i][j];
;                     *(float4*)(p.dtb + (size_t)row * 32 + c) =
;                         make_float4(softplusf(v[0] + db.x), softplusf(v[1] + db.y), softplusf(v[2] + db.z), softplusf(v[3] + db.w));
	s_nop 0
	v_pk_add_f32 v[82:83], v[82:83], v[90:91]
	v_pk_add_f32 v[90:91], v[98:99], v[86:87]
	s_nop 0
	v_pk_add_f32 v[100:101], v[84:85], v[90:91] neg_lo:[0,1] neg_hi:[0,1]
	v_pk_add_f32 v[98:99], v[90:91], v[98:99] neg_lo:[0,1] neg_hi:[0,1]
	v_pk_add_f32 v[84:85], v[84:85], v[100:101] neg_lo:[0,1] neg_hi:[0,1]
	s_nop 0
	v_pk_add_f32 v[84:85], v[84:85], v[90:91] neg_lo:[0,1] neg_hi:[0,1]
	s_nop 0
	v_pk_add_f32 v[82:83], v[82:83], v[84:85]
	v_pk_add_f32 v[84:85], v[98:99], v[86:87] neg_lo:[0,1] neg_hi:[0,1]
	s_nop 0
	v_pk_add_f32 v[82:83], v[84:85], v[82:83]
	v_pk_add_f32 v[84:85], v[88:89], v[94:95]
	v_pk_add_f32 v[82:83], v[100:101], v[82:83]
	v_pk_add_f32 v[86:87], v[84:85], v[88:89] neg_lo:[0,1] neg_hi:[0,1]
	v_pk_mul_f32 v[82:83], v[92:93], v[82:83]
	v_pk_add_f32 v[86:87], v[94:95], v[86:87] neg_lo:[0,1] neg_hi:[0,1]
	s_nop 0
	v_pk_add_f32 v[82:83], v[86:87], v[82:83]
	s_nop 0
	v_pk_add_f32 v[86:87], v[84:85], v[82:83]
	s_nop 0
	v_pk_add_f32 v[84:85], v[86:87], v[84:85] neg_lo:[0,1] neg_hi:[0,1]
	v_pk_mul_f32 v[88:89], v[86:87], v[86:87]
	v_pk_add_f32 v[82:83], v[82:83], v[84:85] neg_lo:[0,1] neg_hi:[0,1]
	v_pk_fma_f32 v[90:91], v[88:89], s[28:29], v[66:67] op_sel_hi:[1,0,0]
	v_ldexp_f32 v93, v83, 1
	v_add_f32_e32 v83, v60, v80
	v_max_f32_e32 v80, 0, v83
	v_mul_f32_e64 v83, |v83|, s2
	v_exp_f32_e32 v129, v83
	v_ldexp_f32 v84, v86, 1
	v_pk_fma_f32 v[90:91], v[88:89], v[90:91], s[30:31] op_sel_hi:[1,1,0]
	v_ldexp_f32 v85, v87, 1
	v_add_f32_e32 v83, 1.0, v129
	v_pk_mul_f32 v[86:87], v[86:87], v[88:89]
	v_add_f32_e32 v88, -1.0, v83
	v_sub_f32_e32 v89, v88, v83
	v_add_f32_e32 v89, 1.0, v89
	v_sub_f32_e32 v88, v129, v88
	v_add_f32_e32 v92, v88, v89
	v_frexp_mant_f32_e32 v88, v83
	v_cmp_gt_f32_e32 vcc, s26, v88
	v_cvt_f64_f32_e32 v[88:89], v83
	v_frexp_exp_i32_f64_e32 v88, v[88:89]
	v_subbrev_co_u32_e32 v130, vcc, 0, v88, vcc
	v_sub_u32_e32 v89, 0, v130
	v_ldexp_f32 v88, v83, v89
	v_add_f32_e32 v83, v61, v81
	v_max_f32_e32 v81, 0, v83
	v_mul_f32_e64 v83, |v83|, s2
	v_exp_f32_e32 v131, v83
	v_ldexp_f32 v94, v92, v89
	v_pk_mul_f32 v[86:87], v[86:87], v[90:91]
	v_ldexp_f32 v82, v82, 1
	v_add_f32_e32 v83, 1.0, v131
	v_add_f32_e32 v89, -1.0, v83
	v_sub_f32_e32 v92, v89, v83
	v_add_f32_e32 v92, 1.0, v92
	v_sub_f32_e32 v89, v131, v89
	v_add_f32_e32 v92, v89, v92
	v_frexp_mant_f32_e32 v89, v83
	v_cvt_f64_f32_e32 v[98:99], v83
	v_cmp_gt_f32_e32 vcc, s26, v89
	v_frexp_exp_i32_f64_e32 v89, v[98:99]
	v_pk_add_f32 v[90:91], v[84:85], v[86:87]
	v_subbrev_co_u32_e32 v132, vcc, 0, v89, vcc
	v_sub_u32_e32 v95, 0, v132
	v_ldexp_f32 v89, v83, v95
	v_pk_add_f32 v[98:99], v[88:89], 1.0 op_sel_hi:[1,0]
	v_ldexp_f32 v95, v92, v95
	v_pk_add_f32 v[100:101], v[98:99], -1.0 op_sel_hi:[1,0]
	v_pk_add_f32 v[112:113], v[88:89], -1.0 op_sel_hi:[1,0]
	v_pk_add_f32 v[100:101], v[88:89], v[100:101] neg_lo:[0,1] neg_hi:[0,1]
	v_pk_add_f32 v[114:115], v[112:113], 1.0 op_sel_hi:[1,0]
	v_pk_add_f32 v[100:101], v[94:95], v[100:101]
	v_pk_add_f32 v[88:89], v[88:89], v[114:115] neg_lo:[0,1] neg_hi:[0,1]
	v_pk_add_f32 v[102:103], v[98:99], v[100:101]
	v_pk_add_f32 v[88:89], v[94:95], v[88:89]
	v_rcp_f32_e32 v110, v102
	v_rcp_f32_e32 v111, v103
	v_pk_add_f32 v[94:95], v[112:113], v[88:89]
	v_pk_add_f32 v[98:99], v[102:103], v[98:99] neg_lo:[0,1] neg_hi:[0,1]
	v_pk_add_f32 v[112:113], v[94:95], v[112:113] neg_lo:[0,1] neg_hi:[0,1]
	v_pk_add_f32 v[98:99], v[100:101], v[98:99] neg_lo:[0,1] neg_hi:[0,1]
	v_pk_mul_f32 v[100:101], v[94:95], v[110:111]
	v_pk_add_f32 v[88:89], v[88:89], v[112:113] neg_lo:[0,1] neg_hi:[0,1]
	v_pk_mul_f32 v[112:113], v[102:103], v[100:101]
	v_pk_add_f32 v[84:85], v[90:91], v[84:85] neg_lo:[0,1] neg_hi:[0,1]
	v_pk_fma_f32 v[114:115], v[100:101], v[102:103], v[112:113] neg_lo:[0,0,1] neg_hi:[0,0,1]
	v_pk_add_f32 v[84:85], v[86:87], v[84:85] neg_lo:[0,1] neg_hi:[0,1]
	v_pk_fma_f32 v[114:115], v[100:101], v[98:99], v[114:115]
	v_mov_b32_e32 v87, v85
	v_pk_add_f32 v[116:117], v[112:113], v[114:115]
	v_mov_b32_e32 v83, v93
	v_pk_add_f32 v[118:119], v[94:95], v[116:117] neg_lo:[0,1] neg_hi:[0,1]
	v_pk_add_f32 v[112:113], v[116:117], v[112:113] neg_lo:[0,1] neg_hi:[0,1]
	v_pk_add_f32 v[94:95], v[94:95], v[118:119] neg_lo:[0,1] neg_hi:[0,1]
	v_mov_b32_e32 v124, v90
	v_pk_add_f32 v[94:95], v[94:95], v[116:117] neg_lo:[0,1] neg_hi:[0,1]
	v_cmp_neq_f32_e32 vcc, s8, v97
	v_pk_add_f32 v[88:89], v[88:89], v[94:95]
	v_pk_add_f32 v[94:95], v[112:113], v[114:115] neg_lo:[0,1] neg_hi:[0,1]
	s_nop 0
	v_pk_add_f32 v[88:89], v[94:95], v[88:89]
	s_nop 0
	v_pk_add_f32 v[94:95], v[118:119], v[88:89]
	s_nop 0
	v_pk_mul_f32 v[112:113], v[110:111], v[94:95]
	s_nop 0
	v_pk_mul_f32 v[114:115], v[102:103], v[112:113]
	s_nop 0
	v_pk_fma_f32 v[102:103], v[112:113], v[102:103], v[114:115] neg_lo:[0,0,1] neg_hi:[0,0,1]
	s_nop 0
	v_pk_fma_f32 v[98:99], v[112:113], v[98:99], v[102:103]
	v_pk_add_f32 v[102:103], v[118:119], v[94:95] neg_lo:[0,1] neg_hi:[0,1]
	s_nop 0
	v_pk_add_f32 v[88:89], v[88:89], v[102:103]
	v_pk_add_f32 v[102:103], v[114:115], v[98:99]
	s_nop 0
	v_pk_add_f32 v[116:117], v[94:95], v[102:103] neg_lo:[0,1] neg_hi:[0,1]
	v_pk_add_f32 v[114:115], v[102:103], v[114:115] neg_lo:[0,1] neg_hi:[0,1]
	v_pk_add_f32 v[94:95], v[94:95], v[116:117] neg_lo:[0,1] neg_hi:[0,1]
	s_nop 0
	v_pk_add_f32 v[94:95], v[94:95], v[102:103] neg_lo:[0,1] neg_hi:[0,1]
	s_nop 0
	v_pk_add_f32 v[88:89], v[88:89], v[94:95]
	v_pk_add_f32 v[94:95], v[114:115], v[98:99] neg_lo:[0,1] neg_hi:[0,1]
	s_nop 0
	v_pk_add_f32 v[88:89], v[94:95], v[88:89]
	v_pk_add_f32 v[94:95], v[100:101], v[112:113]
	v_pk_add_f32 v[88:89], v[116:117], v[88:89]
	v_pk_add_f32 v[98:99], v[94:95], v[100:101] neg_lo:[0,1] neg_hi:[0,1]
; __device__ __forceinline__ float softplusf(float x) { return fmaxf(x, 0.f) + log1pf(__expf(-fabsf(x))); }
; __device__ void phaseA_tile(const Params& p, int l, int mt, int nt, char* smem) {
;     ...
;                 for (int j = 0; j < 2; ++j) {
;                     const int c = j * 16 + g4 * 4;
;                     const float4 db = *(const float4*)(p.dt_bias + l * 32 + c);
;                     const f32x4 v = acc[i][j];
;                     *(float4*)(p.dtb + (size_t)row * 32 + c) =
;                         make_float4(softplusf(v[0] + db.x), softplusf(v[1] + db.y), softplusf(v[2] + db.z), softplusf(v[3] + db.w));
	v_pk_mul_f32 v[88:89], v[110:111], v[88:89]
	v_pk_add_f32 v[98:99], v[112:113], v[98:99] neg_lo:[0,1] neg_hi:[0,1]
	s_nop 0
	v_pk_add_f32 v[88:89], v[98:99], v[88:89]
	s_nop 0
	v_pk_add_f32 v[98:99], v[94:95], v[88:89]
	s_nop 0
	v_pk_mul_f32 v[100:101], v[98:99], v[98:99]
	v_pk_add_f32 v[94:95], v[98:99], v[94:95] neg_lo:[0,1] neg_hi:[0,1]
	v_pk_fma_f32 v[102:103], v[100:101], s[28:29], v[66:67] op_sel_hi:[1,0,0]
	v_pk_add_f32 v[88:89], v[88:89], v[94:95] neg_lo:[0,1] neg_hi:[0,1]
	v_ldexp_f32 v94, v98, 1
	v_pk_fma_f32 v[102:103], v[100:101], v[102:103], s[30:31] op_sel_hi:[1,1,0]
	v_ldexp_f32 v95, v99, 1
	v_pk_mul_f32 v[98:99], v[98:99], v[100:101]
	v_cvt_f32_i32_e32 v101, v121
	v_cvt_f32_i32_e32 v100, v120
	v_ldexp_f32 v111, v89, 1
	v_ldexp_f32 v88, v88, 1
	v_mov_b32_e32 v89, v111
	v_pk_mul_f32 v[112:113], v[100:101], s[12:13] op_sel_hi:[1,0]
	s_nop 0
	v_pk_fma_f32 v[114:115], v[100:101], s[12:13], v[112:113] op_sel_hi:[1,0,1] neg_lo:[0,0,1] neg_hi:[0,0,1]
	v_mov_b32_e32 v86, v112
	v_pk_fma_f32 v[100:101], v[100:101], s[14:15], v[114:115] op_sel_hi:[1,0,1]
	v_mov_b32_e32 v121, v113
	v_mov_b32_e32 v92, v100
	v_pk_add_f32 v[86:87], v[86:87], v[92:93]
	v_pk_add_f32 v[92:93], v[82:83], v[84:85]
	v_mov_b32_e32 v85, v91
	v_mov_b32_e32 v83, v93
	v_pk_add_f32 v[114:115], v[112:113], v[100:101]
	v_pk_add_f32 v[82:83], v[82:83], v[84:85]
	v_pk_add_f32 v[84:85], v[90:91], v[92:93]
	v_mov_b32_e32 v125, v115
	v_pk_add_f32 v[116:117], v[114:115], v[84:85]
	v_mov_b32_e32 v122, v84
	v_mov_b32_e32 v123, v117
	v_pk_add_f32 v[122:123], v[122:123], v[124:125] neg_lo:[0,1] neg_hi:[0,1]
	v_mov_b32_e32 v118, v116
	v_mov_b32_e32 v119, v115
	v_mov_b32_e32 v120, v114
	v_mov_b32_e32 v124, v114
	v_mov_b32_e32 v125, v117
	v_mov_b32_e32 v113, v123
	v_pk_add_f32 v[118:119], v[118:119], v[120:121] neg_lo:[0,1] neg_hi:[0,1]
	v_mov_b32_e32 v120, v84
	v_mov_b32_e32 v121, v101
	v_pk_add_f32 v[112:113], v[124:125], v[112:113] neg_lo:[0,1] neg_hi:[0,1]
	v_pk_add_f32 v[120:121], v[120:121], v[118:119] neg_lo:[0,1] neg_hi:[0,1]
	v_mov_b32_e32 v124, v112
	v_mov_b32_e32 v125, v119
	v_mov_b32_e32 v126, v116
	v_mov_b32_e32 v127, v85
	v_mov_b32_e32 v119, v91
	v_pk_add_f32 v[124:125], v[100:101], v[124:125] neg_lo:[0,1] neg_hi:[0,1]
	v_pk_add_f32 v[118:119], v[126:127], v[118:119] neg_lo:[0,1] neg_hi:[0,1]
	v_mov_b32_e32 v101, v115
	v_pk_add_f32 v[84:85], v[84:85], v[90:91] neg_lo:[0,1] neg_hi:[0,1]
	v_pk_add_f32 v[86:87], v[86:87], v[118:119] neg_lo:[0,1] neg_hi:[0,1]
	v_pk_add_f32 v[90:91], v[100:101], v[112:113] neg_lo:[0,1] neg_hi:[0,1]
	v_pk_add_f32 v[82:83], v[82:83], v[122:123] neg_lo:[0,1] neg_hi:[0,1]
	v_pk_add_f32 v[84:85], v[92:93], v[84:85] neg_lo:[0,1] neg_hi:[0,1]
	v_pk_add_f32 v[92:93], v[82:83], v[90:91]
	v_mov_b32_e32 v91, v121
	v_mov_b32_e32 v83, v87
	v_pk_add_f32 v[100:101], v[120:121], v[86:87]
	v_pk_add_f32 v[82:83], v[90:91], v[82:83]
	v_mov_b32_e32 v86, v92
	v_pk_add_f32 v[82:83], v[82:83], v[124:125] neg_lo:[0,1] neg_hi:[0,1]
	v_mov_b32_e32 v87, v101
	v_pk_add_f32 v[86:87], v[86:87], v[82:83] neg_lo:[0,1] neg_hi:[0,1]
	v_pk_add_f32 v[82:83], v[84:85], v[82:83] neg_lo:[0,1] neg_hi:[0,1]
	v_pk_add_f32 v[86:87], v[90:91], v[86:87] neg_lo:[0,1] neg_hi:[0,1]
	v_pk_add_f32 v[84:85], v[100:101], v[92:93]
	v_pk_add_f32 v[82:83], v[82:83], v[86:87]
	v_pk_add_f32 v[86:87], v[116:117], v[84:85]
	s_nop 0
	v_pk_add_f32 v[90:91], v[86:87], v[116:117] neg_lo:[0,1] neg_hi:[0,1]
	s_nop 0
	v_pk_add_f32 v[84:85], v[84:85], v[90:91] neg_lo:[0,1] neg_hi:[0,1]
	s_nop 0
	v_pk_add_f32 v[82:83], v[82:83], v[84:85]
	s_nop 0
	v_pk_add_f32 v[82:83], v[86:87], v[82:83]
	v_pk_mul_f32 v[86:87], v[98:99], v[102:103]
	v_cndmask_b32_e32 v82, v160, v82, vcc
	v_cmp_neq_f32_e32 vcc, s8, v128
	v_pk_add_f32 v[90:91], v[94:95], v[86:87]
	s_nop 0
	v_cndmask_b32_e32 v83, v160, v83, vcc
	v_cmp_ngt_f32_e32 vcc, -1.0, v128
	v_pk_add_f32 v[94:95], v[90:91], v[94:95] neg_lo:[0,1] neg_hi:[0,1]
	v_mov_b32_e32 v114, v90
	v_cndmask_b32_e32 v83, v161, v83, vcc
	v_cmp_ngt_f32_e32 vcc, -1.0, v97
	v_pk_add_f32 v[86:87], v[86:87], v[94:95] neg_lo:[0,1] neg_hi:[0,1]
	s_nop 0
	v_cndmask_b32_e32 v82, v161, v82, vcc
	v_cmp_neq_f32_e32 vcc, -1.0, v97
	v_pk_add_f32 v[98:99], v[88:89], v[86:87]
	v_mov_b32_e32 v95, v87
	v_cndmask_b32_e32 v82, v162, v82, vcc
	v_cmp_neq_f32_e32 vcc, -1.0, v128
	v_mov_b32_e32 v89, v99
	v_mov_b32_e32 v87, v91
	v_cndmask_b32_e32 v83, v162, v83, vcc
	v_cmp_lt_f32_e64 vcc, |v97|, s9
	v_cndmask_b32_e64 v83, v83, v128, s[0:1]
	v_pk_add_f32 v[86:87], v[88:89], v[86:87]
	v_cndmask_b32_e32 v82, v82, v97, vcc
	v_pk_add_f32 v[78:79], v[78:79], v[82:83]
	v_cvt_f32_i32_e32 v83, v132
	v_cvt_f32_i32_e32 v82, v130
	v_pk_add_f32 v[88:89], v[90:91], v[98:99]
	v_cmp_neq_f32_e32 vcc, s8, v129
	v_mov_b32_e32 v112, v88
	v_pk_mul_f32 v[84:85], v[82:83], s[12:13] op_sel_hi:[1,0]
	v_mov_b32_e32 v117, v89
	v_pk_fma_f32 v[92:93], v[82:83], s[12:13], v[84:85] op_sel_hi:[1,0,1] neg_lo:[0,0,1] neg_hi:[0,0,1]
	v_mov_b32_e32 v94, v84
	v_pk_fma_f32 v[82:83], v[82:83], s[14:15], v[92:93] op_sel_hi:[1,0,1]
	v_cmp_lt_f32_e64 s[0:1], |v131|, s9
	v_pk_add_f32 v[92:93], v[84:85], v[82:83]
	v_mov_b32_e32 v110, v82
	v_pk_add_f32 v[100:101], v[92:93], v[88:89]
	v_mov_b32_e32 v115, v93
	v_mov_b32_e32 v113, v101
	v_pk_add_f32 v[112:113], v[112:113], v[114:115] neg_lo:[0,1] neg_hi:[0,1]
	v_pk_add_f32 v[94:95], v[94:95], v[110:111]
	v_mov_b32_e32 v102, v100
	v_mov_b32_e32 v103, v93
	v_mov_b32_e32 v110, v92
	v_mov_b32_e32 v111, v85
	v_mov_b32_e32 v114, v92
	v_mov_b32_e32 v115, v101
	v_mov_b32_e32 v85, v113
	v_pk_add_f32 v[102:103], v[102:103], v[110:111] neg_lo:[0,1] neg_hi:[0,1]
	v_mov_b32_e32 v110, v88
	v_mov_b32_e32 v111, v83
; __device__ __forceinline__ float softplusf(float x) { return fmaxf(x, 0.f) + log1pf(__expf(-fabsf(x))); }
; __device__ __forceinline__ float logsigf(float x) { return fminf(x, 0.f) - log1pf(__expf(-fabsf(x))); }
; __device__ void phaseA_tile(const Params& p, int l, int mt, int nt, char* smem) {
;     ...
;                 for (int j = 0; j < 2; ++j) {
;                     const int c = j * 16 + g4 * 4;
;                     const float4 db = *(const float4*)(p.dt_bias + l * 32 + c);
;                     const f32x4 v = acc[i][j];
;                     *(float4*)(p.dtb + (size_t)row * 32 + c) =
;                         make_float4(softplusf(v[0] + db.x), softplusf(v[1] + db.y), softplusf(v[2] + db.z), softplusf(v[3] + db.w));
;                 }
;                 {
;                     const int c = g4 * 4;
;                     const float4 fb = *(const float4*)(p.b_f + l * 16 + c);
;                     const f32x4 v = acc[i][2];
;                     float4 lf = make_float4(logsigf(v[0] + fb.x), logsigf(v[1] + fb.y), logsigf(v[2] + fb.z), logsigf(v[3] + fb.w));
	v_pk_add_f32 v[84:85], v[114:115], v[84:85] neg_lo:[0,1] neg_hi:[0,1]
	v_pk_add_f32 v[110:111], v[110:111], v[102:103] neg_lo:[0,1] neg_hi:[0,1]
	v_mov_b32_e32 v114, v84
	v_mov_b32_e32 v115, v103
	v_mov_b32_e32 v116, v100
	v_mov_b32_e32 v103, v91
	v_pk_add_f32 v[114:115], v[82:83], v[114:115] neg_lo:[0,1] neg_hi:[0,1]
	v_pk_add_f32 v[102:103], v[116:117], v[102:103] neg_lo:[0,1] neg_hi:[0,1]
	v_mov_b32_e32 v83, v93
	v_pk_add_f32 v[88:89], v[88:89], v[90:91] neg_lo:[0,1] neg_hi:[0,1]
	v_pk_add_f32 v[90:91], v[94:95], v[102:103] neg_lo:[0,1] neg_hi:[0,1]
	v_pk_add_f32 v[82:83], v[82:83], v[84:85] neg_lo:[0,1] neg_hi:[0,1]
	v_pk_add_f32 v[84:85], v[86:87], v[112:113] neg_lo:[0,1] neg_hi:[0,1]
	v_pk_add_f32 v[92:93], v[110:111], v[90:91]
	v_pk_add_f32 v[86:87], v[84:85], v[82:83]
	v_mov_b32_e32 v83, v111
	v_mov_b32_e32 v85, v91
	v_pk_add_f32 v[84:85], v[82:83], v[84:85]
	v_mov_b32_e32 v90, v86
	v_pk_add_f32 v[84:85], v[84:85], v[114:115] neg_lo:[0,1] neg_hi:[0,1]
	v_mov_b32_e32 v91, v93
	v_pk_add_f32 v[88:89], v[98:99], v[88:89] neg_lo:[0,1] neg_hi:[0,1]
	v_pk_add_f32 v[90:91], v[90:91], v[84:85] neg_lo:[0,1] neg_hi:[0,1]
	v_pk_add_f32 v[84:85], v[88:89], v[84:85] neg_lo:[0,1] neg_hi:[0,1]
	v_pk_add_f32 v[82:83], v[82:83], v[90:91] neg_lo:[0,1] neg_hi:[0,1]
	s_nop 0
	v_pk_add_f32 v[82:83], v[84:85], v[82:83]
	v_pk_add_f32 v[84:85], v[92:93], v[86:87]
	s_nop 0
	v_pk_add_f32 v[86:87], v[100:101], v[84:85]
	s_nop 0
	v_pk_add_f32 v[88:89], v[86:87], v[100:101] neg_lo:[0,1] neg_hi:[0,1]
	s_nop 0
	v_pk_add_f32 v[84:85], v[84:85], v[88:89] neg_lo:[0,1] neg_hi:[0,1]
	s_nop 0
	v_pk_add_f32 v[82:83], v[82:83], v[84:85]
	s_nop 0
	v_pk_add_f32 v[82:83], v[86:87], v[82:83]
	s_nop 0
	v_cndmask_b32_e32 v82, v160, v82, vcc
	v_cmp_neq_f32_e32 vcc, s8, v131
	s_nop 1
	v_cndmask_b32_e32 v83, v160, v83, vcc
	v_cmp_ngt_f32_e32 vcc, -1.0, v131
	s_nop 1
	v_cndmask_b32_e32 v83, v161, v83, vcc
	v_cmp_ngt_f32_e32 vcc, -1.0, v129
	s_nop 1
	v_cndmask_b32_e32 v82, v161, v82, vcc
	v_cmp_neq_f32_e32 vcc, -1.0, v129
	s_nop 1
	v_cndmask_b32_e32 v82, v162, v82, vcc
	v_cmp_neq_f32_e32 vcc, -1.0, v131
	s_nop 1
	v_cndmask_b32_e32 v83, v162, v83, vcc
	v_cmp_lt_f32_e64 vcc, |v129|, s9
	v_cndmask_b32_e64 v83, v83, v131, s[0:1]
	s_and_b64 s[0:1], s[60:61], exec
	v_cndmask_b32_e32 v82, v82, v129, vcc
	v_pk_add_f32 v[80:81], v[80:81], v[82:83]
	global_store_dwordx4 v[68:69], v[78:81], off offset:64
	global_load_dwordx4 v[78:81], v0, s[78:79]
	s_cselect_b32 s7, s46, s42
	s_cselect_b32 s6, s43, s59
	s_waitcnt vmcnt(0)
	v_add_f32_e32 v69, v54, v78
	v_min_f32_e32 v68, 0, v69
	v_mul_f32_e64 v69, |v69|, s2
	v_exp_f32_e32 v97, v69
	v_add_f32_e32 v79, v55, v79
	v_add_f32_e32 v81, v57, v81
	v_add_f32_e32 v69, 1.0, v97
	v_add_f32_e32 v78, -1.0, v69
	v_sub_f32_e32 v82, v78, v69
	v_add_f32_e32 v82, 1.0, v82
	v_sub_f32_e32 v78, v97, v78
	v_add_f32_e32 v84, v78, v82
	v_frexp_mant_f32_e32 v78, v69
	v_cvt_f64_f32_e32 v[82:83], v69
	v_cmp_gt_f32_e32 vcc, s26, v78
	v_frexp_exp_i32_f64_e32 v78, v[82:83]
	s_nop 0
	v_subbrev_co_u32_e32 v118, vcc, 0, v78, vcc
	v_sub_u32_e32 v82, 0, v118
	v_ldexp_f32 v78, v69, v82
	v_min_f32_e32 v69, 0, v79
	v_mul_f32_e64 v79, |v79|, s2
	v_exp_f32_e32 v126, v79
	v_ldexp_f32 v82, v84, v82
	v_add_f32_e32 v79, 1.0, v126
	v_add_f32_e32 v83, -1.0, v79
	v_sub_f32_e32 v84, v83, v79
	v_add_f32_e32 v84, 1.0, v84
	v_sub_f32_e32 v83, v126, v83
	v_add_f32_e32 v83, v83, v84
	v_frexp_mant_f32_e32 v84, v79
	v_cmp_gt_f32_e32 vcc, s26, v84
	v_cvt_f64_f32_e32 v[84:85], v79
	v_frexp_exp_i32_f64_e32 v84, v[84:85]
	v_subbrev_co_u32_e32 v119, vcc, 0, v84, vcc
	v_sub_u32_e32 v84, 0, v119
	v_ldexp_f32 v79, v79, v84
	v_ldexp_f32 v83, v83, v84
	v_pk_add_f32 v[84:85], v[78:79], 1.0 op_sel_hi:[1,0]
	v_pk_add_f32 v[92:93], v[78:79], -1.0 op_sel_hi:[1,0]
	v_pk_add_f32 v[86:87], v[84:85], -1.0 op_sel_hi:[1,0]
	v_pk_add_f32 v[94:95], v[92:93], 1.0 op_sel_hi:[1,0]
	v_pk_add_f32 v[86:87], v[78:79], v[86:87] neg_lo:[0,1] neg_hi:[0,1]
	v_pk_add_f32 v[78:79], v[78:79], v[94:95] neg_lo:[0,1] neg_hi:[0,1]
	v_pk_add_f32 v[86:87], v[82:83], v[86:87]
	v_pk_add_f32 v[78:79], v[82:83], v[78:79]
	v_pk_add_f32 v[88:89], v[84:85], v[86:87]
	v_pk_add_f32 v[82:83], v[92:93], v[78:79]
	v_rcp_f32_e32 v90, v88
	v_rcp_f32_e32 v91, v89
	v_pk_add_f32 v[84:85], v[88:89], v[84:85] neg_lo:[0,1] neg_hi:[0,1]
	v_pk_add_f32 v[92:93], v[82:83], v[92:93] neg_lo:[0,1] neg_hi:[0,1]
	v_pk_add_f32 v[84:85], v[86:87], v[84:85] neg_lo:[0,1] neg_hi:[0,1]
	v_pk_mul_f32 v[86:87], v[82:83], v[90:91]
	v_pk_add_f32 v[78:79], v[78:79], v[92:93] neg_lo:[0,1] neg_hi:[0,1]
	v_pk_mul_f32 v[92:93], v[88:89], v[86:87]
	v_cmp_lt_f32_e64 s[0:1], |v126|, s9
	v_pk_fma_f32 v[94:95], v[86:87], v[88:89], v[92:93] neg_lo:[0,0,1] neg_hi:[0,0,1]
	s_nop 0
	v_pk_fma_f32 v[94:95], v[86:87], v[84:85], v[94:95]
	s_nop 0
	v_pk_add_f32 v[98:99], v[92:93], v[94:95]
	s_nop 0
	v_pk_add_f32 v[100:101], v[82:83], v[98:99] neg_lo:[0,1] neg_hi:[0,1]
	v_pk_add_f32 v[92:93], v[98:99], v[92:93] neg_lo:[0,1] neg_hi:[0,1]
	v_pk_add_f32 v[82:83], v[82:83], v[100:101] neg_lo:[0,1] neg_hi:[0,1]
	s_nop 0
	v_pk_add_f32 v[82:83], v[82:83], v[98:99] neg_lo:[0,1] neg_hi:[0,1]
	s_nop 0
	v_pk_add_f32 v[78:79], v[78:79], v[82:83]
	v_pk_add_f32 v[82:83], v[92:93], v[94:95] neg_lo:[0,1] neg_hi:[0,1]
	s_nop 0
	v_pk_add_f32 v[78:79], v[82:83], v[78:79]
	s_nop 0
	v_pk_add_f32 v[82:83], v[100:101], v[78:79]
	s_nop 0
	v_pk_mul_f32 v[92:93], v[90:91], v[82:83]
	s_nop 0
	v_pk_mul_f32 v[94:95], v[88:89], v[92:93]
	s_nop 0
	v_pk_fma_f32 v[88:89], v[92:93], v[88:89], v[94:95] neg_lo:[0,0,1] neg_hi:[0,0,1]
	s_nop 0
	v_pk_fma_f32 v[84:85], v[92:93], v[84:85], v[88:89]
; __device__ __forceinline__ float logsigf(float x) { return fminf(x, 0.f) - log1pf(__expf(-fabsf(x))); }
; __device__ void phaseA_tile(const Params& p, int l, int mt, int nt, char* smem) {
;     ...
;                 {
;                     const int c = g4 * 4;
;                     const float4 fb = *(const float4*)(p.b_f + l * 16 + c);
;                     const f32x4 v = acc[i][2];
;                     float4 lf = make_float4(logsigf(v[0] + fb.x), logsigf(v[1] + fb.y), logsigf(v[2] + fb.z), logsigf(v[3] + fb.w));
	v_pk_add_f32 v[88:89], v[100:101], v[82:83] neg_lo:[0,1] neg_hi:[0,1]
	s_nop 0
	v_pk_add_f32 v[78:79], v[78:79], v[88:89]
	v_pk_add_f32 v[88:89], v[94:95], v[84:85]
	s_nop 0
	v_pk_add_f32 v[98:99], v[82:83], v[88:89] neg_lo:[0,1] neg_hi:[0,1]
	v_pk_add_f32 v[94:95], v[88:89], v[94:95] neg_lo:[0,1] neg_hi:[0,1]
	v_pk_add_f32 v[82:83], v[82:83], v[98:99] neg_lo:[0,1] neg_hi:[0,1]
	s_nop 0
	v_pk_add_f32 v[82:83], v[82:83], v[88:89] neg_lo:[0,1] neg_hi:[0,1]
	s_nop 0
	v_pk_add_f32 v[78:79], v[78:79], v[82:83]
	v_pk_add_f32 v[82:83], v[94:95], v[84:85] neg_lo:[0,1] neg_hi:[0,1]
	s_nop 0
	v_pk_add_f32 v[78:79], v[82:83], v[78:79]
	v_pk_add_f32 v[82:83], v[86:87], v[92:93]
	v_pk_add_f32 v[78:79], v[98:99], v[78:79]
	v_pk_add_f32 v[84:85], v[82:83], v[86:87] neg_lo:[0,1] neg_hi:[0,1]
	v_pk_mul_f32 v[78:79], v[90:91], v[78:79]
	v_pk_add_f32 v[84:85], v[92:93], v[84:85] neg_lo:[0,1] neg_hi:[0,1]
	s_nop 0
	v_pk_add_f32 v[78:79], v[84:85], v[78:79]
	s_nop 0
	v_pk_add_f32 v[84:85], v[82:83], v[78:79]
	s_nop 0
	v_pk_add_f32 v[82:83], v[84:85], v[82:83] neg_lo:[0,1] neg_hi:[0,1]
	v_pk_mul_f32 v[88:89], v[84:85], v[84:85]
	v_pk_add_f32 v[78:79], v[78:79], v[82:83] neg_lo:[0,1] neg_hi:[0,1]
	v_pk_fma_f32 v[90:91], v[88:89], s[28:29], v[66:67] op_sel_hi:[1,0,0]
	v_ldexp_f32 v93, v79, 1
	v_add_f32_e32 v79, v56, v80
	v_ldexp_f32 v86, v78, 1
	v_min_f32_e32 v78, 0, v79
	v_mul_f32_e64 v79, |v79|, s2
	v_exp_f32_e32 v127, v79
	v_ldexp_f32 v82, v84, 1
	v_pk_fma_f32 v[90:91], v[88:89], v[90:91], s[30:31] op_sel_hi:[1,1,0]
	v_ldexp_f32 v83, v85, 1
	v_add_f32_e32 v79, 1.0, v127
	v_add_f32_e32 v80, -1.0, v79
	v_sub_f32_e32 v87, v80, v79
	v_add_f32_e32 v87, 1.0, v87
	v_sub_f32_e32 v80, v127, v80
	v_pk_mul_f32 v[84:85], v[84:85], v[88:89]
	v_add_f32_e32 v87, v80, v87
	v_frexp_mant_f32_e32 v80, v79
	v_cvt_f64_f32_e32 v[88:89], v79
	v_cmp_gt_f32_e32 vcc, s26, v80
	v_frexp_exp_i32_f64_e32 v80, v[88:89]
	v_pk_mul_f32 v[84:85], v[84:85], v[90:91]
	v_subbrev_co_u32_e32 v128, vcc, 0, v80, vcc
	v_sub_u32_e32 v88, 0, v128
	v_ldexp_f32 v80, v79, v88
	v_min_f32_e32 v79, 0, v81
	v_mul_f32_e64 v81, |v81|, s2
	v_exp_f32_e32 v129, v81
	v_ldexp_f32 v88, v87, v88
	v_pk_add_f32 v[90:91], v[82:83], v[84:85]
	v_add_f32_e32 v81, 1.0, v129
	v_add_f32_e32 v87, -1.0, v81
	v_sub_f32_e32 v89, v87, v81
	v_add_f32_e32 v89, 1.0, v89
	v_sub_f32_e32 v87, v129, v87
	v_add_f32_e32 v87, v87, v89
	v_frexp_mant_f32_e32 v89, v81
	v_cvt_f64_f32_e32 v[94:95], v81
	v_cmp_gt_f32_e32 vcc, s26, v89
	v_frexp_exp_i32_f64_e32 v89, v[94:95]
	v_pk_add_f32 v[82:83], v[90:91], v[82:83] neg_lo:[0,1] neg_hi:[0,1]
	v_subbrev_co_u32_e32 v130, vcc, 0, v89, vcc
	v_sub_u32_e32 v89, 0, v130
	v_ldexp_f32 v81, v81, v89
	v_pk_add_f32 v[94:95], v[80:81], 1.0 op_sel_hi:[1,0]
	v_ldexp_f32 v89, v87, v89
	v_pk_add_f32 v[98:99], v[94:95], -1.0 op_sel_hi:[1,0]
	v_pk_add_f32 v[110:111], v[80:81], -1.0 op_sel_hi:[1,0]
	v_pk_add_f32 v[98:99], v[80:81], v[98:99] neg_lo:[0,1] neg_hi:[0,1]
	v_pk_add_f32 v[112:113], v[110:111], 1.0 op_sel_hi:[1,0]
	v_pk_add_f32 v[98:99], v[88:89], v[98:99]
	v_pk_add_f32 v[80:81], v[80:81], v[112:113] neg_lo:[0,1] neg_hi:[0,1]
	v_pk_add_f32 v[100:101], v[94:95], v[98:99]
	v_pk_add_f32 v[80:81], v[88:89], v[80:81]
	v_rcp_f32_e32 v102, v100
	v_rcp_f32_e32 v103, v101
	v_pk_add_f32 v[88:89], v[110:111], v[80:81]
	v_pk_add_f32 v[94:95], v[100:101], v[94:95] neg_lo:[0,1] neg_hi:[0,1]
	v_pk_add_f32 v[110:111], v[88:89], v[110:111] neg_lo:[0,1] neg_hi:[0,1]
	v_pk_add_f32 v[94:95], v[98:99], v[94:95] neg_lo:[0,1] neg_hi:[0,1]
	v_pk_mul_f32 v[98:99], v[88:89], v[102:103]
	v_pk_add_f32 v[80:81], v[80:81], v[110:111] neg_lo:[0,1] neg_hi:[0,1]
	v_pk_mul_f32 v[110:111], v[100:101], v[98:99]
	v_pk_add_f32 v[82:83], v[84:85], v[82:83] neg_lo:[0,1] neg_hi:[0,1]
	v_pk_fma_f32 v[112:113], v[98:99], v[100:101], v[110:111] neg_lo:[0,0,1] neg_hi:[0,0,1]
	v_mov_b32_e32 v85, v83
	v_pk_fma_f32 v[112:113], v[98:99], v[94:95], v[112:113]
	v_mov_b32_e32 v87, v93
	v_pk_add_f32 v[114:115], v[110:111], v[112:113]
	v_mov_b32_e32 v122, v90
	v_pk_add_f32 v[116:117], v[88:89], v[114:115] neg_lo:[0,1] neg_hi:[0,1]
	v_pk_add_f32 v[110:111], v[114:115], v[110:111] neg_lo:[0,1] neg_hi:[0,1]
	v_pk_add_f32 v[88:89], v[88:89], v[116:117] neg_lo:[0,1] neg_hi:[0,1]
	v_cmp_neq_f32_e32 vcc, s8, v97
	v_pk_add_f32 v[88:89], v[88:89], v[114:115] neg_lo:[0,1] neg_hi:[0,1]
	s_nop 0
	v_pk_add_f32 v[80:81], v[80:81], v[88:89]
	v_pk_add_f32 v[88:89], v[110:111], v[112:113] neg_lo:[0,1] neg_hi:[0,1]
	s_nop 0
	v_pk_add_f32 v[80:81], v[88:89], v[80:81]
	s_nop 0
	v_pk_add_f32 v[88:89], v[116:117], v[80:81]
	s_nop 0
	v_pk_mul_f32 v[110:111], v[102:103], v[88:89]
	s_nop 0
	v_pk_mul_f32 v[112:113], v[100:101], v[110:111]
	s_nop 0
	v_pk_fma_f32 v[100:101], v[110:111], v[100:101], v[112:113] neg_lo:[0,0,1] neg_hi:[0,0,1]
	s_nop 0
	v_pk_fma_f32 v[94:95], v[110:111], v[94:95], v[100:101]
	v_pk_add_f32 v[100:101], v[116:117], v[88:89] neg_lo:[0,1] neg_hi:[0,1]
	s_nop 0
	v_pk_add_f32 v[80:81], v[80:81], v[100:101]
	v_pk_add_f32 v[100:101], v[112:113], v[94:95]
	s_nop 0
	v_pk_add_f32 v[114:115], v[88:89], v[100:101] neg_lo:[0,1] neg_hi:[0,1]
	v_pk_add_f32 v[112:113], v[100:101], v[112:113] neg_lo:[0,1] neg_hi:[0,1]
	v_pk_add_f32 v[88:89], v[88:89], v[114:115] neg_lo:[0,1] neg_hi:[0,1]
	s_nop 0
	v_pk_add_f32 v[88:89], v[88:89], v[100:101] neg_lo:[0,1] neg_hi:[0,1]
	s_nop 0
	v_pk_add_f32 v[80:81], v[80:81], v[88:89]
	v_pk_add_f32 v[88:89], v[112:113], v[94:95] neg_lo:[0,1] neg_hi:[0,1]
	s_nop 0
	v_pk_add_f32 v[80:81], v[88:89], v[80:81]
	v_pk_add_f32 v[88:89], v[98:99], v[110:111]
	v_pk_add_f32 v[80:81], v[114:115], v[80:81]
	v_pk_add_f32 v[94:95], v[88:89], v[98:99] neg_lo:[0,1] neg_hi:[0,1]
; __device__ __forceinline__ float softplusf(float x) { return fmaxf(x, 0.f) + log1pf(__expf(-fabsf(x))); }
; __device__ __forceinline__ float logsigf(float x) { return fminf(x, 0.f) - log1pf(__expf(-fabsf(x))); }
; __device__ void phaseA_tile(const Params& p, int l, int mt, int nt, char* smem) {
;     ...
;                     const float4 fb = *(const float4*)(p.b_f + l * 16 + c);
;                     const f32x4 v = acc[i][2];
;                     float4 lf = make_float4(logsigf(v[0] + fb.x), logsigf(v[1] + fb.y), logsigf(v[2] + fb.z), logsigf(v[3] + fb.w));
;                     float* o = samp ? (p.out + O_LFS + ((size_t)l * TSM + (row - TP)) * 16 + c)
;                                     : (p.out + O_LFP + ((size_t)l * TP + row) * 16 + c);
;                     *(float4*)o = lf;
;                     *(float4*)(lf_s + rl * 16 + c) = lf;
	v_pk_mul_f32 v[80:81], v[102:103], v[80:81]
	v_pk_add_f32 v[94:95], v[110:111], v[94:95] neg_lo:[0,1] neg_hi:[0,1]
	s_nop 0
	v_pk_add_f32 v[80:81], v[94:95], v[80:81]
	s_nop 0
	v_pk_add_f32 v[94:95], v[88:89], v[80:81]
	s_nop 0
	v_pk_add_f32 v[88:89], v[94:95], v[88:89] neg_lo:[0,1] neg_hi:[0,1]
	v_pk_mul_f32 v[100:101], v[94:95], v[94:95]
	v_pk_add_f32 v[80:81], v[80:81], v[88:89] neg_lo:[0,1] neg_hi:[0,1]
	v_pk_fma_f32 v[102:103], v[100:101], s[28:29], v[66:67] op_sel_hi:[1,0,0]
	v_ldexp_f32 v98, v80, 1
	v_add_u32_e32 v80, 0xffff8000, v76
	v_ldexp_f32 v111, v81, 1
	v_ashrrev_i32_e32 v81, 31, v80
	v_cndmask_b32_e64 v77, v77, v81, s[60:61]
	v_cndmask_b32_e64 v76, v76, v80, s[60:61]
	v_cvt_f32_i32_e32 v81, v119
	v_cvt_f32_i32_e32 v80, v118
	v_ldexp_f32 v88, v94, 1
	v_pk_fma_f32 v[102:103], v[100:101], v[102:103], s[30:31] op_sel_hi:[1,1,0]
	v_ldexp_f32 v89, v95, 1
	v_pk_mul_f32 v[94:95], v[94:95], v[100:101]
	v_pk_mul_f32 v[100:101], v[80:81], s[12:13] op_sel_hi:[1,0]
	v_mov_b32_e32 v99, v111
	v_pk_fma_f32 v[112:113], v[80:81], s[12:13], v[100:101] op_sel_hi:[1,0,1] neg_lo:[0,0,1] neg_hi:[0,0,1]
	v_mov_b32_e32 v84, v100
	v_pk_fma_f32 v[80:81], v[80:81], s[14:15], v[112:113] op_sel_hi:[1,0,1]
	v_mov_b32_e32 v119, v101
	v_mov_b32_e32 v92, v80
	v_pk_add_f32 v[84:85], v[84:85], v[92:93]
	v_pk_add_f32 v[92:93], v[86:87], v[82:83]
	v_mov_b32_e32 v83, v91
	v_mov_b32_e32 v87, v93
	v_pk_add_f32 v[112:113], v[100:101], v[80:81]
	v_pk_add_f32 v[82:83], v[86:87], v[82:83]
	v_pk_add_f32 v[86:87], v[90:91], v[92:93]
	v_mov_b32_e32 v123, v113
	v_pk_add_f32 v[114:115], v[112:113], v[86:87]
	v_mov_b32_e32 v120, v86
	v_mov_b32_e32 v121, v115
	v_pk_add_f32 v[120:121], v[120:121], v[122:123] neg_lo:[0,1] neg_hi:[0,1]
	v_mov_b32_e32 v116, v114
	v_mov_b32_e32 v117, v113
	v_mov_b32_e32 v118, v112
	v_mov_b32_e32 v122, v112
	v_mov_b32_e32 v123, v115
	v_mov_b32_e32 v101, v121
	v_pk_add_f32 v[116:117], v[116:117], v[118:119] neg_lo:[0,1] neg_hi:[0,1]
	v_mov_b32_e32 v118, v86
	v_mov_b32_e32 v119, v81
	v_pk_add_f32 v[100:101], v[122:123], v[100:101] neg_lo:[0,1] neg_hi:[0,1]
	v_pk_add_f32 v[118:119], v[118:119], v[116:117] neg_lo:[0,1] neg_hi:[0,1]
	v_mov_b32_e32 v122, v100
	v_mov_b32_e32 v123, v117
	v_mov_b32_e32 v124, v114
	v_mov_b32_e32 v125, v87
	v_mov_b32_e32 v117, v91
	v_pk_add_f32 v[122:123], v[80:81], v[122:123] neg_lo:[0,1] neg_hi:[0,1]
	v_pk_add_f32 v[116:117], v[124:125], v[116:117] neg_lo:[0,1] neg_hi:[0,1]
	v_mov_b32_e32 v81, v113
	v_pk_add_f32 v[84:85], v[84:85], v[116:117] neg_lo:[0,1] neg_hi:[0,1]
	v_pk_add_f32 v[80:81], v[80:81], v[100:101] neg_lo:[0,1] neg_hi:[0,1]
	v_pk_add_f32 v[82:83], v[82:83], v[120:121] neg_lo:[0,1] neg_hi:[0,1]
	v_pk_add_f32 v[86:87], v[86:87], v[90:91] neg_lo:[0,1] neg_hi:[0,1]
	v_pk_add_f32 v[90:91], v[82:83], v[80:81]
	v_mov_b32_e32 v81, v119
	v_mov_b32_e32 v83, v85
	v_pk_add_f32 v[86:87], v[92:93], v[86:87] neg_lo:[0,1] neg_hi:[0,1]
	v_pk_add_f32 v[92:93], v[118:119], v[84:85]
	v_pk_add_f32 v[82:83], v[80:81], v[82:83]
	v_mov_b32_e32 v84, v90
	v_pk_add_f32 v[82:83], v[82:83], v[122:123] neg_lo:[0,1] neg_hi:[0,1]
	v_mov_b32_e32 v85, v93
	v_pk_add_f32 v[84:85], v[84:85], v[82:83] neg_lo:[0,1] neg_hi:[0,1]
	v_pk_add_f32 v[82:83], v[86:87], v[82:83] neg_lo:[0,1] neg_hi:[0,1]
	v_pk_add_f32 v[80:81], v[80:81], v[84:85] neg_lo:[0,1] neg_hi:[0,1]
	v_lshlrev_b64 v[76:77], 6, v[76:77]
	v_pk_add_f32 v[80:81], v[82:83], v[80:81]
	v_pk_add_f32 v[82:83], v[92:93], v[90:91]
	v_lshl_add_u64 v[76:77], s[6:7], 0, v[76:77]
	v_pk_add_f32 v[84:85], v[114:115], v[82:83]
	v_lshl_add_u64 v[76:77], v[76:77], 0, v[0:1]
	v_pk_add_f32 v[86:87], v[84:85], v[114:115] neg_lo:[0,1] neg_hi:[0,1]
	s_nop 0
	v_pk_add_f32 v[82:83], v[82:83], v[86:87] neg_lo:[0,1] neg_hi:[0,1]
	s_nop 0
	v_pk_add_f32 v[80:81], v[80:81], v[82:83]
	s_nop 0
	v_pk_add_f32 v[80:81], v[84:85], v[80:81]
	v_pk_mul_f32 v[84:85], v[94:95], v[102:103]
	v_cndmask_b32_e32 v80, v160, v80, vcc
	v_cmp_neq_f32_e32 vcc, s8, v126
	v_pk_add_f32 v[86:87], v[88:89], v[84:85]
	s_nop 0
	v_cndmask_b32_e32 v81, v160, v81, vcc
	v_cmp_ngt_f32_e32 vcc, -1.0, v126
	v_pk_add_f32 v[88:89], v[86:87], v[88:89] neg_lo:[0,1] neg_hi:[0,1]
	v_mov_b32_e32 v112, v86
	v_cndmask_b32_e32 v81, v161, v81, vcc
	v_cmp_ngt_f32_e32 vcc, -1.0, v97
	v_pk_add_f32 v[84:85], v[84:85], v[88:89] neg_lo:[0,1] neg_hi:[0,1]
	s_nop 0
	v_cndmask_b32_e32 v80, v161, v80, vcc
	v_cmp_neq_f32_e32 vcc, -1.0, v97
	v_pk_add_f32 v[92:93], v[98:99], v[84:85]
	v_mov_b32_e32 v89, v85
	v_cndmask_b32_e32 v80, v162, v80, vcc
	v_cmp_neq_f32_e32 vcc, -1.0, v126
	v_mov_b32_e32 v99, v93
	v_mov_b32_e32 v85, v87
	v_cndmask_b32_e32 v81, v162, v81, vcc
	v_cmp_lt_f32_e64 vcc, |v97|, s9
	v_cndmask_b32_e64 v81, v81, v126, s[0:1]
	v_pk_add_f32 v[94:95], v[86:87], v[92:93]
	v_cndmask_b32_e32 v80, v80, v97, vcc
	v_pk_add_f32 v[80:81], v[68:69], v[80:81] neg_lo:[0,1] neg_hi:[0,1]
	v_cvt_f32_i32_e32 v69, v130
	v_cvt_f32_i32_e32 v68, v128
	v_pk_add_f32 v[84:85], v[98:99], v[84:85]
	v_mov_b32_e32 v115, v95
	v_cmp_neq_f32_e32 vcc, s8, v127
	v_pk_mul_f32 v[82:83], v[68:69], s[12:13] op_sel_hi:[1,0]
	v_cmp_lt_f32_e64 s[0:1], |v129|, s9
	v_pk_fma_f32 v[90:91], v[68:69], s[12:13], v[82:83] op_sel_hi:[1,0,1] neg_lo:[0,0,1] neg_hi:[0,0,1]
	v_mov_b32_e32 v88, v82
	v_pk_fma_f32 v[68:69], v[68:69], s[14:15], v[90:91] op_sel_hi:[1,0,1]
	v_mov_b32_e32 v103, v83
	v_pk_add_f32 v[90:91], v[82:83], v[68:69]
	v_mov_b32_e32 v110, v68
	v_pk_add_f32 v[98:99], v[90:91], v[94:95]
	v_pk_add_f32 v[88:89], v[88:89], v[110:111]
	v_mov_b32_e32 v110, v94
	v_mov_b32_e32 v111, v99
	v_mov_b32_e32 v113, v91
	v_pk_add_f32 v[110:111], v[110:111], v[112:113] neg_lo:[0,1] neg_hi:[0,1]
	v_mov_b32_e32 v100, v98
; __device__ __forceinline__ float softplusf(float x) { return fmaxf(x, 0.f) + log1pf(__expf(-fabsf(x))); }
; __device__ void phaseA_tile(const Params& p, int l, int mt, int nt, char* smem) {
;     ...
;                     const float4 db = *(const float4*)(p.dt_bias + l * 32 + c);
;                     const f32x4 v = acc[i][j];
;                     *(float4*)(p.dtb + (size_t)row * 32 + c) =
;                         make_float4(softplusf(v[0] + db.x), softplusf(v[1] + db.y), softplusf(v[2] + db.z), softplusf(v[3] + db.w));
;     ...
;                     float* o = samp ? (p.out + O_LFS + ((size_t)l * TSM + (row - TP)) * 16 + c)
;                                     : (p.out + O_LFP + ((size_t)l * TP + row) * 16 + c);
;                     *(float4*)o = lf;
;                     *(float4*)(lf_s + rl * 16 + c) = lf;
	v_mov_b32_e32 v101, v91
	v_mov_b32_e32 v102, v90
	v_mov_b32_e32 v112, v90
	v_mov_b32_e32 v113, v99
	v_mov_b32_e32 v83, v111
	v_pk_add_f32 v[100:101], v[100:101], v[102:103] neg_lo:[0,1] neg_hi:[0,1]
	v_mov_b32_e32 v102, v94
	v_mov_b32_e32 v103, v69
	v_pk_add_f32 v[82:83], v[112:113], v[82:83] neg_lo:[0,1] neg_hi:[0,1]
	v_pk_add_f32 v[102:103], v[102:103], v[100:101] neg_lo:[0,1] neg_hi:[0,1]
	v_mov_b32_e32 v112, v82
	v_mov_b32_e32 v113, v101
	v_mov_b32_e32 v114, v98
	v_mov_b32_e32 v101, v87
	v_pk_add_f32 v[112:113], v[68:69], v[112:113] neg_lo:[0,1] neg_hi:[0,1]
	v_pk_add_f32 v[100:101], v[114:115], v[100:101] neg_lo:[0,1] neg_hi:[0,1]
	v_mov_b32_e32 v69, v91
	v_pk_add_f32 v[88:89], v[88:89], v[100:101] neg_lo:[0,1] neg_hi:[0,1]
	v_pk_add_f32 v[68:69], v[68:69], v[82:83] neg_lo:[0,1] neg_hi:[0,1]
	v_pk_add_f32 v[82:83], v[84:85], v[110:111] neg_lo:[0,1] neg_hi:[0,1]
	v_pk_add_f32 v[90:91], v[102:103], v[88:89]
	v_pk_add_f32 v[84:85], v[82:83], v[68:69]
	v_mov_b32_e32 v69, v103
	v_mov_b32_e32 v83, v89
	v_pk_add_f32 v[82:83], v[68:69], v[82:83]
	v_pk_add_f32 v[86:87], v[94:95], v[86:87] neg_lo:[0,1] neg_hi:[0,1]
	v_pk_add_f32 v[82:83], v[82:83], v[112:113] neg_lo:[0,1] neg_hi:[0,1]
	v_mov_b32_e32 v88, v84
	v_mov_b32_e32 v89, v91
	v_pk_add_f32 v[86:87], v[92:93], v[86:87] neg_lo:[0,1] neg_hi:[0,1]
	v_pk_add_f32 v[88:89], v[88:89], v[82:83] neg_lo:[0,1] neg_hi:[0,1]
	v_pk_add_f32 v[82:83], v[86:87], v[82:83] neg_lo:[0,1] neg_hi:[0,1]
	v_pk_add_f32 v[68:69], v[68:69], v[88:89] neg_lo:[0,1] neg_hi:[0,1]
	s_nop 0
	v_pk_add_f32 v[68:69], v[82:83], v[68:69]
	v_pk_add_f32 v[82:83], v[90:91], v[84:85]
	s_nop 0
	v_pk_add_f32 v[84:85], v[98:99], v[82:83]
	s_nop 0
	v_pk_add_f32 v[86:87], v[84:85], v[98:99] neg_lo:[0,1] neg_hi:[0,1]
	s_nop 0
	v_pk_add_f32 v[82:83], v[82:83], v[86:87] neg_lo:[0,1] neg_hi:[0,1]
	s_nop 0
	v_pk_add_f32 v[68:69], v[68:69], v[82:83]
	s_nop 0
	v_pk_add_f32 v[68:69], v[84:85], v[68:69]
	s_nop 0
	v_cndmask_b32_e32 v68, v160, v68, vcc
	v_cmp_neq_f32_e32 vcc, s8, v129
	s_nop 1
	v_cndmask_b32_e32 v69, v160, v69, vcc
	v_cmp_ngt_f32_e32 vcc, -1.0, v129
	s_nop 1
	v_cndmask_b32_e32 v69, v161, v69, vcc
	v_cmp_ngt_f32_e32 vcc, -1.0, v127
	s_nop 1
	v_cndmask_b32_e32 v68, v161, v68, vcc
	v_cmp_neq_f32_e32 vcc, -1.0, v127
	s_nop 1
	v_cndmask_b32_e32 v68, v162, v68, vcc
	v_cmp_neq_f32_e32 vcc, -1.0, v129
	s_nop 1
	v_cndmask_b32_e32 v69, v162, v69, vcc
	v_cmp_lt_f32_e64 vcc, |v127|, s9
	v_cndmask_b32_e64 v69, v69, v129, s[0:1]
	s_nop 0
	v_cndmask_b32_e32 v68, v68, v127, vcc
	v_pk_add_f32 v[82:83], v[78:79], v[68:69] neg_lo:[0,1] neg_hi:[0,1]
	global_store_dwordx4 v[76:77], v[80:83], off
	v_lshl_or_b32 v68, v71, 6, v0
	ds_write_b128 v68, v[80:83]
	global_load_dwordx4 v[78:81], v0, s[74:75]
	v_or_b32_e32 v82, 16, v71
	v_add_u32_e32 v68, s54, v82
	v_ashrrev_i32_e32 v69, 31, v68
	v_lshlrev_b64 v[76:77], 7, v[68:69]
	v_lshl_add_u64 v[76:77], s[10:11], 0, v[76:77]
	v_lshl_add_u64 v[76:77], v[76:77], 0, v[0:1]
	s_waitcnt vmcnt(0)
	v_add_f32_e32 v83, v46, v78
	v_max_f32_e32 v78, 0, v83
	v_mul_f32_e64 v83, |v83|, s2
	v_exp_f32_e32 v83, v83
	s_nop 0
	v_add_f32_e32 v86, 1.0, v83
	v_add_f32_e32 v84, -1.0, v86
	v_sub_f32_e32 v85, v84, v86
	v_add_f32_e32 v85, 1.0, v85
	v_sub_f32_e32 v84, v83, v84
	v_add_f32_e32 v87, v84, v85
	v_frexp_mant_f32_e32 v84, v86
	v_cmp_gt_f32_e32 vcc, s26, v84
	v_cvt_f64_f32_e32 v[84:85], v86
	v_frexp_exp_i32_f64_e32 v84, v[84:85]
	v_subbrev_co_u32_e32 v97, vcc, 0, v84, vcc
	v_sub_u32_e32 v85, 0, v97
	v_ldexp_f32 v84, v86, v85
	v_ldexp_f32 v86, v87, v85
	v_add_f32_e32 v85, v47, v79
	v_max_f32_e32 v79, 0, v85
	v_mul_f32_e64 v85, |v85|, s2
	v_exp_f32_e32 v130, v85
	s_nop 0
	v_add_f32_e32 v85, 1.0, v130
	v_add_f32_e32 v87, -1.0, v85
	v_sub_f32_e32 v88, v87, v85
	v_add_f32_e32 v88, 1.0, v88
	v_sub_f32_e32 v87, v130, v87
	v_add_f32_e32 v87, v87, v88
	v_frexp_mant_f32_e32 v88, v85
	v_cmp_gt_f32_e32 vcc, s26, v88
	v_cvt_f64_f32_e32 v[88:89], v85
	v_frexp_exp_i32_f64_e32 v88, v[88:89]
	v_subbrev_co_u32_e32 v122, vcc, 0, v88, vcc
	v_sub_u32_e32 v88, 0, v122
	v_ldexp_f32 v85, v85, v88
	v_ldexp_f32 v87, v87, v88
	v_pk_add_f32 v[88:89], v[84:85], 1.0 op_sel_hi:[1,0]
	v_pk_add_f32 v[98:99], v[84:85], -1.0 op_sel_hi:[1,0]
	v_pk_add_f32 v[90:91], v[88:89], -1.0 op_sel_hi:[1,0]
	v_pk_add_f32 v[100:101], v[98:99], 1.0 op_sel_hi:[1,0]
	v_pk_add_f32 v[90:91], v[84:85], v[90:91] neg_lo:[0,1] neg_hi:[0,1]
	v_pk_add_f32 v[84:85], v[84:85], v[100:101] neg_lo:[0,1] neg_hi:[0,1]
	v_pk_add_f32 v[90:91], v[86:87], v[90:91]
	v_pk_add_f32 v[84:85], v[86:87], v[84:85]
	v_pk_add_f32 v[92:93], v[88:89], v[90:91]
	v_pk_add_f32 v[86:87], v[98:99], v[84:85]
	v_rcp_f32_e32 v94, v92
	v_rcp_f32_e32 v95, v93
	v_pk_add_f32 v[88:89], v[92:93], v[88:89] neg_lo:[0,1] neg_hi:[0,1]
	v_pk_add_f32 v[98:99], v[86:87], v[98:99] neg_lo:[0,1] neg_hi:[0,1]
	v_pk_add_f32 v[88:89], v[90:91], v[88:89] neg_lo:[0,1] neg_hi:[0,1]
	v_pk_mul_f32 v[90:91], v[86:87], v[94:95]
	v_pk_add_f32 v[84:85], v[84:85], v[98:99] neg_lo:[0,1] neg_hi:[0,1]
	v_pk_mul_f32 v[98:99], v[92:93], v[90:91]
	v_cmp_lt_f32_e64 s[0:1], |v130|, s9
	v_pk_fma_f32 v[100:101], v[90:91], v[92:93], v[98:99] neg_lo:[0,0,1] neg_hi:[0,0,1]
	s_nop 0
	v_pk_fma_f32 v[100:101], v[90:91], v[88:89], v[100:101]
	s_nop 0
	v_pk_add_f32 v[102:103], v[98:99], v[100:101]
	s_nop 0
	v_pk_add_f32 v[110:111], v[86:87], v[102:103] neg_lo:[0,1] neg_hi:[0,1]
	v_pk_add_f32 v[98:99], v[102:103], v[98:99] neg_lo:[0,1] neg_hi:[0,1]
	v_pk_add_f32 v[86:87], v[86:87], v[110:111] neg_lo:[0,1] neg_hi:[0,1]
	s_nop 0
	v_pk_add_f32 v[86:87], v[86:87], v[102:103] neg_lo:[0,1] neg_hi:[0,1]
	s_nop 0
	v_pk_add_f32 v[84:85], v[84:85], v[86:87]
; __device__ __forceinline__ float softplusf(float x) { return fmaxf(x, 0.f) + log1pf(__expf(-fabsf(x))); }
; __device__ void phaseA_tile(const Params& p, int l, int mt, int nt, char* smem) {
;     ...
;                     const float4 db = *(const float4*)(p.dt_bias + l * 32 + c);
;                     const f32x4 v = acc[i][j];
;                     *(float4*)(p.dtb + (size_t)row * 32 + c) =
;                         make_float4(softplusf(v[0] + db.x), softplusf(v[1] + db.y), softplusf(v[2] + db.z), softplusf(v[3] + db.w));
	v_pk_add_f32 v[86:87], v[98:99], v[100:101] neg_lo:[0,1] neg_hi:[0,1]
	s_nop 0
	v_pk_add_f32 v[84:85], v[86:87], v[84:85]
	s_nop 0
	v_pk_add_f32 v[86:87], v[110:111], v[84:85]
	s_nop 0
	v_pk_mul_f32 v[98:99], v[94:95], v[86:87]
	s_nop 0
	v_pk_mul_f32 v[100:101], v[92:93], v[98:99]
	s_nop 0
	v_pk_fma_f32 v[92:93], v[98:99], v[92:93], v[100:101] neg_lo:[0,0,1] neg_hi:[0,0,1]
	s_nop 0
	v_pk_fma_f32 v[88:89], v[98:99], v[88:89], v[92:93]
	v_pk_add_f32 v[92:93], v[110:111], v[86:87] neg_lo:[0,1] neg_hi:[0,1]
	s_nop 0
	v_pk_add_f32 v[84:85], v[84:85], v[92:93]
	v_pk_add_f32 v[92:93], v[100:101], v[88:89]
	s_nop 0
	v_pk_add_f32 v[102:103], v[86:87], v[92:93] neg_lo:[0,1] neg_hi:[0,1]
	v_pk_add_f32 v[100:101], v[92:93], v[100:101] neg_lo:[0,1] neg_hi:[0,1]
	v_pk_add_f32 v[86:87], v[86:87], v[102:103] neg_lo:[0,1] neg_hi:[0,1]
	s_nop 0
	v_pk_add_f32 v[86:87], v[86:87], v[92:93] neg_lo:[0,1] neg_hi:[0,1]
	s_nop 0
	v_pk_add_f32 v[84:85], v[84:85], v[86:87]
	v_pk_add_f32 v[86:87], v[100:101], v[88:89] neg_lo:[0,1] neg_hi:[0,1]
	s_nop 0
	v_pk_add_f32 v[84:85], v[86:87], v[84:85]
	v_pk_add_f32 v[86:87], v[90:91], v[98:99]
	v_pk_add_f32 v[84:85], v[102:103], v[84:85]
	v_pk_add_f32 v[88:89], v[86:87], v[90:91] neg_lo:[0,1] neg_hi:[0,1]
	v_pk_mul_f32 v[84:85], v[94:95], v[84:85]
	v_pk_add_f32 v[88:89], v[98:99], v[88:89] neg_lo:[0,1] neg_hi:[0,1]
	s_nop 0
	v_pk_add_f32 v[84:85], v[88:89], v[84:85]
	s_nop 0
	v_pk_add_f32 v[88:89], v[86:87], v[84:85]
	s_nop 0
	v_pk_add_f32 v[86:87], v[88:89], v[86:87] neg_lo:[0,1] neg_hi:[0,1]
	v_pk_mul_f32 v[90:91], v[88:89], v[88:89]
	v_pk_add_f32 v[84:85], v[84:85], v[86:87] neg_lo:[0,1] neg_hi:[0,1]
	v_pk_fma_f32 v[92:93], v[90:91], s[28:29], v[66:67] op_sel_hi:[1,0,0]
	v_ldexp_f32 v95, v85, 1
	v_add_f32_e32 v85, v48, v80
	v_max_f32_e32 v80, 0, v85
	v_mul_f32_e64 v85, |v85|, s2
	v_exp_f32_e32 v131, v85
	v_ldexp_f32 v86, v88, 1
	v_pk_fma_f32 v[92:93], v[90:91], v[92:93], s[30:31] op_sel_hi:[1,1,0]
	v_ldexp_f32 v87, v89, 1
	v_add_f32_e32 v85, 1.0, v131
	v_pk_mul_f32 v[88:89], v[88:89], v[90:91]
	v_add_f32_e32 v90, -1.0, v85
	v_sub_f32_e32 v91, v90, v85
	v_add_f32_e32 v91, 1.0, v91
	v_sub_f32_e32 v90, v131, v90
	v_add_f32_e32 v94, v90, v91
	v_frexp_mant_f32_e32 v90, v85
	v_cmp_gt_f32_e32 vcc, s26, v90
	v_cvt_f64_f32_e32 v[90:91], v85
	v_frexp_exp_i32_f64_e32 v90, v[90:91]
	v_subbrev_co_u32_e32 v132, vcc, 0, v90, vcc
	v_sub_u32_e32 v91, 0, v132
	v_ldexp_f32 v90, v85, v91
	v_add_f32_e32 v85, v49, v81
	v_max_f32_e32 v81, 0, v85
	v_mul_f32_e64 v85, |v85|, s2
	v_exp_f32_e32 v133, v85
	v_ldexp_f32 v98, v94, v91
	v_pk_mul_f32 v[88:89], v[88:89], v[92:93]
	v_ldexp_f32 v84, v84, 1
	v_add_f32_e32 v85, 1.0, v133
	v_add_f32_e32 v91, -1.0, v85
	v_sub_f32_e32 v94, v91, v85
	v_add_f32_e32 v94, 1.0, v94
	v_sub_f32_e32 v91, v133, v91
	v_add_f32_e32 v94, v91, v94
	v_frexp_mant_f32_e32 v91, v85
	v_cvt_f64_f32_e32 v[100:101], v85
	v_cmp_gt_f32_e32 vcc, s26, v91
	v_frexp_exp_i32_f64_e32 v91, v[100:101]
	v_pk_add_f32 v[92:93], v[86:87], v[88:89]
	v_subbrev_co_u32_e32 v134, vcc, 0, v91, vcc
	v_sub_u32_e32 v99, 0, v134
	v_ldexp_f32 v91, v85, v99
	v_pk_add_f32 v[100:101], v[90:91], 1.0 op_sel_hi:[1,0]
	v_ldexp_f32 v99, v94, v99
	v_pk_add_f32 v[102:103], v[100:101], -1.0 op_sel_hi:[1,0]
	v_pk_add_f32 v[114:115], v[90:91], -1.0 op_sel_hi:[1,0]
	v_pk_add_f32 v[102:103], v[90:91], v[102:103] neg_lo:[0,1] neg_hi:[0,1]
	v_pk_add_f32 v[116:117], v[114:115], 1.0 op_sel_hi:[1,0]
	v_pk_add_f32 v[102:103], v[98:99], v[102:103]
	v_pk_add_f32 v[90:91], v[90:91], v[116:117] neg_lo:[0,1] neg_hi:[0,1]
	v_pk_add_f32 v[110:111], v[100:101], v[102:103]
	v_pk_add_f32 v[90:91], v[98:99], v[90:91]
	v_rcp_f32_e32 v112, v110
	v_rcp_f32_e32 v113, v111
	v_pk_add_f32 v[98:99], v[114:115], v[90:91]
	v_pk_add_f32 v[100:101], v[110:111], v[100:101] neg_lo:[0,1] neg_hi:[0,1]
	v_pk_add_f32 v[114:115], v[98:99], v[114:115] neg_lo:[0,1] neg_hi:[0,1]
	v_pk_add_f32 v[100:101], v[102:103], v[100:101] neg_lo:[0,1] neg_hi:[0,1]
	v_pk_mul_f32 v[102:103], v[98:99], v[112:113]
	v_pk_add_f32 v[90:91], v[90:91], v[114:115] neg_lo:[0,1] neg_hi:[0,1]
	v_pk_mul_f32 v[114:115], v[110:111], v[102:103]
	v_pk_add_f32 v[86:87], v[92:93], v[86:87] neg_lo:[0,1] neg_hi:[0,1]
	v_pk_fma_f32 v[116:117], v[102:103], v[110:111], v[114:115] neg_lo:[0,0,1] neg_hi:[0,0,1]
	v_pk_add_f32 v[86:87], v[88:89], v[86:87] neg_lo:[0,1] neg_hi:[0,1]
	v_pk_fma_f32 v[116:117], v[102:103], v[100:101], v[116:117]
	v_mov_b32_e32 v89, v87
	v_pk_add_f32 v[118:119], v[114:115], v[116:117]
	v_mov_b32_e32 v85, v95
	v_pk_add_f32 v[120:121], v[98:99], v[118:119] neg_lo:[0,1] neg_hi:[0,1]
	v_pk_add_f32 v[114:115], v[118:119], v[114:115] neg_lo:[0,1] neg_hi:[0,1]
	v_pk_add_f32 v[98:99], v[98:99], v[120:121] neg_lo:[0,1] neg_hi:[0,1]
	v_mov_b32_e32 v126, v92
	v_pk_add_f32 v[98:99], v[98:99], v[118:119] neg_lo:[0,1] neg_hi:[0,1]
	v_cmp_neq_f32_e32 vcc, s8, v83
	v_pk_add_f32 v[90:91], v[90:91], v[98:99]
	v_pk_add_f32 v[98:99], v[114:115], v[116:117] neg_lo:[0,1] neg_hi:[0,1]
	s_nop 0
	v_pk_add_f32 v[90:91], v[98:99], v[90:91]
	s_nop 0
	v_pk_add_f32 v[98:99], v[120:121], v[90:91]
	s_nop 0
	v_pk_mul_f32 v[114:115], v[112:113], v[98:99]
	s_nop 0
	v_pk_mul_f32 v[116:117], v[110:111], v[114:115]
	s_nop 0
	v_pk_fma_f32 v[110:111], v[114:115], v[110:111], v[116:117] neg_lo:[0,0,1] neg_hi:[0,0,1]
	s_nop 0
	v_pk_fma_f32 v[100:101], v[114:115], v[100:101], v[110:111]
	v_pk_add_f32 v[110:111], v[120:121], v[98:99] neg_lo:[0,1] neg_hi:[0,1]
	s_nop 0
	v_pk_add_f32 v[90:91], v[90:91], v[110:111]
	v_pk_add_f32 v[110:111], v[116:117], v[100:101]
	s_nop 0
	v_pk_add_f32 v[118:119], v[98:99], v[110:111] neg_lo:[0,1] neg_hi:[0,1]
; __device__ __forceinline__ float softplusf(float x) { return fmaxf(x, 0.f) + log1pf(__expf(-fabsf(x))); }
; __device__ void phaseA_tile(const Params& p, int l, int mt, int nt, char* smem) {
;     ...
;                     const f32x4 v = acc[i][j];
;                     *(float4*)(p.dtb + (size_t)row * 32 + c) =
;                         make_float4(softplusf(v[0] + db.x), softplusf(v[1] + db.y), softplusf(v[2] + db.z), softplusf(v[3] + db.w));
	v_pk_add_f32 v[116:117], v[110:111], v[116:117] neg_lo:[0,1] neg_hi:[0,1]
	v_pk_add_f32 v[98:99], v[98:99], v[118:119] neg_lo:[0,1] neg_hi:[0,1]
	s_nop 0
	v_pk_add_f32 v[98:99], v[98:99], v[110:111] neg_lo:[0,1] neg_hi:[0,1]
	s_nop 0
	v_pk_add_f32 v[90:91], v[90:91], v[98:99]
	v_pk_add_f32 v[98:99], v[116:117], v[100:101] neg_lo:[0,1] neg_hi:[0,1]
	s_nop 0
	v_pk_add_f32 v[90:91], v[98:99], v[90:91]
	v_pk_add_f32 v[98:99], v[102:103], v[114:115]
	v_pk_add_f32 v[90:91], v[118:119], v[90:91]
	v_pk_add_f32 v[100:101], v[98:99], v[102:103] neg_lo:[0,1] neg_hi:[0,1]
	v_pk_mul_f32 v[90:91], v[112:113], v[90:91]
	v_pk_add_f32 v[100:101], v[114:115], v[100:101] neg_lo:[0,1] neg_hi:[0,1]
	s_nop 0
	v_pk_add_f32 v[90:91], v[100:101], v[90:91]
	s_nop 0
	v_pk_add_f32 v[100:101], v[98:99], v[90:91]
	s_nop 0
	v_pk_mul_f32 v[102:103], v[100:101], v[100:101]
	v_pk_add_f32 v[98:99], v[100:101], v[98:99] neg_lo:[0,1] neg_hi:[0,1]
	v_pk_fma_f32 v[110:111], v[102:103], s[28:29], v[66:67] op_sel_hi:[1,0,0]
	v_pk_add_f32 v[90:91], v[90:91], v[98:99] neg_lo:[0,1] neg_hi:[0,1]
	v_ldexp_f32 v98, v100, 1
	v_pk_fma_f32 v[110:111], v[102:103], v[110:111], s[30:31] op_sel_hi:[1,1,0]
	v_ldexp_f32 v99, v101, 1
	v_pk_mul_f32 v[100:101], v[100:101], v[102:103]
	v_cvt_f32_i32_e32 v103, v122
	v_cvt_f32_i32_e32 v102, v97
	v_ldexp_f32 v113, v91, 1
	v_ldexp_f32 v90, v90, 1
	v_mov_b32_e32 v91, v113
	v_pk_mul_f32 v[114:115], v[102:103], s[12:13] op_sel_hi:[1,0]
	s_nop 0
	v_pk_fma_f32 v[116:117], v[102:103], s[12:13], v[114:115] op_sel_hi:[1,0,1] neg_lo:[0,0,1] neg_hi:[0,0,1]
	v_mov_b32_e32 v88, v114
	v_pk_fma_f32 v[102:103], v[102:103], s[14:15], v[116:117] op_sel_hi:[1,0,1]
	v_mov_b32_e32 v123, v115
	v_mov_b32_e32 v94, v102
	v_pk_add_f32 v[88:89], v[88:89], v[94:95]
	v_pk_add_f32 v[94:95], v[84:85], v[86:87]
	v_mov_b32_e32 v87, v93
	v_mov_b32_e32 v85, v95
	v_pk_add_f32 v[116:117], v[114:115], v[102:103]
	v_pk_add_f32 v[84:85], v[84:85], v[86:87]
	v_pk_add_f32 v[86:87], v[92:93], v[94:95]
	v_mov_b32_e32 v127, v117
	v_pk_add_f32 v[118:119], v[116:117], v[86:87]
	v_mov_b32_e32 v124, v86
	v_mov_b32_e32 v125, v119
	v_pk_add_f32 v[124:125], v[124:125], v[126:127] neg_lo:[0,1] neg_hi:[0,1]
	v_mov_b32_e32 v120, v118
	v_mov_b32_e32 v121, v117
	v_mov_b32_e32 v122, v116
	v_mov_b32_e32 v126, v116
	v_mov_b32_e32 v127, v119
	v_mov_b32_e32 v115, v125
	v_pk_add_f32 v[120:121], v[120:121], v[122:123] neg_lo:[0,1] neg_hi:[0,1]
	v_mov_b32_e32 v122, v86
	v_mov_b32_e32 v123, v103
	v_pk_add_f32 v[114:115], v[126:127], v[114:115] neg_lo:[0,1] neg_hi:[0,1]
	v_pk_add_f32 v[122:123], v[122:123], v[120:121] neg_lo:[0,1] neg_hi:[0,1]
	v_mov_b32_e32 v126, v114
	v_mov_b32_e32 v127, v121
	v_mov_b32_e32 v128, v118
	v_mov_b32_e32 v129, v87
	v_mov_b32_e32 v121, v93
	v_pk_add_f32 v[126:127], v[102:103], v[126:127] neg_lo:[0,1] neg_hi:[0,1]
	v_pk_add_f32 v[120:121], v[128:129], v[120:121] neg_lo:[0,1] neg_hi:[0,1]
	v_mov_b32_e32 v103, v117
	v_pk_add_f32 v[86:87], v[86:87], v[92:93] neg_lo:[0,1] neg_hi:[0,1]
	v_pk_add_f32 v[88:89], v[88:89], v[120:121] neg_lo:[0,1] neg_hi:[0,1]
	v_pk_add_f32 v[92:93], v[102:103], v[114:115] neg_lo:[0,1] neg_hi:[0,1]
	v_pk_add_f32 v[84:85], v[84:85], v[124:125] neg_lo:[0,1] neg_hi:[0,1]
	v_pk_add_f32 v[86:87], v[94:95], v[86:87] neg_lo:[0,1] neg_hi:[0,1]
	v_pk_add_f32 v[94:95], v[84:85], v[92:93]
	v_mov_b32_e32 v93, v123
	v_mov_b32_e32 v85, v89
	v_pk_add_f32 v[102:103], v[122:123], v[88:89]
	v_pk_add_f32 v[84:85], v[92:93], v[84:85]
	v_mov_b32_e32 v88, v94
	v_pk_add_f32 v[84:85], v[84:85], v[126:127] neg_lo:[0,1] neg_hi:[0,1]
	v_mov_b32_e32 v89, v103
	v_pk_add_f32 v[88:89], v[88:89], v[84:85] neg_lo:[0,1] neg_hi:[0,1]
	v_pk_add_f32 v[84:85], v[86:87], v[84:85] neg_lo:[0,1] neg_hi:[0,1]
	v_pk_add_f32 v[88:89], v[92:93], v[88:89] neg_lo:[0,1] neg_hi:[0,1]
	v_pk_add_f32 v[86:87], v[102:103], v[94:95]
	v_pk_add_f32 v[84:85], v[84:85], v[88:89]
	v_pk_add_f32 v[88:89], v[118:119], v[86:87]
	s_nop 0
	v_pk_add_f32 v[92:93], v[88:89], v[118:119] neg_lo:[0,1] neg_hi:[0,1]
	s_nop 0
	v_pk_add_f32 v[86:87], v[86:87], v[92:93] neg_lo:[0,1] neg_hi:[0,1]
	s_nop 0
	v_pk_add_f32 v[84:85], v[84:85], v[86:87]
	s_nop 0
	v_pk_add_f32 v[84:85], v[88:89], v[84:85]
	v_pk_mul_f32 v[88:89], v[100:101], v[110:111]
	v_cndmask_b32_e32 v84, v160, v84, vcc
	v_cmp_neq_f32_e32 vcc, s8, v130
	v_pk_add_f32 v[92:93], v[98:99], v[88:89]
	s_nop 0
	v_cndmask_b32_e32 v85, v160, v85, vcc
	v_cmp_ngt_f32_e32 vcc, -1.0, v130
	v_pk_add_f32 v[98:99], v[92:93], v[98:99] neg_lo:[0,1] neg_hi:[0,1]
	v_mov_b32_e32 v116, v92
	v_cndmask_b32_e32 v85, v161, v85, vcc
	v_cmp_ngt_f32_e32 vcc, -1.0, v83
	v_pk_add_f32 v[88:89], v[88:89], v[98:99] neg_lo:[0,1] neg_hi:[0,1]
	s_nop 0
	v_cndmask_b32_e32 v84, v161, v84, vcc
	v_cmp_neq_f32_e32 vcc, -1.0, v83
	v_pk_add_f32 v[100:101], v[90:91], v[88:89]
	v_mov_b32_e32 v99, v89
	v_cndmask_b32_e32 v84, v162, v84, vcc
	v_cmp_neq_f32_e32 vcc, -1.0, v130
	v_mov_b32_e32 v91, v101
	v_mov_b32_e32 v89, v93
	v_cndmask_b32_e32 v85, v162, v85, vcc
	v_cmp_lt_f32_e64 vcc, |v83|, s9
	v_cndmask_b32_e64 v85, v85, v130, s[0:1]
	v_pk_add_f32 v[88:89], v[90:91], v[88:89]
	v_cndmask_b32_e32 v84, v84, v83, vcc
	v_pk_add_f32 v[78:79], v[78:79], v[84:85]
	v_cvt_f32_i32_e32 v85, v134
	v_cvt_f32_i32_e32 v84, v132
	v_pk_add_f32 v[90:91], v[92:93], v[100:101]
	v_cmp_neq_f32_e32 vcc, s8, v131
	v_mov_b32_e32 v114, v90
	v_pk_mul_f32 v[86:87], v[84:85], s[12:13] op_sel_hi:[1,0]
	v_mov_b32_e32 v119, v91
	v_pk_fma_f32 v[94:95], v[84:85], s[12:13], v[86:87] op_sel_hi:[1,0,1] neg_lo:[0,0,1] neg_hi:[0,0,1]
	v_mov_b32_e32 v98, v86
	v_pk_fma_f32 v[84:85], v[84:85], s[14:15], v[94:95] op_sel_hi:[1,0,1]
	v_cmp_lt_f32_e64 s[0:1], |v133|, s9
; __device__ __forceinline__ float softplusf(float x) { return fmaxf(x, 0.f) + log1pf(__expf(-fabsf(x))); }
; __device__ void phaseA_tile(const Params& p, int l, int mt, int nt, char* smem) {
;     ...
;                     const float4 db = *(const float4*)(p.dt_bias + l * 32 + c);
;                     const f32x4 v = acc[i][j];
;                     *(float4*)(p.dtb + (size_t)row * 32 + c) =
;                         make_float4(softplusf(v[0] + db.x), softplusf(v[1] + db.y), softplusf(v[2] + db.z), softplusf(v[3] + db.w));
	v_pk_add_f32 v[94:95], v[86:87], v[84:85]
	v_mov_b32_e32 v112, v84
	v_pk_add_f32 v[102:103], v[94:95], v[90:91]
	v_mov_b32_e32 v117, v95
	v_mov_b32_e32 v115, v103
	v_pk_add_f32 v[114:115], v[114:115], v[116:117] neg_lo:[0,1] neg_hi:[0,1]
	v_pk_add_f32 v[98:99], v[98:99], v[112:113]
	v_mov_b32_e32 v110, v102
	v_mov_b32_e32 v111, v95
	v_mov_b32_e32 v112, v94
	v_mov_b32_e32 v113, v87
	v_mov_b32_e32 v116, v94
	v_mov_b32_e32 v117, v103
	v_mov_b32_e32 v87, v115
	v_pk_add_f32 v[110:111], v[110:111], v[112:113] neg_lo:[0,1] neg_hi:[0,1]
	v_mov_b32_e32 v112, v90
	v_mov_b32_e32 v113, v85
	v_pk_add_f32 v[86:87], v[116:117], v[86:87] neg_lo:[0,1] neg_hi:[0,1]
	v_pk_add_f32 v[112:113], v[112:113], v[110:111] neg_lo:[0,1] neg_hi:[0,1]
	v_mov_b32_e32 v116, v86
	v_mov_b32_e32 v117, v111
	v_mov_b32_e32 v118, v102
	v_mov_b32_e32 v111, v93
	v_pk_add_f32 v[116:117], v[84:85], v[116:117] neg_lo:[0,1] neg_hi:[0,1]
	v_pk_add_f32 v[110:111], v[118:119], v[110:111] neg_lo:[0,1] neg_hi:[0,1]
	v_mov_b32_e32 v85, v95
	v_pk_add_f32 v[90:91], v[90:91], v[92:93] neg_lo:[0,1] neg_hi:[0,1]
	v_pk_add_f32 v[92:93], v[98:99], v[110:111] neg_lo:[0,1] neg_hi:[0,1]
	v_pk_add_f32 v[84:85], v[84:85], v[86:87] neg_lo:[0,1] neg_hi:[0,1]
	v_pk_add_f32 v[86:87], v[88:89], v[114:115] neg_lo:[0,1] neg_hi:[0,1]
	v_pk_add_f32 v[94:95], v[112:113], v[92:93]
	v_pk_add_f32 v[88:89], v[86:87], v[84:85]
	v_mov_b32_e32 v85, v113
	v_mov_b32_e32 v87, v93
	v_pk_add_f32 v[86:87], v[84:85], v[86:87]
	v_mov_b32_e32 v92, v88
	v_pk_add_f32 v[86:87], v[86:87], v[116:117] neg_lo:[0,1] neg_hi:[0,1]
	v_mov_b32_e32 v93, v95
	v_pk_add_f32 v[90:91], v[100:101], v[90:91] neg_lo:[0,1] neg_hi:[0,1]
	v_pk_add_f32 v[92:93], v[92:93], v[86:87] neg_lo:[0,1] neg_hi:[0,1]
	v_pk_add_f32 v[86:87], v[90:91], v[86:87] neg_lo:[0,1] neg_hi:[0,1]
	v_pk_add_f32 v[84:85], v[84:85], v[92:93] neg_lo:[0,1] neg_hi:[0,1]
	s_nop 0
	v_pk_add_f32 v[84:85], v[86:87], v[84:85]
	v_pk_add_f32 v[86:87], v[94:95], v[88:89]
	s_nop 0
	v_pk_add_f32 v[88:89], v[102:103], v[86:87]
	s_nop 0
	v_pk_add_f32 v[90:91], v[88:89], v[102:103] neg_lo:[0,1] neg_hi:[0,1]
	s_nop 0
	v_pk_add_f32 v[86:87], v[86:87], v[90:91] neg_lo:[0,1] neg_hi:[0,1]
	s_nop 0
	v_pk_add_f32 v[84:85], v[84:85], v[86:87]
	s_nop 0
	v_pk_add_f32 v[84:85], v[88:89], v[84:85]
	s_nop 0
	v_cndmask_b32_e32 v83, v160, v84, vcc
	v_cmp_neq_f32_e32 vcc, s8, v133
	s_nop 1
	v_cndmask_b32_e32 v84, v160, v85, vcc
	v_cmp_ngt_f32_e32 vcc, -1.0, v133
	s_nop 1
	v_cndmask_b32_e32 v84, v161, v84, vcc
	v_cmp_ngt_f32_e32 vcc, -1.0, v131
	s_nop 1
	v_cndmask_b32_e32 v83, v161, v83, vcc
	v_cmp_neq_f32_e32 vcc, -1.0, v131
	s_nop 1
	v_cndmask_b32_e32 v83, v162, v83, vcc
	v_cmp_neq_f32_e32 vcc, -1.0, v133
	s_nop 1
	v_cndmask_b32_e32 v84, v162, v84, vcc
	v_cmp_lt_f32_e64 vcc, |v131|, s9
	v_cndmask_b32_e64 v85, v84, v133, s[0:1]
	s_nop 0
	v_cndmask_b32_e32 v84, v83, v131, vcc
	v_pk_add_f32 v[80:81], v[80:81], v[84:85]
	global_store_dwordx4 v[76:77], v[78:81], off
	global_load_dwordx4 v[78:81], v0, s[74:75] offset:64
	s_waitcnt vmcnt(0)
	v_add_f32_e32 v83, v42, v78
	v_max_f32_e32 v78, 0, v83
	v_mul_f32_e64 v83, |v83|, s2
	v_exp_f32_e32 v83, v83
	s_nop 0
	v_add_f32_e32 v86, 1.0, v83
	v_add_f32_e32 v84, -1.0, v86
	v_sub_f32_e32 v85, v84, v86
	v_add_f32_e32 v85, 1.0, v85
	v_sub_f32_e32 v84, v83, v84
	v_add_f32_e32 v87, v84, v85
	v_frexp_mant_f32_e32 v84, v86
	v_cmp_gt_f32_e32 vcc, s26, v84
	v_cvt_f64_f32_e32 v[84:85], v86
	v_frexp_exp_i32_f64_e32 v84, v[84:85]
	v_subbrev_co_u32_e32 v97, vcc, 0, v84, vcc
	v_sub_u32_e32 v85, 0, v97
	v_ldexp_f32 v84, v86, v85
	v_ldexp_f32 v86, v87, v85
	v_add_f32_e32 v85, v43, v79
	v_max_f32_e32 v79, 0, v85
	v_mul_f32_e64 v85, |v85|, s2
	v_exp_f32_e32 v130, v85
	s_nop 0
	v_add_f32_e32 v85, 1.0, v130
	v_add_f32_e32 v87, -1.0, v85
	v_sub_f32_e32 v88, v87, v85
	v_add_f32_e32 v88, 1.0, v88
	v_sub_f32_e32 v87, v130, v87
	v_add_f32_e32 v87, v87, v88
	v_frexp_mant_f32_e32 v88, v85
	v_cmp_gt_f32_e32 vcc, s26, v88
	v_cvt_f64_f32_e32 v[88:89], v85
	v_frexp_exp_i32_f64_e32 v88, v[88:89]
	v_subbrev_co_u32_e32 v122, vcc, 0, v88, vcc
	v_sub_u32_e32 v88, 0, v122
	v_ldexp_f32 v85, v85, v88
	v_ldexp_f32 v87, v87, v88
	v_pk_add_f32 v[88:89], v[84:85], 1.0 op_sel_hi:[1,0]
	v_pk_add_f32 v[98:99], v[84:85], -1.0 op_sel_hi:[1,0]
	v_pk_add_f32 v[90:91], v[88:89], -1.0 op_sel_hi:[1,0]
	v_pk_add_f32 v[100:101], v[98:99], 1.0 op_sel_hi:[1,0]
	v_pk_add_f32 v[90:91], v[84:85], v[90:91] neg_lo:[0,1] neg_hi:[0,1]
	v_pk_add_f32 v[84:85], v[84:85], v[100:101] neg_lo:[0,1] neg_hi:[0,1]
	v_pk_add_f32 v[90:91], v[86:87], v[90:91]
	v_pk_add_f32 v[84:85], v[86:87], v[84:85]
	v_pk_add_f32 v[92:93], v[88:89], v[90:91]
	v_pk_add_f32 v[86:87], v[98:99], v[84:85]
	v_rcp_f32_e32 v94, v92
	v_rcp_f32_e32 v95, v93
	v_pk_add_f32 v[88:89], v[92:93], v[88:89] neg_lo:[0,1] neg_hi:[0,1]
	v_pk_add_f32 v[98:99], v[86:87], v[98:99] neg_lo:[0,1] neg_hi:[0,1]
	v_pk_add_f32 v[88:89], v[90:91], v[88:89] neg_lo:[0,1] neg_hi:[0,1]
	v_pk_mul_f32 v[90:91], v[86:87], v[94:95]
	v_pk_add_f32 v[84:85], v[84:85], v[98:99] neg_lo:[0,1] neg_hi:[0,1]
	v_pk_mul_f32 v[98:99], v[92:93], v[90:91]
	v_cmp_lt_f32_e64 s[0:1], |v130|, s9
	v_pk_fma_f32 v[100:101], v[90:91], v[92:93], v[98:99] neg_lo:[0,0,1] neg_hi:[0,0,1]
	s_nop 0
	v_pk_fma_f32 v[100:101], v[90:91], v[88:89], v[100:101]
	s_nop 0
	v_pk_add_f32 v[102:103], v[98:99], v[100:101]
	s_nop 0
	v_pk_add_f32 v[110:111], v[86:87], v[102:103] neg_lo:[0,1] neg_hi:[0,1]
	v_pk_add_f32 v[98:99], v[102:103], v[98:99] neg_lo:[0,1] neg_hi:[0,1]
	v_pk_add_f32 v[86:87], v[86:87], v[110:111] neg_lo:[0,1] neg_hi:[0,1]
	s_nop 0
	v_pk_add_f32 v[86:87], v[86:87], v[102:103] neg_lo:[0,1] neg_hi:[0,1]
	s_nop 0
; __device__ __forceinline__ float softplusf(float x) { return fmaxf(x, 0.f) + log1pf(__expf(-fabsf(x))); }
; __device__ void phaseA_tile(const Params& p, int l, int mt, int nt, char* smem) {
;     ...
;                     const f32x4 v = acc[i][j];
;                     *(float4*)(p.dtb + (size_t)row * 32 + c) =
;                         make_float4(softplusf(v[0] + db.x), softplusf(v[1] + db.y), softplusf(v[2] + db.z), softplusf(v[3] + db.w));
	v_pk_add_f32 v[84:85], v[84:85], v[86:87]
	v_pk_add_f32 v[86:87], v[98:99], v[100:101] neg_lo:[0,1] neg_hi:[0,1]
	s_nop 0
	v_pk_add_f32 v[84:85], v[86:87], v[84:85]
	s_nop 0
	v_pk_add_f32 v[86:87], v[110:111], v[84:85]
	s_nop 0
	v_pk_mul_f32 v[98:99], v[94:95], v[86:87]
	s_nop 0
	v_pk_mul_f32 v[100:101], v[92:93], v[98:99]
	s_nop 0
	v_pk_fma_f32 v[92:93], v[98:99], v[92:93], v[100:101] neg_lo:[0,0,1] neg_hi:[0,0,1]
	s_nop 0
	v_pk_fma_f32 v[88:89], v[98:99], v[88:89], v[92:93]
	v_pk_add_f32 v[92:93], v[110:111], v[86:87] neg_lo:[0,1] neg_hi:[0,1]
	s_nop 0
	v_pk_add_f32 v[84:85], v[84:85], v[92:93]
	v_pk_add_f32 v[92:93], v[100:101], v[88:89]
	s_nop 0
	v_pk_add_f32 v[102:103], v[86:87], v[92:93] neg_lo:[0,1] neg_hi:[0,1]
	v_pk_add_f32 v[100:101], v[92:93], v[100:101] neg_lo:[0,1] neg_hi:[0,1]
	v_pk_add_f32 v[86:87], v[86:87], v[102:103] neg_lo:[0,1] neg_hi:[0,1]
	s_nop 0
	v_pk_add_f32 v[86:87], v[86:87], v[92:93] neg_lo:[0,1] neg_hi:[0,1]
	s_nop 0
	v_pk_add_f32 v[84:85], v[84:85], v[86:87]
	v_pk_add_f32 v[86:87], v[100:101], v[88:89] neg_lo:[0,1] neg_hi:[0,1]
	s_nop 0
	v_pk_add_f32 v[84:85], v[86:87], v[84:85]
	v_pk_add_f32 v[86:87], v[90:91], v[98:99]
	v_pk_add_f32 v[84:85], v[102:103], v[84:85]
	v_pk_add_f32 v[88:89], v[86:87], v[90:91] neg_lo:[0,1] neg_hi:[0,1]
	v_pk_mul_f32 v[84:85], v[94:95], v[84:85]
	v_pk_add_f32 v[88:89], v[98:99], v[88:89] neg_lo:[0,1] neg_hi:[0,1]
	s_nop 0
	v_pk_add_f32 v[84:85], v[88:89], v[84:85]
	s_nop 0
	v_pk_add_f32 v[88:89], v[86:87], v[84:85]
	s_nop 0
	v_pk_add_f32 v[86:87], v[88:89], v[86:87] neg_lo:[0,1] neg_hi:[0,1]
	v_pk_mul_f32 v[90:91], v[88:89], v[88:89]
	v_pk_add_f32 v[84:85], v[84:85], v[86:87] neg_lo:[0,1] neg_hi:[0,1]
	v_pk_fma_f32 v[92:93], v[90:91], s[28:29], v[66:67] op_sel_hi:[1,0,0]
	v_ldexp_f32 v95, v85, 1
	v_add_f32_e32 v85, v44, v80
	v_max_f32_e32 v80, 0, v85
	v_mul_f32_e64 v85, |v85|, s2
	v_exp_f32_e32 v131, v85
	v_ldexp_f32 v86, v88, 1
	v_pk_fma_f32 v[92:93], v[90:91], v[92:93], s[30:31] op_sel_hi:[1,1,0]
	v_ldexp_f32 v87, v89, 1
	v_add_f32_e32 v85, 1.0, v131
	v_pk_mul_f32 v[88:89], v[88:89], v[90:91]
	v_add_f32_e32 v90, -1.0, v85
	v_sub_f32_e32 v91, v90, v85
	v_add_f32_e32 v91, 1.0, v91
	v_sub_f32_e32 v90, v131, v90
	v_add_f32_e32 v94, v90, v91
	v_frexp_mant_f32_e32 v90, v85
	v_cmp_gt_f32_e32 vcc, s26, v90
	v_cvt_f64_f32_e32 v[90:91], v85
	v_frexp_exp_i32_f64_e32 v90, v[90:91]
	v_subbrev_co_u32_e32 v132, vcc, 0, v90, vcc
	v_sub_u32_e32 v91, 0, v132
	v_ldexp_f32 v90, v85, v91
	v_add_f32_e32 v85, v45, v81
	v_max_f32_e32 v81, 0, v85
	v_mul_f32_e64 v85, |v85|, s2
	v_exp_f32_e32 v133, v85
	v_ldexp_f32 v98, v94, v91
	v_pk_mul_f32 v[88:89], v[88:89], v[92:93]
	v_ldexp_f32 v84, v84, 1
	v_add_f32_e32 v85, 1.0, v133
	v_add_f32_e32 v91, -1.0, v85
	v_sub_f32_e32 v94, v91, v85
	v_add_f32_e32 v94, 1.0, v94
	v_sub_f32_e32 v91, v133, v91
	v_add_f32_e32 v94, v91, v94
	v_frexp_mant_f32_e32 v91, v85
	v_cvt_f64_f32_e32 v[100:101], v85
	v_cmp_gt_f32_e32 vcc, s26, v91
	v_frexp_exp_i32_f64_e32 v91, v[100:101]
	v_pk_add_f32 v[92:93], v[86:87], v[88:89]
	v_subbrev_co_u32_e32 v134, vcc, 0, v91, vcc
	v_sub_u32_e32 v99, 0, v134
	v_ldexp_f32 v91, v85, v99
	v_pk_add_f32 v[100:101], v[90:91], 1.0 op_sel_hi:[1,0]
	v_ldexp_f32 v99, v94, v99
	v_pk_add_f32 v[102:103], v[100:101], -1.0 op_sel_hi:[1,0]
	v_pk_add_f32 v[114:115], v[90:91], -1.0 op_sel_hi:[1,0]
	v_pk_add_f32 v[102:103], v[90:91], v[102:103] neg_lo:[0,1] neg_hi:[0,1]
	v_pk_add_f32 v[116:117], v[114:115], 1.0 op_sel_hi:[1,0]
	v_pk_add_f32 v[102:103], v[98:99], v[102:103]
	v_pk_add_f32 v[90:91], v[90:91], v[116:117] neg_lo:[0,1] neg_hi:[0,1]
	v_pk_add_f32 v[110:111], v[100:101], v[102:103]
	v_pk_add_f32 v[90:91], v[98:99], v[90:91]
	v_rcp_f32_e32 v112, v110
	v_rcp_f32_e32 v113, v111
	v_pk_add_f32 v[98:99], v[114:115], v[90:91]
	v_pk_add_f32 v[100:101], v[110:111], v[100:101] neg_lo:[0,1] neg_hi:[0,1]
	v_pk_add_f32 v[114:115], v[98:99], v[114:115] neg_lo:[0,1] neg_hi:[0,1]
	v_pk_add_f32 v[100:101], v[102:103], v[100:101] neg_lo:[0,1] neg_hi:[0,1]
	v_pk_mul_f32 v[102:103], v[98:99], v[112:113]
	v_pk_add_f32 v[90:91], v[90:91], v[114:115] neg_lo:[0,1] neg_hi:[0,1]
	v_pk_mul_f32 v[114:115], v[110:111], v[102:103]
	v_pk_add_f32 v[86:87], v[92:93], v[86:87] neg_lo:[0,1] neg_hi:[0,1]
	v_pk_fma_f32 v[116:117], v[102:103], v[110:111], v[114:115] neg_lo:[0,0,1] neg_hi:[0,0,1]
	v_pk_add_f32 v[86:87], v[88:89], v[86:87] neg_lo:[0,1] neg_hi:[0,1]
	v_pk_fma_f32 v[116:117], v[102:103], v[100:101], v[116:117]
	v_mov_b32_e32 v89, v87
	v_pk_add_f32 v[118:119], v[114:115], v[116:117]
	v_mov_b32_e32 v85, v95
	v_pk_add_f32 v[120:121], v[98:99], v[118:119] neg_lo:[0,1] neg_hi:[0,1]
	v_pk_add_f32 v[114:115], v[118:119], v[114:115] neg_lo:[0,1] neg_hi:[0,1]
	v_pk_add_f32 v[98:99], v[98:99], v[120:121] neg_lo:[0,1] neg_hi:[0,1]
	v_mov_b32_e32 v126, v92
	v_pk_add_f32 v[98:99], v[98:99], v[118:119] neg_lo:[0,1] neg_hi:[0,1]
	v_cmp_neq_f32_e32 vcc, s8, v83
	v_pk_add_f32 v[90:91], v[90:91], v[98:99]
	v_pk_add_f32 v[98:99], v[114:115], v[116:117] neg_lo:[0,1] neg_hi:[0,1]
	s_nop 0
	v_pk_add_f32 v[90:91], v[98:99], v[90:91]
	s_nop 0
	v_pk_add_f32 v[98:99], v[120:121], v[90:91]
	s_nop 0
	v_pk_mul_f32 v[114:115], v[112:113], v[98:99]
	s_nop 0
	v_pk_mul_f32 v[116:117], v[110:111], v[114:115]
	s_nop 0
	v_pk_fma_f32 v[110:111], v[114:115], v[110:111], v[116:117] neg_lo:[0,0,1] neg_hi:[0,0,1]
	s_nop 0
	v_pk_fma_f32 v[100:101], v[114:115], v[100:101], v[110:111]
	v_pk_add_f32 v[110:111], v[120:121], v[98:99] neg_lo:[0,1] neg_hi:[0,1]
	s_nop 0
	v_pk_add_f32 v[90:91], v[90:91], v[110:111]
	v_pk_add_f32 v[110:111], v[116:117], v[100:101]
	s_nop 0
	v_pk_add_f32 v[118:119], v[98:99], v[110:111] neg_lo:[0,1] neg_hi:[0,1]
; __device__ __forceinline__ float softplusf(float x) { return fmaxf(x, 0.f) + log1pf(__expf(-fabsf(x))); }
; __device__ void phaseA_tile(const Params& p, int l, int mt, int nt, char* smem) {
;     ...
;                     const f32x4 v = acc[i][j];
;                     *(float4*)(p.dtb + (size_t)row * 32 + c) =
;                         make_float4(softplusf(v[0] + db.x), softplusf(v[1] + db.y), softplusf(v[2] + db.z), softplusf(v[3] + db.w));
	v_pk_add_f32 v[116:117], v[110:111], v[116:117] neg_lo:[0,1] neg_hi:[0,1]
	v_pk_add_f32 v[98:99], v[98:99], v[118:119] neg_lo:[0,1] neg_hi:[0,1]
	s_nop 0
	v_pk_add_f32 v[98:99], v[98:99], v[110:111] neg_lo:[0,1] neg_hi:[0,1]
	s_nop 0
	v_pk_add_f32 v[90:91], v[90:91], v[98:99]
	v_pk_add_f32 v[98:99], v[116:117], v[100:101] neg_lo:[0,1] neg_hi:[0,1]
	s_nop 0
	v_pk_add_f32 v[90:91], v[98:99], v[90:91]
	v_pk_add_f32 v[98:99], v[102:103], v[114:115]
	v_pk_add_f32 v[90:91], v[118:119], v[90:91]
	v_pk_add_f32 v[100:101], v[98:99], v[102:103] neg_lo:[0,1] neg_hi:[0,1]
	v_pk_mul_f32 v[90:91], v[112:113], v[90:91]
	v_pk_add_f32 v[100:101], v[114:115], v[100:101] neg_lo:[0,1] neg_hi:[0,1]
	s_nop 0
	v_pk_add_f32 v[90:91], v[100:101], v[90:91]
	s_nop 0
	v_pk_add_f32 v[100:101], v[98:99], v[90:91]
	s_nop 0
	v_pk_mul_f32 v[102:103], v[100:101], v[100:101]
	v_pk_add_f32 v[98:99], v[100:101], v[98:99] neg_lo:[0,1] neg_hi:[0,1]
	v_pk_fma_f32 v[110:111], v[102:103], s[28:29], v[66:67] op_sel_hi:[1,0,0]
	v_pk_add_f32 v[90:91], v[90:91], v[98:99] neg_lo:[0,1] neg_hi:[0,1]
	v_ldexp_f32 v98, v100, 1
	v_pk_fma_f32 v[110:111], v[102:103], v[110:111], s[30:31] op_sel_hi:[1,1,0]
	v_ldexp_f32 v99, v101, 1
	v_pk_mul_f32 v[100:101], v[100:101], v[102:103]
	v_cvt_f32_i32_e32 v103, v122
	v_cvt_f32_i32_e32 v102, v97
	v_ldexp_f32 v113, v91, 1
	v_ldexp_f32 v90, v90, 1
	v_mov_b32_e32 v91, v113
	v_pk_mul_f32 v[114:115], v[102:103], s[12:13] op_sel_hi:[1,0]
	s_nop 0
	v_pk_fma_f32 v[116:117], v[102:103], s[12:13], v[114:115] op_sel_hi:[1,0,1] neg_lo:[0,0,1] neg_hi:[0,0,1]
	v_mov_b32_e32 v88, v114
	v_pk_fma_f32 v[102:103], v[102:103], s[14:15], v[116:117] op_sel_hi:[1,0,1]
	v_mov_b32_e32 v123, v115
	v_mov_b32_e32 v94, v102
	v_pk_add_f32 v[88:89], v[88:89], v[94:95]
	v_pk_add_f32 v[94:95], v[84:85], v[86:87]
	v_mov_b32_e32 v87, v93
	v_mov_b32_e32 v85, v95
	v_pk_add_f32 v[116:117], v[114:115], v[102:103]
	v_pk_add_f32 v[84:85], v[84:85], v[86:87]
	v_pk_add_f32 v[86:87], v[92:93], v[94:95]
	v_mov_b32_e32 v127, v117
	v_pk_add_f32 v[118:119], v[116:117], v[86:87]
	v_mov_b32_e32 v124, v86
	v_mov_b32_e32 v125, v119
	v_pk_add_f32 v[124:125], v[124:125], v[126:127] neg_lo:[0,1] neg_hi:[0,1]
	v_mov_b32_e32 v120, v118
	v_mov_b32_e32 v121, v117
	v_mov_b32_e32 v122, v116
	v_mov_b32_e32 v126, v116
	v_mov_b32_e32 v127, v119
	v_mov_b32_e32 v115, v125
	v_pk_add_f32 v[120:121], v[120:121], v[122:123] neg_lo:[0,1] neg_hi:[0,1]
	v_mov_b32_e32 v122, v86
	v_mov_b32_e32 v123, v103
	v_pk_add_f32 v[114:115], v[126:127], v[114:115] neg_lo:[0,1] neg_hi:[0,1]
	v_pk_add_f32 v[122:123], v[122:123], v[120:121] neg_lo:[0,1] neg_hi:[0,1]
	v_mov_b32_e32 v126, v114
	v_mov_b32_e32 v127, v121
	v_mov_b32_e32 v128, v118
	v_mov_b32_e32 v129, v87
	v_mov_b32_e32 v121, v93
	v_pk_add_f32 v[126:127], v[102:103], v[126:127] neg_lo:[0,1] neg_hi:[0,1]
	v_pk_add_f32 v[120:121], v[128:129], v[120:121] neg_lo:[0,1] neg_hi:[0,1]
	v_mov_b32_e32 v103, v117
	v_pk_add_f32 v[86:87], v[86:87], v[92:93] neg_lo:[0,1] neg_hi:[0,1]
	v_pk_add_f32 v[88:89], v[88:89], v[120:121] neg_lo:[0,1] neg_hi:[0,1]
	v_pk_add_f32 v[92:93], v[102:103], v[114:115] neg_lo:[0,1] neg_hi:[0,1]
	v_pk_add_f32 v[84:85], v[84:85], v[124:125] neg_lo:[0,1] neg_hi:[0,1]
	v_pk_add_f32 v[86:87], v[94:95], v[86:87] neg_lo:[0,1] neg_hi:[0,1]
	v_pk_add_f32 v[94:95], v[84:85], v[92:93]
	v_mov_b32_e32 v93, v123
	v_mov_b32_e32 v85, v89
	v_pk_add_f32 v[102:103], v[122:123], v[88:89]
	v_pk_add_f32 v[84:85], v[92:93], v[84:85]
	v_mov_b32_e32 v88, v94
	v_pk_add_f32 v[84:85], v[84:85], v[126:127] neg_lo:[0,1] neg_hi:[0,1]
	v_mov_b32_e32 v89, v103
	v_pk_add_f32 v[88:89], v[88:89], v[84:85] neg_lo:[0,1] neg_hi:[0,1]
	v_pk_add_f32 v[84:85], v[86:87], v[84:85] neg_lo:[0,1] neg_hi:[0,1]
	v_pk_add_f32 v[88:89], v[92:93], v[88:89] neg_lo:[0,1] neg_hi:[0,1]
	v_pk_add_f32 v[86:87], v[102:103], v[94:95]
	v_pk_add_f32 v[84:85], v[84:85], v[88:89]
	v_pk_add_f32 v[88:89], v[118:119], v[86:87]
	s_nop 0
	v_pk_add_f32 v[92:93], v[88:89], v[118:119] neg_lo:[0,1] neg_hi:[0,1]
	s_nop 0
	v_pk_add_f32 v[86:87], v[86:87], v[92:93] neg_lo:[0,1] neg_hi:[0,1]
	s_nop 0
	v_pk_add_f32 v[84:85], v[84:85], v[86:87]
	s_nop 0
	v_pk_add_f32 v[84:85], v[88:89], v[84:85]
	v_pk_mul_f32 v[88:89], v[100:101], v[110:111]
	v_cndmask_b32_e32 v84, v160, v84, vcc
	v_cmp_neq_f32_e32 vcc, s8, v130
	v_pk_add_f32 v[92:93], v[98:99], v[88:89]
	s_nop 0
	v_cndmask_b32_e32 v85, v160, v85, vcc
	v_cmp_ngt_f32_e32 vcc, -1.0, v130
	v_pk_add_f32 v[98:99], v[92:93], v[98:99] neg_lo:[0,1] neg_hi:[0,1]
	v_mov_b32_e32 v116, v92
	v_cndmask_b32_e32 v85, v161, v85, vcc
	v_cmp_ngt_f32_e32 vcc, -1.0, v83
	v_pk_add_f32 v[88:89], v[88:89], v[98:99] neg_lo:[0,1] neg_hi:[0,1]
	s_nop 0
	v_cndmask_b32_e32 v84, v161, v84, vcc
	v_cmp_neq_f32_e32 vcc, -1.0, v83
	v_pk_add_f32 v[100:101], v[90:91], v[88:89]
	v_mov_b32_e32 v99, v89
	v_cndmask_b32_e32 v84, v162, v84, vcc
	v_cmp_neq_f32_e32 vcc, -1.0, v130
	v_mov_b32_e32 v91, v101
	v_mov_b32_e32 v89, v93
	v_cndmask_b32_e32 v85, v162, v85, vcc
	v_cmp_lt_f32_e64 vcc, |v83|, s9
	v_cndmask_b32_e64 v85, v85, v130, s[0:1]
	v_pk_add_f32 v[88:89], v[90:91], v[88:89]
	v_cndmask_b32_e32 v84, v84, v83, vcc
	v_pk_add_f32 v[78:79], v[78:79], v[84:85]
	v_cvt_f32_i32_e32 v85, v134
	v_cvt_f32_i32_e32 v84, v132
	v_pk_add_f32 v[90:91], v[92:93], v[100:101]
	v_cmp_neq_f32_e32 vcc, s8, v131
	v_mov_b32_e32 v114, v90
	v_pk_mul_f32 v[86:87], v[84:85], s[12:13] op_sel_hi:[1,0]
	v_mov_b32_e32 v119, v91
	v_pk_fma_f32 v[94:95], v[84:85], s[12:13], v[86:87] op_sel_hi:[1,0,1] neg_lo:[0,0,1] neg_hi:[0,0,1]
	v_mov_b32_e32 v98, v86
	v_pk_fma_f32 v[84:85], v[84:85], s[14:15], v[94:95] op_sel_hi:[1,0,1]
	v_cmp_lt_f32_e64 s[0:1], |v133|, s9
; __device__ __forceinline__ float softplusf(float x) { return fmaxf(x, 0.f) + log1pf(__expf(-fabsf(x))); }
; __device__ __forceinline__ float logsigf(float x) { return fminf(x, 0.f) - log1pf(__expf(-fabsf(x))); }
; __device__ void phaseA_tile(const Params& p, int l, int mt, int nt, char* smem) {
;     ...
;                     *(float4*)(p.dtb + (size_t)row * 32 + c) =
;                         make_float4(softplusf(v[0] + db.x), softplusf(v[1] + db.y), softplusf(v[2] + db.z), softplusf(v[3] + db.w));
;                 }
;                 {
;                     const int c = g4 * 4;
;                     const float4 fb = *(const float4*)(p.b_f + l * 16 + c);
;                     const f32x4 v = acc[i][2];
;                     float4 lf = make_float4(logsigf(v[0] + fb.x), logsigf(v[1] + fb.y), logsigf(v[2] + fb.z), logsigf(v[3] + fb.w));
	v_pk_add_f32 v[94:95], v[86:87], v[84:85]
	v_mov_b32_e32 v112, v84
	v_pk_add_f32 v[102:103], v[94:95], v[90:91]
	v_mov_b32_e32 v117, v95
	v_mov_b32_e32 v115, v103
	v_pk_add_f32 v[114:115], v[114:115], v[116:117] neg_lo:[0,1] neg_hi:[0,1]
	v_pk_add_f32 v[98:99], v[98:99], v[112:113]
	v_mov_b32_e32 v110, v102
	v_mov_b32_e32 v111, v95
	v_mov_b32_e32 v112, v94
	v_mov_b32_e32 v113, v87
	v_mov_b32_e32 v116, v94
	v_mov_b32_e32 v117, v103
	v_mov_b32_e32 v87, v115
	v_pk_add_f32 v[110:111], v[110:111], v[112:113] neg_lo:[0,1] neg_hi:[0,1]
	v_mov_b32_e32 v112, v90
	v_mov_b32_e32 v113, v85
	v_pk_add_f32 v[86:87], v[116:117], v[86:87] neg_lo:[0,1] neg_hi:[0,1]
	v_pk_add_f32 v[112:113], v[112:113], v[110:111] neg_lo:[0,1] neg_hi:[0,1]
	v_mov_b32_e32 v116, v86
	v_mov_b32_e32 v117, v111
	v_mov_b32_e32 v118, v102
	v_mov_b32_e32 v111, v93
	v_pk_add_f32 v[116:117], v[84:85], v[116:117] neg_lo:[0,1] neg_hi:[0,1]
	v_pk_add_f32 v[110:111], v[118:119], v[110:111] neg_lo:[0,1] neg_hi:[0,1]
	v_mov_b32_e32 v85, v95
	v_pk_add_f32 v[90:91], v[90:91], v[92:93] neg_lo:[0,1] neg_hi:[0,1]
	v_pk_add_f32 v[92:93], v[98:99], v[110:111] neg_lo:[0,1] neg_hi:[0,1]
	v_pk_add_f32 v[84:85], v[84:85], v[86:87] neg_lo:[0,1] neg_hi:[0,1]
	v_pk_add_f32 v[86:87], v[88:89], v[114:115] neg_lo:[0,1] neg_hi:[0,1]
	v_pk_add_f32 v[94:95], v[112:113], v[92:93]
	v_pk_add_f32 v[88:89], v[86:87], v[84:85]
	v_mov_b32_e32 v85, v113
	v_mov_b32_e32 v87, v93
	v_pk_add_f32 v[86:87], v[84:85], v[86:87]
	v_mov_b32_e32 v92, v88
	v_pk_add_f32 v[86:87], v[86:87], v[116:117] neg_lo:[0,1] neg_hi:[0,1]
	v_mov_b32_e32 v93, v95
	v_pk_add_f32 v[90:91], v[100:101], v[90:91] neg_lo:[0,1] neg_hi:[0,1]
	v_pk_add_f32 v[92:93], v[92:93], v[86:87] neg_lo:[0,1] neg_hi:[0,1]
	v_pk_add_f32 v[86:87], v[90:91], v[86:87] neg_lo:[0,1] neg_hi:[0,1]
	v_pk_add_f32 v[84:85], v[84:85], v[92:93] neg_lo:[0,1] neg_hi:[0,1]
	s_nop 0
	v_pk_add_f32 v[84:85], v[86:87], v[84:85]
	v_pk_add_f32 v[86:87], v[94:95], v[88:89]
	s_nop 0
	v_pk_add_f32 v[88:89], v[102:103], v[86:87]
	s_nop 0
	v_pk_add_f32 v[90:91], v[88:89], v[102:103] neg_lo:[0,1] neg_hi:[0,1]
	s_nop 0
	v_pk_add_f32 v[86:87], v[86:87], v[90:91] neg_lo:[0,1] neg_hi:[0,1]
	s_nop 0
	v_pk_add_f32 v[84:85], v[84:85], v[86:87]
	s_nop 0
	v_pk_add_f32 v[84:85], v[88:89], v[84:85]
	s_nop 0
	v_cndmask_b32_e32 v83, v160, v84, vcc
	v_cmp_neq_f32_e32 vcc, s8, v133
	s_nop 1
	v_cndmask_b32_e32 v84, v160, v85, vcc
	v_cmp_ngt_f32_e32 vcc, -1.0, v133
	s_nop 1
	v_cndmask_b32_e32 v84, v161, v84, vcc
	v_cmp_ngt_f32_e32 vcc, -1.0, v131
	s_nop 1
	v_cndmask_b32_e32 v83, v161, v83, vcc
	v_cmp_neq_f32_e32 vcc, -1.0, v131
	s_nop 1
	v_cndmask_b32_e32 v83, v162, v83, vcc
	v_cmp_neq_f32_e32 vcc, -1.0, v133
	s_nop 1
	v_cndmask_b32_e32 v84, v162, v84, vcc
	v_cmp_lt_f32_e64 vcc, |v131|, s9
	v_cndmask_b32_e64 v85, v84, v133, s[0:1]
	s_nop 0
	v_cndmask_b32_e32 v84, v83, v131, vcc
	v_pk_add_f32 v[80:81], v[80:81], v[84:85]
	global_store_dwordx4 v[76:77], v[78:81], off offset:64
	global_load_dwordx4 v[76:79], v0, s[78:79]
	s_waitcnt vmcnt(0)
	v_add_f32_e32 v80, v38, v76
	v_min_f32_e32 v76, 0, v80
	v_mul_f32_e64 v80, |v80|, s2
	v_exp_f32_e32 v83, v80
	s_nop 0
	v_add_f32_e32 v84, 1.0, v83
	v_add_f32_e32 v80, -1.0, v84
	v_sub_f32_e32 v81, v80, v84
	v_add_f32_e32 v81, 1.0, v81
	v_sub_f32_e32 v80, v83, v80
	v_add_f32_e32 v85, v80, v81
	v_frexp_mant_f32_e32 v80, v84
	v_cmp_gt_f32_e32 vcc, s26, v80
	v_cvt_f64_f32_e32 v[80:81], v84
	v_frexp_exp_i32_f64_e32 v80, v[80:81]
	v_subbrev_co_u32_e32 v97, vcc, 0, v80, vcc
	v_sub_u32_e32 v81, 0, v97
	v_ldexp_f32 v80, v84, v81
	v_ldexp_f32 v84, v85, v81
	v_add_f32_e32 v81, v39, v77
	v_min_f32_e32 v77, 0, v81
	v_mul_f32_e64 v81, |v81|, s2
	v_exp_f32_e32 v128, v81
	s_nop 0
	v_add_f32_e32 v81, 1.0, v128
	v_add_f32_e32 v85, -1.0, v81
	v_sub_f32_e32 v86, v85, v81
	v_add_f32_e32 v86, 1.0, v86
	v_sub_f32_e32 v85, v128, v85
	v_add_f32_e32 v85, v85, v86
	v_frexp_mant_f32_e32 v86, v81
	v_cmp_gt_f32_e32 vcc, s26, v86
	v_cvt_f64_f32_e32 v[86:87], v81
	v_frexp_exp_i32_f64_e32 v86, v[86:87]
	v_subbrev_co_u32_e32 v120, vcc, 0, v86, vcc
	v_sub_u32_e32 v86, 0, v120
	v_ldexp_f32 v81, v81, v86
	v_ldexp_f32 v85, v85, v86
	v_pk_add_f32 v[86:87], v[80:81], 1.0 op_sel_hi:[1,0]
	v_pk_add_f32 v[94:95], v[80:81], -1.0 op_sel_hi:[1,0]
	v_pk_add_f32 v[88:89], v[86:87], -1.0 op_sel_hi:[1,0]
	v_pk_add_f32 v[98:99], v[94:95], 1.0 op_sel_hi:[1,0]
	v_pk_add_f32 v[88:89], v[80:81], v[88:89] neg_lo:[0,1] neg_hi:[0,1]
	v_pk_add_f32 v[80:81], v[80:81], v[98:99] neg_lo:[0,1] neg_hi:[0,1]
	v_pk_add_f32 v[88:89], v[84:85], v[88:89]
	v_pk_add_f32 v[80:81], v[84:85], v[80:81]
	v_pk_add_f32 v[90:91], v[86:87], v[88:89]
	v_pk_add_f32 v[84:85], v[94:95], v[80:81]
	v_rcp_f32_e32 v92, v90
	v_rcp_f32_e32 v93, v91
	v_pk_add_f32 v[86:87], v[90:91], v[86:87] neg_lo:[0,1] neg_hi:[0,1]
	v_pk_add_f32 v[94:95], v[84:85], v[94:95] neg_lo:[0,1] neg_hi:[0,1]
	v_pk_add_f32 v[86:87], v[88:89], v[86:87] neg_lo:[0,1] neg_hi:[0,1]
	v_pk_mul_f32 v[88:89], v[84:85], v[92:93]
	v_pk_add_f32 v[80:81], v[80:81], v[94:95] neg_lo:[0,1] neg_hi:[0,1]
	v_pk_mul_f32 v[94:95], v[90:91], v[88:89]
	v_cmp_lt_f32_e64 s[0:1], |v128|, s9
	v_pk_fma_f32 v[98:99], v[88:89], v[90:91], v[94:95] neg_lo:[0,0,1] neg_hi:[0,0,1]
	s_nop 0
	v_pk_fma_f32 v[98:99], v[88:89], v[86:87], v[98:99]
	s_nop 0
	v_pk_add_f32 v[100:101], v[94:95], v[98:99]
	s_nop 0
	v_pk_add_f32 v[102:103], v[84:85], v[100:101] neg_lo:[0,1] neg_hi:[0,1]
	v_pk_add_f32 v[94:95], v[100:101], v[94:95] neg_lo:[0,1] neg_hi:[0,1]
	v_pk_add_f32 v[84:85], v[84:85], v[102:103] neg_lo:[0,1] neg_hi:[0,1]
	s_nop 0
	v_pk_add_f32 v[84:85], v[84:85], v[100:101] neg_lo:[0,1] neg_hi:[0,1]
	s_nop 0
; __device__ __forceinline__ float logsigf(float x) { return fminf(x, 0.f) - log1pf(__expf(-fabsf(x))); }
; __device__ void phaseA_tile(const Params& p, int l, int mt, int nt, char* smem) {
;     ...
;                     const float4 fb = *(const float4*)(p.b_f + l * 16 + c);
;                     const f32x4 v = acc[i][2];
;                     float4 lf = make_float4(logsigf(v[0] + fb.x), logsigf(v[1] + fb.y), logsigf(v[2] + fb.z), logsigf(v[3] + fb.w));
;                     float* o = samp ? (p.out + O_LFS + ((size_t)l * TSM + (row - TP)) * 16 + c)
	v_pk_add_f32 v[80:81], v[80:81], v[84:85]
	v_pk_add_f32 v[84:85], v[94:95], v[98:99] neg_lo:[0,1] neg_hi:[0,1]
	s_nop 0
	v_pk_add_f32 v[80:81], v[84:85], v[80:81]
	s_nop 0
	v_pk_add_f32 v[84:85], v[102:103], v[80:81]
	s_nop 0
	v_pk_mul_f32 v[94:95], v[92:93], v[84:85]
	s_nop 0
	v_pk_mul_f32 v[98:99], v[90:91], v[94:95]
	s_nop 0
	v_pk_fma_f32 v[90:91], v[94:95], v[90:91], v[98:99] neg_lo:[0,0,1] neg_hi:[0,0,1]
	s_nop 0
	v_pk_fma_f32 v[86:87], v[94:95], v[86:87], v[90:91]
	v_pk_add_f32 v[90:91], v[102:103], v[84:85] neg_lo:[0,1] neg_hi:[0,1]
	s_nop 0
	v_pk_add_f32 v[80:81], v[80:81], v[90:91]
	v_pk_add_f32 v[90:91], v[98:99], v[86:87]
	s_nop 0
	v_pk_add_f32 v[100:101], v[84:85], v[90:91] neg_lo:[0,1] neg_hi:[0,1]
	v_pk_add_f32 v[98:99], v[90:91], v[98:99] neg_lo:[0,1] neg_hi:[0,1]
	v_pk_add_f32 v[84:85], v[84:85], v[100:101] neg_lo:[0,1] neg_hi:[0,1]
	s_nop 0
	v_pk_add_f32 v[84:85], v[84:85], v[90:91] neg_lo:[0,1] neg_hi:[0,1]
	s_nop 0
	v_pk_add_f32 v[80:81], v[80:81], v[84:85]
	v_pk_add_f32 v[84:85], v[98:99], v[86:87] neg_lo:[0,1] neg_hi:[0,1]
	s_nop 0
	v_pk_add_f32 v[80:81], v[84:85], v[80:81]
	v_pk_add_f32 v[84:85], v[88:89], v[94:95]
	v_pk_add_f32 v[80:81], v[100:101], v[80:81]
	v_pk_add_f32 v[86:87], v[84:85], v[88:89] neg_lo:[0,1] neg_hi:[0,1]
	v_pk_mul_f32 v[80:81], v[92:93], v[80:81]
	v_pk_add_f32 v[86:87], v[94:95], v[86:87] neg_lo:[0,1] neg_hi:[0,1]
	s_nop 0
	v_pk_add_f32 v[80:81], v[86:87], v[80:81]
	s_nop 0
	v_pk_add_f32 v[86:87], v[84:85], v[80:81]
	s_nop 0
	v_pk_add_f32 v[84:85], v[86:87], v[84:85] neg_lo:[0,1] neg_hi:[0,1]
	v_pk_mul_f32 v[88:89], v[86:87], v[86:87]
	v_pk_add_f32 v[80:81], v[80:81], v[84:85] neg_lo:[0,1] neg_hi:[0,1]
	v_pk_fma_f32 v[90:91], v[88:89], s[28:29], v[66:67] op_sel_hi:[1,0,0]
	v_ldexp_f32 v93, v81, 1
	v_add_f32_e32 v81, v40, v78
	v_min_f32_e32 v78, 0, v81
	v_mul_f32_e64 v81, |v81|, s2
	v_exp_f32_e32 v129, v81
	v_ldexp_f32 v84, v86, 1
	v_pk_fma_f32 v[90:91], v[88:89], v[90:91], s[30:31] op_sel_hi:[1,1,0]
	v_ldexp_f32 v85, v87, 1
	v_add_f32_e32 v81, 1.0, v129
	v_pk_mul_f32 v[86:87], v[86:87], v[88:89]
	v_add_f32_e32 v88, -1.0, v81
	v_sub_f32_e32 v89, v88, v81
	v_add_f32_e32 v89, 1.0, v89
	v_sub_f32_e32 v88, v129, v88
	v_add_f32_e32 v92, v88, v89
	v_frexp_mant_f32_e32 v88, v81
	v_cmp_gt_f32_e32 vcc, s26, v88
	v_cvt_f64_f32_e32 v[88:89], v81
	v_frexp_exp_i32_f64_e32 v88, v[88:89]
	v_subbrev_co_u32_e32 v130, vcc, 0, v88, vcc
	v_sub_u32_e32 v89, 0, v130
	v_ldexp_f32 v88, v81, v89
	v_add_f32_e32 v81, v41, v79
	v_min_f32_e32 v79, 0, v81
	v_mul_f32_e64 v81, |v81|, s2
	v_exp_f32_e32 v131, v81
	v_ldexp_f32 v94, v92, v89
	v_pk_mul_f32 v[86:87], v[86:87], v[90:91]
	v_ldexp_f32 v80, v80, 1
	v_add_f32_e32 v81, 1.0, v131
	v_add_f32_e32 v89, -1.0, v81
	v_sub_f32_e32 v92, v89, v81
	v_add_f32_e32 v92, 1.0, v92
	v_sub_f32_e32 v89, v131, v89
	v_add_f32_e32 v92, v89, v92
	v_frexp_mant_f32_e32 v89, v81
	v_cvt_f64_f32_e32 v[98:99], v81
	v_cmp_gt_f32_e32 vcc, s26, v89
	v_frexp_exp_i32_f64_e32 v89, v[98:99]
	v_pk_add_f32 v[90:91], v[84:85], v[86:87]
	v_subbrev_co_u32_e32 v132, vcc, 0, v89, vcc
	v_sub_u32_e32 v95, 0, v132
	v_ldexp_f32 v89, v81, v95
	v_pk_add_f32 v[98:99], v[88:89], 1.0 op_sel_hi:[1,0]
	v_ldexp_f32 v95, v92, v95
	v_pk_add_f32 v[100:101], v[98:99], -1.0 op_sel_hi:[1,0]
	v_pk_add_f32 v[112:113], v[88:89], -1.0 op_sel_hi:[1,0]
	v_pk_add_f32 v[100:101], v[88:89], v[100:101] neg_lo:[0,1] neg_hi:[0,1]
	v_pk_add_f32 v[114:115], v[112:113], 1.0 op_sel_hi:[1,0]
	v_pk_add_f32 v[100:101], v[94:95], v[100:101]
	v_pk_add_f32 v[88:89], v[88:89], v[114:115] neg_lo:[0,1] neg_hi:[0,1]
	v_pk_add_f32 v[102:103], v[98:99], v[100:101]
	v_pk_add_f32 v[88:89], v[94:95], v[88:89]
	v_rcp_f32_e32 v110, v102
	v_rcp_f32_e32 v111, v103
	v_pk_add_f32 v[94:95], v[112:113], v[88:89]
	v_pk_add_f32 v[98:99], v[102:103], v[98:99] neg_lo:[0,1] neg_hi:[0,1]
	v_pk_add_f32 v[112:113], v[94:95], v[112:113] neg_lo:[0,1] neg_hi:[0,1]
	v_pk_add_f32 v[98:99], v[100:101], v[98:99] neg_lo:[0,1] neg_hi:[0,1]
	v_pk_mul_f32 v[100:101], v[94:95], v[110:111]
	v_pk_add_f32 v[88:89], v[88:89], v[112:113] neg_lo:[0,1] neg_hi:[0,1]
	v_pk_mul_f32 v[112:113], v[102:103], v[100:101]
	v_pk_add_f32 v[84:85], v[90:91], v[84:85] neg_lo:[0,1] neg_hi:[0,1]
	v_pk_fma_f32 v[114:115], v[100:101], v[102:103], v[112:113] neg_lo:[0,0,1] neg_hi:[0,0,1]
	v_add_u32_e32 v81, 0xffff8000, v68
	v_pk_fma_f32 v[114:115], v[100:101], v[98:99], v[114:115]
	v_pk_add_f32 v[84:85], v[86:87], v[84:85] neg_lo:[0,1] neg_hi:[0,1]
	v_pk_add_f32 v[116:117], v[112:113], v[114:115]
	v_cndmask_b32_e64 v68, v68, v81, s[60:61]
	v_pk_add_f32 v[118:119], v[94:95], v[116:117] neg_lo:[0,1] neg_hi:[0,1]
	v_pk_add_f32 v[112:113], v[116:117], v[112:113] neg_lo:[0,1] neg_hi:[0,1]
	v_pk_add_f32 v[94:95], v[94:95], v[118:119] neg_lo:[0,1] neg_hi:[0,1]
	v_mov_b32_e32 v87, v85
	v_pk_add_f32 v[94:95], v[94:95], v[116:117] neg_lo:[0,1] neg_hi:[0,1]
	v_mov_b32_e32 v124, v90
	v_pk_add_f32 v[88:89], v[88:89], v[94:95]
	v_pk_add_f32 v[94:95], v[112:113], v[114:115] neg_lo:[0,1] neg_hi:[0,1]
	v_cmp_neq_f32_e32 vcc, s8, v83
	v_pk_add_f32 v[88:89], v[94:95], v[88:89]
	s_nop 0
	v_pk_add_f32 v[94:95], v[118:119], v[88:89]
	s_nop 0
	v_pk_mul_f32 v[112:113], v[110:111], v[94:95]
	s_nop 0
	v_pk_mul_f32 v[114:115], v[102:103], v[112:113]
	s_nop 0
	v_pk_fma_f32 v[102:103], v[112:113], v[102:103], v[114:115] neg_lo:[0,0,1] neg_hi:[0,0,1]
	s_nop 0
	v_pk_fma_f32 v[98:99], v[112:113], v[98:99], v[102:103]
	v_pk_add_f32 v[102:103], v[118:119], v[94:95] neg_lo:[0,1] neg_hi:[0,1]
	s_nop 0
	v_pk_add_f32 v[88:89], v[88:89], v[102:103]
	v_pk_add_f32 v[102:103], v[114:115], v[98:99]
	s_nop 0
	v_pk_add_f32 v[116:117], v[94:95], v[102:103] neg_lo:[0,1] neg_hi:[0,1]
; __device__ __forceinline__ float logsigf(float x) { return fminf(x, 0.f) - log1pf(__expf(-fabsf(x))); }
; __device__ void phaseA_tile(const Params& p, int l, int mt, int nt, char* smem) {
;     ...
;                     float4 lf = make_float4(logsigf(v[0] + fb.x), logsigf(v[1] + fb.y), logsigf(v[2] + fb.z), logsigf(v[3] + fb.w));
;                     float* o = samp ? (p.out + O_LFS + ((size_t)l * TSM + (row - TP)) * 16 + c)
;                                     : (p.out + O_LFP + ((size_t)l * TP + row) * 16 + c);
;                     *(float4*)o = lf;
	v_pk_add_f32 v[114:115], v[102:103], v[114:115] neg_lo:[0,1] neg_hi:[0,1]
	v_pk_add_f32 v[94:95], v[94:95], v[116:117] neg_lo:[0,1] neg_hi:[0,1]
	s_nop 0
	v_pk_add_f32 v[94:95], v[94:95], v[102:103] neg_lo:[0,1] neg_hi:[0,1]
	s_nop 0
	v_pk_add_f32 v[88:89], v[88:89], v[94:95]
	v_pk_add_f32 v[94:95], v[114:115], v[98:99] neg_lo:[0,1] neg_hi:[0,1]
	s_nop 0
	v_pk_add_f32 v[88:89], v[94:95], v[88:89]
	v_pk_add_f32 v[94:95], v[100:101], v[112:113]
	v_pk_add_f32 v[88:89], v[116:117], v[88:89]
	v_pk_add_f32 v[98:99], v[94:95], v[100:101] neg_lo:[0,1] neg_hi:[0,1]
	v_pk_mul_f32 v[88:89], v[110:111], v[88:89]
	v_pk_add_f32 v[98:99], v[112:113], v[98:99] neg_lo:[0,1] neg_hi:[0,1]
	s_nop 0
	v_pk_add_f32 v[88:89], v[98:99], v[88:89]
	s_nop 0
	v_pk_add_f32 v[98:99], v[94:95], v[88:89]
	s_nop 0
	v_pk_mul_f32 v[100:101], v[98:99], v[98:99]
	v_pk_add_f32 v[94:95], v[98:99], v[94:95] neg_lo:[0,1] neg_hi:[0,1]
	v_pk_fma_f32 v[102:103], v[100:101], s[28:29], v[66:67] op_sel_hi:[1,0,0]
	v_pk_add_f32 v[88:89], v[88:89], v[94:95] neg_lo:[0,1] neg_hi:[0,1]
	v_ldexp_f32 v94, v98, 1
	v_pk_fma_f32 v[102:103], v[100:101], v[102:103], s[30:31] op_sel_hi:[1,1,0]
	v_ldexp_f32 v95, v99, 1
	v_pk_mul_f32 v[98:99], v[98:99], v[100:101]
	v_cvt_f32_i32_e32 v101, v120
	v_cvt_f32_i32_e32 v100, v97
	v_ldexp_f32 v111, v89, 1
	v_ashrrev_i32_e32 v89, 31, v81
	v_mov_b32_e32 v81, v93
	v_pk_mul_f32 v[112:113], v[100:101], s[12:13] op_sel_hi:[1,0]
	v_ldexp_f32 v88, v88, 1
	v_pk_fma_f32 v[114:115], v[100:101], s[12:13], v[112:113] op_sel_hi:[1,0,1] neg_lo:[0,0,1] neg_hi:[0,0,1]
	v_mov_b32_e32 v86, v112
	v_pk_fma_f32 v[100:101], v[100:101], s[14:15], v[114:115] op_sel_hi:[1,0,1]
	v_mov_b32_e32 v121, v113
	v_mov_b32_e32 v92, v100
	v_pk_add_f32 v[86:87], v[86:87], v[92:93]
	v_pk_add_f32 v[92:93], v[80:81], v[84:85]
	v_mov_b32_e32 v85, v91
	v_mov_b32_e32 v81, v93
	v_pk_add_f32 v[114:115], v[112:113], v[100:101]
	v_pk_add_f32 v[80:81], v[80:81], v[84:85]
	v_pk_add_f32 v[84:85], v[90:91], v[92:93]
	v_mov_b32_e32 v125, v115
	v_pk_add_f32 v[116:117], v[114:115], v[84:85]
	v_mov_b32_e32 v122, v84
	v_mov_b32_e32 v123, v117
	v_pk_add_f32 v[122:123], v[122:123], v[124:125] neg_lo:[0,1] neg_hi:[0,1]
	v_mov_b32_e32 v118, v116
	v_mov_b32_e32 v119, v115
	v_mov_b32_e32 v120, v114
	v_mov_b32_e32 v124, v114
	v_mov_b32_e32 v125, v117
	v_mov_b32_e32 v113, v123
	v_pk_add_f32 v[118:119], v[118:119], v[120:121] neg_lo:[0,1] neg_hi:[0,1]
	v_mov_b32_e32 v120, v84
	v_mov_b32_e32 v121, v101
	v_pk_add_f32 v[112:113], v[124:125], v[112:113] neg_lo:[0,1] neg_hi:[0,1]
	v_pk_add_f32 v[120:121], v[120:121], v[118:119] neg_lo:[0,1] neg_hi:[0,1]
	v_mov_b32_e32 v124, v112
	v_mov_b32_e32 v125, v119
	v_mov_b32_e32 v126, v116
	v_mov_b32_e32 v127, v85
	v_mov_b32_e32 v119, v91
	v_pk_add_f32 v[124:125], v[100:101], v[124:125] neg_lo:[0,1] neg_hi:[0,1]
	v_pk_add_f32 v[118:119], v[126:127], v[118:119] neg_lo:[0,1] neg_hi:[0,1]
	v_mov_b32_e32 v101, v115
	v_pk_add_f32 v[84:85], v[84:85], v[90:91] neg_lo:[0,1] neg_hi:[0,1]
	v_pk_add_f32 v[86:87], v[86:87], v[118:119] neg_lo:[0,1] neg_hi:[0,1]
	v_pk_add_f32 v[90:91], v[100:101], v[112:113] neg_lo:[0,1] neg_hi:[0,1]
	v_pk_add_f32 v[80:81], v[80:81], v[122:123] neg_lo:[0,1] neg_hi:[0,1]
	v_pk_add_f32 v[84:85], v[92:93], v[84:85] neg_lo:[0,1] neg_hi:[0,1]
	v_pk_add_f32 v[92:93], v[80:81], v[90:91]
	v_mov_b32_e32 v91, v121
	v_mov_b32_e32 v81, v87
	v_pk_add_f32 v[100:101], v[120:121], v[86:87]
	v_pk_add_f32 v[80:81], v[90:91], v[80:81]
	v_mov_b32_e32 v86, v92
	v_pk_add_f32 v[80:81], v[80:81], v[124:125] neg_lo:[0,1] neg_hi:[0,1]
	v_mov_b32_e32 v87, v101
	v_pk_add_f32 v[86:87], v[86:87], v[80:81] neg_lo:[0,1] neg_hi:[0,1]
	v_pk_add_f32 v[80:81], v[84:85], v[80:81] neg_lo:[0,1] neg_hi:[0,1]
	v_pk_add_f32 v[86:87], v[90:91], v[86:87] neg_lo:[0,1] neg_hi:[0,1]
	v_pk_add_f32 v[84:85], v[100:101], v[92:93]
	v_pk_add_f32 v[80:81], v[80:81], v[86:87]
	v_pk_add_f32 v[86:87], v[116:117], v[84:85]
	v_cndmask_b32_e64 v69, v69, v89, s[60:61]
	v_pk_add_f32 v[90:91], v[86:87], v[116:117] neg_lo:[0,1] neg_hi:[0,1]
	v_mov_b32_e32 v89, v111
	v_pk_add_f32 v[84:85], v[84:85], v[90:91] neg_lo:[0,1] neg_hi:[0,1]
	v_lshlrev_b64 v[68:69], 6, v[68:69]
	v_pk_add_f32 v[80:81], v[80:81], v[84:85]
	v_lshl_add_u64 v[68:69], s[6:7], 0, v[68:69]
	v_pk_add_f32 v[80:81], v[86:87], v[80:81]
	v_pk_mul_f32 v[86:87], v[98:99], v[102:103]
	v_cndmask_b32_e32 v80, v160, v80, vcc
	v_cmp_neq_f32_e32 vcc, s8, v128
	v_pk_add_f32 v[90:91], v[94:95], v[86:87]
	v_lshl_add_u64 v[68:69], v[68:69], 0, v[0:1]
	v_cndmask_b32_e32 v81, v160, v81, vcc
	v_cmp_ngt_f32_e32 vcc, -1.0, v128
	v_pk_add_f32 v[94:95], v[90:91], v[94:95] neg_lo:[0,1] neg_hi:[0,1]
	v_mov_b32_e32 v114, v90
	v_cndmask_b32_e32 v81, v161, v81, vcc
	v_cmp_ngt_f32_e32 vcc, -1.0, v83
	v_pk_add_f32 v[86:87], v[86:87], v[94:95] neg_lo:[0,1] neg_hi:[0,1]
	s_nop 0
	v_cndmask_b32_e32 v80, v161, v80, vcc
	v_cmp_neq_f32_e32 vcc, -1.0, v83
	v_pk_add_f32 v[98:99], v[88:89], v[86:87]
	v_mov_b32_e32 v95, v87
	v_cndmask_b32_e32 v80, v162, v80, vcc
	v_cmp_neq_f32_e32 vcc, -1.0, v128
	v_mov_b32_e32 v89, v99
	v_mov_b32_e32 v87, v91
	v_cndmask_b32_e32 v81, v162, v81, vcc
	v_cmp_lt_f32_e64 vcc, |v83|, s9
	v_cndmask_b32_e64 v81, v81, v128, s[0:1]
	v_pk_add_f32 v[86:87], v[88:89], v[86:87]
	v_cndmask_b32_e32 v80, v80, v83, vcc
	v_pk_add_f32 v[76:77], v[76:77], v[80:81] neg_lo:[0,1] neg_hi:[0,1]
	v_cvt_f32_i32_e32 v81, v132
	v_cvt_f32_i32_e32 v80, v130
	v_pk_add_f32 v[88:89], v[90:91], v[98:99]
	v_cmp_neq_f32_e32 vcc, s8, v129
	v_mov_b32_e32 v112, v88
	v_pk_mul_f32 v[84:85], v[80:81], s[12:13] op_sel_hi:[1,0]
	v_mov_b32_e32 v117, v89
	v_pk_fma_f32 v[92:93], v[80:81], s[12:13], v[84:85] op_sel_hi:[1,0,1] neg_lo:[0,0,1] neg_hi:[0,0,1]
; __device__ __forceinline__ float softplusf(float x) { return fmaxf(x, 0.f) + log1pf(__expf(-fabsf(x))); }
; __device__ __forceinline__ float logsigf(float x) { return fminf(x, 0.f) - log1pf(__expf(-fabsf(x))); }
; __device__ void phaseA_tile(const Params& p, int l, int mt, int nt, char* smem) {
;     ...
;                     const float4 db = *(const float4*)(p.dt_bias + l * 32 + c);
;                     const f32x4 v = acc[i][j];
;                     *(float4*)(p.dtb + (size_t)row * 32 + c) =
;                         make_float4(softplusf(v[0] + db.x), softplusf(v[1] + db.y), softplusf(v[2] + db.z), softplusf(v[3] + db.w));
;     ...
;                     *(float4*)o = lf;
;                     *(float4*)(lf_s + rl * 16 + c) = lf;
	v_mov_b32_e32 v94, v84
	v_pk_fma_f32 v[80:81], v[80:81], s[14:15], v[92:93] op_sel_hi:[1,0,1]
	v_cmp_lt_f32_e64 s[0:1], |v131|, s9
	v_pk_add_f32 v[92:93], v[84:85], v[80:81]
	v_mov_b32_e32 v110, v80
	v_pk_add_f32 v[100:101], v[92:93], v[88:89]
	v_mov_b32_e32 v115, v93
	v_mov_b32_e32 v113, v101
	v_pk_add_f32 v[112:113], v[112:113], v[114:115] neg_lo:[0,1] neg_hi:[0,1]
	v_pk_add_f32 v[94:95], v[94:95], v[110:111]
	v_mov_b32_e32 v102, v100
	v_mov_b32_e32 v103, v93
	v_mov_b32_e32 v110, v92
	v_mov_b32_e32 v111, v85
	v_mov_b32_e32 v114, v92
	v_mov_b32_e32 v115, v101
	v_mov_b32_e32 v85, v113
	v_pk_add_f32 v[102:103], v[102:103], v[110:111] neg_lo:[0,1] neg_hi:[0,1]
	v_mov_b32_e32 v110, v88
	v_mov_b32_e32 v111, v81
	v_pk_add_f32 v[84:85], v[114:115], v[84:85] neg_lo:[0,1] neg_hi:[0,1]
	v_pk_add_f32 v[110:111], v[110:111], v[102:103] neg_lo:[0,1] neg_hi:[0,1]
	v_mov_b32_e32 v114, v84
	v_mov_b32_e32 v115, v103
	v_mov_b32_e32 v116, v100
	v_mov_b32_e32 v103, v91
	v_pk_add_f32 v[114:115], v[80:81], v[114:115] neg_lo:[0,1] neg_hi:[0,1]
	v_pk_add_f32 v[102:103], v[116:117], v[102:103] neg_lo:[0,1] neg_hi:[0,1]
	v_mov_b32_e32 v81, v93
	v_pk_add_f32 v[88:89], v[88:89], v[90:91] neg_lo:[0,1] neg_hi:[0,1]
	v_pk_add_f32 v[90:91], v[94:95], v[102:103] neg_lo:[0,1] neg_hi:[0,1]
	v_pk_add_f32 v[80:81], v[80:81], v[84:85] neg_lo:[0,1] neg_hi:[0,1]
	v_pk_add_f32 v[84:85], v[86:87], v[112:113] neg_lo:[0,1] neg_hi:[0,1]
	v_pk_add_f32 v[92:93], v[110:111], v[90:91]
	v_pk_add_f32 v[86:87], v[84:85], v[80:81]
	v_mov_b32_e32 v81, v111
	v_mov_b32_e32 v85, v91
	v_pk_add_f32 v[84:85], v[80:81], v[84:85]
	v_mov_b32_e32 v90, v86
	v_pk_add_f32 v[84:85], v[84:85], v[114:115] neg_lo:[0,1] neg_hi:[0,1]
	v_mov_b32_e32 v91, v93
	v_pk_add_f32 v[88:89], v[98:99], v[88:89] neg_lo:[0,1] neg_hi:[0,1]
	v_pk_add_f32 v[90:91], v[90:91], v[84:85] neg_lo:[0,1] neg_hi:[0,1]
	v_pk_add_f32 v[84:85], v[88:89], v[84:85] neg_lo:[0,1] neg_hi:[0,1]
	v_pk_add_f32 v[80:81], v[80:81], v[90:91] neg_lo:[0,1] neg_hi:[0,1]
	s_nop 0
	v_pk_add_f32 v[80:81], v[84:85], v[80:81]
	v_pk_add_f32 v[84:85], v[92:93], v[86:87]
	s_nop 0
	v_pk_add_f32 v[86:87], v[100:101], v[84:85]
	s_nop 0
	v_pk_add_f32 v[88:89], v[86:87], v[100:101] neg_lo:[0,1] neg_hi:[0,1]
	s_nop 0
	v_pk_add_f32 v[84:85], v[84:85], v[88:89] neg_lo:[0,1] neg_hi:[0,1]
	s_nop 0
	v_pk_add_f32 v[80:81], v[80:81], v[84:85]
	s_nop 0
	v_pk_add_f32 v[80:81], v[86:87], v[80:81]
	s_nop 0
	v_cndmask_b32_e32 v80, v160, v80, vcc
	v_cmp_neq_f32_e32 vcc, s8, v131
	s_nop 1
	v_cndmask_b32_e32 v81, v160, v81, vcc
	v_cmp_ngt_f32_e32 vcc, -1.0, v131
	s_nop 1
	v_cndmask_b32_e32 v81, v161, v81, vcc
	v_cmp_ngt_f32_e32 vcc, -1.0, v129
	s_nop 1
	v_cndmask_b32_e32 v80, v161, v80, vcc
	v_cmp_neq_f32_e32 vcc, -1.0, v129
	s_nop 1
	v_cndmask_b32_e32 v80, v162, v80, vcc
	v_cmp_neq_f32_e32 vcc, -1.0, v131
	s_nop 1
	v_cndmask_b32_e32 v81, v162, v81, vcc
	v_cmp_lt_f32_e64 vcc, |v129|, s9
	v_cndmask_b32_e64 v81, v81, v131, s[0:1]
	s_nop 0
	v_cndmask_b32_e32 v80, v80, v129, vcc
	v_pk_add_f32 v[78:79], v[78:79], v[80:81] neg_lo:[0,1] neg_hi:[0,1]
	global_store_dwordx4 v[68:69], v[76:79], off
	v_lshl_or_b32 v68, v82, 6, v0
	ds_write_b128 v68, v[76:79]
	global_load_dwordx4 v[78:81], v0, s[74:75]
	v_or_b32_e32 v82, 32, v71
	v_add_u32_e32 v68, s54, v82
	v_ashrrev_i32_e32 v69, 31, v68
	v_lshlrev_b64 v[76:77], 7, v[68:69]
	v_lshl_add_u64 v[76:77], s[10:11], 0, v[76:77]
	v_lshl_add_u64 v[76:77], v[76:77], 0, v[0:1]
	v_or_b32_e32 v71, 48, v71
	s_waitcnt vmcnt(0)
	v_add_f32_e32 v83, v30, v78
	v_max_f32_e32 v78, 0, v83
	v_mul_f32_e64 v83, |v83|, s2
	v_exp_f32_e32 v83, v83
	s_nop 0
	v_add_f32_e32 v86, 1.0, v83
	v_add_f32_e32 v84, -1.0, v86
	v_sub_f32_e32 v85, v84, v86
	v_add_f32_e32 v85, 1.0, v85
	v_sub_f32_e32 v84, v83, v84
	v_add_f32_e32 v87, v84, v85
	v_frexp_mant_f32_e32 v84, v86
	v_cmp_gt_f32_e32 vcc, s26, v84
	v_cvt_f64_f32_e32 v[84:85], v86
	v_frexp_exp_i32_f64_e32 v84, v[84:85]
	v_subbrev_co_u32_e32 v97, vcc, 0, v84, vcc
	v_sub_u32_e32 v85, 0, v97
	v_ldexp_f32 v84, v86, v85
	v_ldexp_f32 v86, v87, v85
	v_add_f32_e32 v85, v31, v79
	v_max_f32_e32 v79, 0, v85
	v_mul_f32_e64 v85, |v85|, s2
	v_exp_f32_e32 v130, v85
	s_nop 0
	v_add_f32_e32 v85, 1.0, v130
	v_add_f32_e32 v87, -1.0, v85
	v_sub_f32_e32 v88, v87, v85
	v_add_f32_e32 v88, 1.0, v88
	v_sub_f32_e32 v87, v130, v87
	v_add_f32_e32 v87, v87, v88
	v_frexp_mant_f32_e32 v88, v85
	v_cmp_gt_f32_e32 vcc, s26, v88
	v_cvt_f64_f32_e32 v[88:89], v85
	v_frexp_exp_i32_f64_e32 v88, v[88:89]
	v_subbrev_co_u32_e32 v122, vcc, 0, v88, vcc
	v_sub_u32_e32 v88, 0, v122
	v_ldexp_f32 v85, v85, v88
	v_ldexp_f32 v87, v87, v88
	v_pk_add_f32 v[88:89], v[84:85], 1.0 op_sel_hi:[1,0]
	v_pk_add_f32 v[98:99], v[84:85], -1.0 op_sel_hi:[1,0]
	v_pk_add_f32 v[90:91], v[88:89], -1.0 op_sel_hi:[1,0]
	v_pk_add_f32 v[100:101], v[98:99], 1.0 op_sel_hi:[1,0]
	v_pk_add_f32 v[90:91], v[84:85], v[90:91] neg_lo:[0,1] neg_hi:[0,1]
	v_pk_add_f32 v[84:85], v[84:85], v[100:101] neg_lo:[0,1] neg_hi:[0,1]
	v_pk_add_f32 v[90:91], v[86:87], v[90:91]
	v_pk_add_f32 v[84:85], v[86:87], v[84:85]
	v_pk_add_f32 v[92:93], v[88:89], v[90:91]
	v_pk_add_f32 v[86:87], v[98:99], v[84:85]
	v_rcp_f32_e32 v94, v92
	v_rcp_f32_e32 v95, v93
	v_pk_add_f32 v[88:89], v[92:93], v[88:89] neg_lo:[0,1] neg_hi:[0,1]
	v_pk_add_f32 v[98:99], v[86:87], v[98:99] neg_lo:[0,1] neg_hi:[0,1]
	v_pk_add_f32 v[88:89], v[90:91], v[88:89] neg_lo:[0,1] neg_hi:[0,1]
	v_pk_mul_f32 v[90:91], v[86:87], v[94:95]
	v_pk_add_f32 v[84:85], v[84:85], v[98:99] neg_lo:[0,1] neg_hi:[0,1]
	v_pk_mul_f32 v[98:99], v[92:93], v[90:91]
	v_cmp_lt_f32_e64 s[0:1], |v130|, s9
	v_pk_fma_f32 v[100:101], v[90:91], v[92:93], v[98:99] neg_lo:[0,0,1] neg_hi:[0,0,1]
; __device__ __forceinline__ float softplusf(float x) { return fmaxf(x, 0.f) + log1pf(__expf(-fabsf(x))); }
; __device__ void phaseA_tile(const Params& p, int l, int mt, int nt, char* smem) {
;     ...
;                     const f32x4 v = acc[i][j];
;                     *(float4*)(p.dtb + (size_t)row * 32 + c) =
;                         make_float4(softplusf(v[0] + db.x), softplusf(v[1] + db.y), softplusf(v[2] + db.z), softplusf(v[3] + db.w));
	s_nop 0
	v_pk_fma_f32 v[100:101], v[90:91], v[88:89], v[100:101]
	s_nop 0
	v_pk_add_f32 v[102:103], v[98:99], v[100:101]
	s_nop 0
	v_pk_add_f32 v[110:111], v[86:87], v[102:103] neg_lo:[0,1] neg_hi:[0,1]
	v_pk_add_f32 v[98:99], v[102:103], v[98:99] neg_lo:[0,1] neg_hi:[0,1]
	v_pk_add_f32 v[86:87], v[86:87], v[110:111] neg_lo:[0,1] neg_hi:[0,1]
	s_nop 0
	v_pk_add_f32 v[86:87], v[86:87], v[102:103] neg_lo:[0,1] neg_hi:[0,1]
	s_nop 0
	v_pk_add_f32 v[84:85], v[84:85], v[86:87]
	v_pk_add_f32 v[86:87], v[98:99], v[100:101] neg_lo:[0,1] neg_hi:[0,1]
	s_nop 0
	v_pk_add_f32 v[84:85], v[86:87], v[84:85]
	s_nop 0
	v_pk_add_f32 v[86:87], v[110:111], v[84:85]
	s_nop 0
	v_pk_mul_f32 v[98:99], v[94:95], v[86:87]
	s_nop 0
	v_pk_mul_f32 v[100:101], v[92:93], v[98:99]
	s_nop 0
	v_pk_fma_f32 v[92:93], v[98:99], v[92:93], v[100:101] neg_lo:[0,0,1] neg_hi:[0,0,1]
	s_nop 0
	v_pk_fma_f32 v[88:89], v[98:99], v[88:89], v[92:93]
	v_pk_add_f32 v[92:93], v[110:111], v[86:87] neg_lo:[0,1] neg_hi:[0,1]
	s_nop 0
	v_pk_add_f32 v[84:85], v[84:85], v[92:93]
	v_pk_add_f32 v[92:93], v[100:101], v[88:89]
	s_nop 0
	v_pk_add_f32 v[102:103], v[86:87], v[92:93] neg_lo:[0,1] neg_hi:[0,1]
	v_pk_add_f32 v[100:101], v[92:93], v[100:101] neg_lo:[0,1] neg_hi:[0,1]
	v_pk_add_f32 v[86:87], v[86:87], v[102:103] neg_lo:[0,1] neg_hi:[0,1]
	s_nop 0
	v_pk_add_f32 v[86:87], v[86:87], v[92:93] neg_lo:[0,1] neg_hi:[0,1]
	s_nop 0
	v_pk_add_f32 v[84:85], v[84:85], v[86:87]
	v_pk_add_f32 v[86:87], v[100:101], v[88:89] neg_lo:[0,1] neg_hi:[0,1]
	s_nop 0
	v_pk_add_f32 v[84:85], v[86:87], v[84:85]
	v_pk_add_f32 v[86:87], v[90:91], v[98:99]
	v_pk_add_f32 v[84:85], v[102:103], v[84:85]
	v_pk_add_f32 v[88:89], v[86:87], v[90:91] neg_lo:[0,1] neg_hi:[0,1]
	v_pk_mul_f32 v[84:85], v[94:95], v[84:85]
	v_pk_add_f32 v[88:89], v[98:99], v[88:89] neg_lo:[0,1] neg_hi:[0,1]
	s_nop 0
	v_pk_add_f32 v[84:85], v[88:89], v[84:85]
	s_nop 0
	v_pk_add_f32 v[88:89], v[86:87], v[84:85]
	s_nop 0
	v_pk_add_f32 v[86:87], v[88:89], v[86:87] neg_lo:[0,1] neg_hi:[0,1]
	v_pk_mul_f32 v[90:91], v[88:89], v[88:89]
	v_pk_add_f32 v[84:85], v[84:85], v[86:87] neg_lo:[0,1] neg_hi:[0,1]
	v_pk_fma_f32 v[92:93], v[90:91], s[28:29], v[66:67] op_sel_hi:[1,0,0]
	v_ldexp_f32 v95, v85, 1
	v_add_f32_e32 v85, v32, v80
	v_max_f32_e32 v80, 0, v85
	v_mul_f32_e64 v85, |v85|, s2
	v_exp_f32_e32 v131, v85
	v_ldexp_f32 v86, v88, 1
	v_pk_fma_f32 v[92:93], v[90:91], v[92:93], s[30:31] op_sel_hi:[1,1,0]
	v_ldexp_f32 v87, v89, 1
	v_add_f32_e32 v85, 1.0, v131
	v_pk_mul_f32 v[88:89], v[88:89], v[90:91]
	v_add_f32_e32 v90, -1.0, v85
	v_sub_f32_e32 v91, v90, v85
	v_add_f32_e32 v91, 1.0, v91
	v_sub_f32_e32 v90, v131, v90
	v_add_f32_e32 v94, v90, v91
	v_frexp_mant_f32_e32 v90, v85
	v_cmp_gt_f32_e32 vcc, s26, v90
	v_cvt_f64_f32_e32 v[90:91], v85
	v_frexp_exp_i32_f64_e32 v90, v[90:91]
	v_subbrev_co_u32_e32 v132, vcc, 0, v90, vcc
	v_sub_u32_e32 v91, 0, v132
	v_ldexp_f32 v90, v85, v91
	v_add_f32_e32 v85, v33, v81
	v_max_f32_e32 v81, 0, v85
	v_mul_f32_e64 v85, |v85|, s2
	v_exp_f32_e32 v133, v85
	v_ldexp_f32 v98, v94, v91
	v_pk_mul_f32 v[88:89], v[88:89], v[92:93]
	v_ldexp_f32 v84, v84, 1
	v_add_f32_e32 v85, 1.0, v133
	v_add_f32_e32 v91, -1.0, v85
	v_sub_f32_e32 v94, v91, v85
	v_add_f32_e32 v94, 1.0, v94
	v_sub_f32_e32 v91, v133, v91
	v_add_f32_e32 v94, v91, v94
	v_frexp_mant_f32_e32 v91, v85
	v_cvt_f64_f32_e32 v[100:101], v85
	v_cmp_gt_f32_e32 vcc, s26, v91
	v_frexp_exp_i32_f64_e32 v91, v[100:101]
	v_pk_add_f32 v[92:93], v[86:87], v[88:89]
	v_subbrev_co_u32_e32 v134, vcc, 0, v91, vcc
	v_sub_u32_e32 v99, 0, v134
	v_ldexp_f32 v91, v85, v99
	v_pk_add_f32 v[100:101], v[90:91], 1.0 op_sel_hi:[1,0]
	v_ldexp_f32 v99, v94, v99
	v_pk_add_f32 v[102:103], v[100:101], -1.0 op_sel_hi:[1,0]
	v_pk_add_f32 v[114:115], v[90:91], -1.0 op_sel_hi:[1,0]
	v_pk_add_f32 v[102:103], v[90:91], v[102:103] neg_lo:[0,1] neg_hi:[0,1]
	v_pk_add_f32 v[116:117], v[114:115], 1.0 op_sel_hi:[1,0]
	v_pk_add_f32 v[102:103], v[98:99], v[102:103]
	v_pk_add_f32 v[90:91], v[90:91], v[116:117] neg_lo:[0,1] neg_hi:[0,1]
	v_pk_add_f32 v[110:111], v[100:101], v[102:103]
	v_pk_add_f32 v[90:91], v[98:99], v[90:91]
	v_rcp_f32_e32 v112, v110
	v_rcp_f32_e32 v113, v111
	v_pk_add_f32 v[98:99], v[114:115], v[90:91]
	v_pk_add_f32 v[100:101], v[110:111], v[100:101] neg_lo:[0,1] neg_hi:[0,1]
	v_pk_add_f32 v[114:115], v[98:99], v[114:115] neg_lo:[0,1] neg_hi:[0,1]
	v_pk_add_f32 v[100:101], v[102:103], v[100:101] neg_lo:[0,1] neg_hi:[0,1]
	v_pk_mul_f32 v[102:103], v[98:99], v[112:113]
	v_pk_add_f32 v[90:91], v[90:91], v[114:115] neg_lo:[0,1] neg_hi:[0,1]
	v_pk_mul_f32 v[114:115], v[110:111], v[102:103]
	v_pk_add_f32 v[86:87], v[92:93], v[86:87] neg_lo:[0,1] neg_hi:[0,1]
	v_pk_fma_f32 v[116:117], v[102:103], v[110:111], v[114:115] neg_lo:[0,0,1] neg_hi:[0,0,1]
	v_pk_add_f32 v[86:87], v[88:89], v[86:87] neg_lo:[0,1] neg_hi:[0,1]
	v_pk_fma_f32 v[116:117], v[102:103], v[100:101], v[116:117]
	v_mov_b32_e32 v89, v87
	v_pk_add_f32 v[118:119], v[114:115], v[116:117]
	v_mov_b32_e32 v85, v95
	v_pk_add_f32 v[120:121], v[98:99], v[118:119] neg_lo:[0,1] neg_hi:[0,1]
	v_pk_add_f32 v[114:115], v[118:119], v[114:115] neg_lo:[0,1] neg_hi:[0,1]
	v_pk_add_f32 v[98:99], v[98:99], v[120:121] neg_lo:[0,1] neg_hi:[0,1]
	v_mov_b32_e32 v126, v92
	v_pk_add_f32 v[98:99], v[98:99], v[118:119] neg_lo:[0,1] neg_hi:[0,1]
	v_cmp_neq_f32_e32 vcc, s8, v83
	v_pk_add_f32 v[90:91], v[90:91], v[98:99]
	v_pk_add_f32 v[98:99], v[114:115], v[116:117] neg_lo:[0,1] neg_hi:[0,1]
	s_nop 0
	v_pk_add_f32 v[90:91], v[98:99], v[90:91]
	s_nop 0
	v_pk_add_f32 v[98:99], v[120:121], v[90:91]
	s_nop 0
	v_pk_mul_f32 v[114:115], v[112:113], v[98:99]
	s_nop 0
; __device__ __forceinline__ float softplusf(float x) { return fmaxf(x, 0.f) + log1pf(__expf(-fabsf(x))); }
; __device__ void phaseA_tile(const Params& p, int l, int mt, int nt, char* smem) {
;     ...
;                     const f32x4 v = acc[i][j];
;                     *(float4*)(p.dtb + (size_t)row * 32 + c) =
;                         make_float4(softplusf(v[0] + db.x), softplusf(v[1] + db.y), softplusf(v[2] + db.z), softplusf(v[3] + db.w));
	v_pk_mul_f32 v[116:117], v[110:111], v[114:115]
	s_nop 0
	v_pk_fma_f32 v[110:111], v[114:115], v[110:111], v[116:117] neg_lo:[0,0,1] neg_hi:[0,0,1]
	s_nop 0
	v_pk_fma_f32 v[100:101], v[114:115], v[100:101], v[110:111]
	v_pk_add_f32 v[110:111], v[120:121], v[98:99] neg_lo:[0,1] neg_hi:[0,1]
	s_nop 0
	v_pk_add_f32 v[90:91], v[90:91], v[110:111]
	v_pk_add_f32 v[110:111], v[116:117], v[100:101]
	s_nop 0
	v_pk_add_f32 v[118:119], v[98:99], v[110:111] neg_lo:[0,1] neg_hi:[0,1]
	v_pk_add_f32 v[116:117], v[110:111], v[116:117] neg_lo:[0,1] neg_hi:[0,1]
	v_pk_add_f32 v[98:99], v[98:99], v[118:119] neg_lo:[0,1] neg_hi:[0,1]
	s_nop 0
	v_pk_add_f32 v[98:99], v[98:99], v[110:111] neg_lo:[0,1] neg_hi:[0,1]
	s_nop 0
	v_pk_add_f32 v[90:91], v[90:91], v[98:99]
	v_pk_add_f32 v[98:99], v[116:117], v[100:101] neg_lo:[0,1] neg_hi:[0,1]
	s_nop 0
	v_pk_add_f32 v[90:91], v[98:99], v[90:91]
	v_pk_add_f32 v[98:99], v[102:103], v[114:115]
	v_pk_add_f32 v[90:91], v[118:119], v[90:91]
	v_pk_add_f32 v[100:101], v[98:99], v[102:103] neg_lo:[0,1] neg_hi:[0,1]
	v_pk_mul_f32 v[90:91], v[112:113], v[90:91]
	v_pk_add_f32 v[100:101], v[114:115], v[100:101] neg_lo:[0,1] neg_hi:[0,1]
	s_nop 0
	v_pk_add_f32 v[90:91], v[100:101], v[90:91]
	s_nop 0
	v_pk_add_f32 v[100:101], v[98:99], v[90:91]
	s_nop 0
	v_pk_mul_f32 v[102:103], v[100:101], v[100:101]
	v_pk_add_f32 v[98:99], v[100:101], v[98:99] neg_lo:[0,1] neg_hi:[0,1]
	v_pk_fma_f32 v[110:111], v[102:103], s[28:29], v[66:67] op_sel_hi:[1,0,0]
	v_pk_add_f32 v[90:91], v[90:91], v[98:99] neg_lo:[0,1] neg_hi:[0,1]
	v_ldexp_f32 v98, v100, 1
	v_pk_fma_f32 v[110:111], v[102:103], v[110:111], s[30:31] op_sel_hi:[1,1,0]
	v_ldexp_f32 v99, v101, 1
	v_pk_mul_f32 v[100:101], v[100:101], v[102:103]
	v_cvt_f32_i32_e32 v103, v122
	v_cvt_f32_i32_e32 v102, v97
	v_ldexp_f32 v113, v91, 1
	v_ldexp_f32 v90, v90, 1
	v_mov_b32_e32 v91, v113
	v_pk_mul_f32 v[114:115], v[102:103], s[12:13] op_sel_hi:[1,0]
	s_nop 0
	v_pk_fma_f32 v[116:117], v[102:103], s[12:13], v[114:115] op_sel_hi:[1,0,1] neg_lo:[0,0,1] neg_hi:[0,0,1]
	v_mov_b32_e32 v88, v114
	v_pk_fma_f32 v[102:103], v[102:103], s[14:15], v[116:117] op_sel_hi:[1,0,1]
	v_mov_b32_e32 v123, v115
	v_mov_b32_e32 v94, v102
	v_pk_add_f32 v[88:89], v[88:89], v[94:95]
	v_pk_add_f32 v[94:95], v[84:85], v[86:87]
	v_mov_b32_e32 v87, v93
	v_mov_b32_e32 v85, v95
	v_pk_add_f32 v[116:117], v[114:115], v[102:103]
	v_pk_add_f32 v[84:85], v[84:85], v[86:87]
	v_pk_add_f32 v[86:87], v[92:93], v[94:95]
	v_mov_b32_e32 v127, v117
	v_pk_add_f32 v[118:119], v[116:117], v[86:87]
	v_mov_b32_e32 v124, v86
	v_mov_b32_e32 v125, v119
	v_pk_add_f32 v[124:125], v[124:125], v[126:127] neg_lo:[0,1] neg_hi:[0,1]
	v_mov_b32_e32 v120, v118
	v_mov_b32_e32 v121, v117
	v_mov_b32_e32 v122, v116
	v_mov_b32_e32 v126, v116
	v_mov_b32_e32 v127, v119
	v_mov_b32_e32 v115, v125
	v_pk_add_f32 v[120:121], v[120:121], v[122:123] neg_lo:[0,1] neg_hi:[0,1]
	v_mov_b32_e32 v122, v86
	v_mov_b32_e32 v123, v103
	v_pk_add_f32 v[114:115], v[126:127], v[114:115] neg_lo:[0,1] neg_hi:[0,1]
	v_pk_add_f32 v[122:123], v[122:123], v[120:121] neg_lo:[0,1] neg_hi:[0,1]
	v_mov_b32_e32 v126, v114
	v_mov_b32_e32 v127, v121
	v_mov_b32_e32 v128, v118
	v_mov_b32_e32 v129, v87
	v_mov_b32_e32 v121, v93
	v_pk_add_f32 v[126:127], v[102:103], v[126:127] neg_lo:[0,1] neg_hi:[0,1]
	v_pk_add_f32 v[120:121], v[128:129], v[120:121] neg_lo:[0,1] neg_hi:[0,1]
	v_mov_b32_e32 v103, v117
	v_pk_add_f32 v[86:87], v[86:87], v[92:93] neg_lo:[0,1] neg_hi:[0,1]
	v_pk_add_f32 v[88:89], v[88:89], v[120:121] neg_lo:[0,1] neg_hi:[0,1]
	v_pk_add_f32 v[92:93], v[102:103], v[114:115] neg_lo:[0,1] neg_hi:[0,1]
	v_pk_add_f32 v[84:85], v[84:85], v[124:125] neg_lo:[0,1] neg_hi:[0,1]
	v_pk_add_f32 v[86:87], v[94:95], v[86:87] neg_lo:[0,1] neg_hi:[0,1]
	v_pk_add_f32 v[94:95], v[84:85], v[92:93]
	v_mov_b32_e32 v93, v123
	v_mov_b32_e32 v85, v89
	v_pk_add_f32 v[102:103], v[122:123], v[88:89]
	v_pk_add_f32 v[84:85], v[92:93], v[84:85]
	v_mov_b32_e32 v88, v94
	v_pk_add_f32 v[84:85], v[84:85], v[126:127] neg_lo:[0,1] neg_hi:[0,1]
	v_mov_b32_e32 v89, v103
	v_pk_add_f32 v[88:89], v[88:89], v[84:85] neg_lo:[0,1] neg_hi:[0,1]
	v_pk_add_f32 v[84:85], v[86:87], v[84:85] neg_lo:[0,1] neg_hi:[0,1]
	v_pk_add_f32 v[88:89], v[92:93], v[88:89] neg_lo:[0,1] neg_hi:[0,1]
	v_pk_add_f32 v[86:87], v[102:103], v[94:95]
	v_pk_add_f32 v[84:85], v[84:85], v[88:89]
	v_pk_add_f32 v[88:89], v[118:119], v[86:87]
	s_nop 0
	v_pk_add_f32 v[92:93], v[88:89], v[118:119] neg_lo:[0,1] neg_hi:[0,1]
	s_nop 0
	v_pk_add_f32 v[86:87], v[86:87], v[92:93] neg_lo:[0,1] neg_hi:[0,1]
	s_nop 0
	v_pk_add_f32 v[84:85], v[84:85], v[86:87]
	s_nop 0
	v_pk_add_f32 v[84:85], v[88:89], v[84:85]
	v_pk_mul_f32 v[88:89], v[100:101], v[110:111]
	v_cndmask_b32_e32 v84, v160, v84, vcc
	v_cmp_neq_f32_e32 vcc, s8, v130
	v_pk_add_f32 v[92:93], v[98:99], v[88:89]
	s_nop 0
	v_cndmask_b32_e32 v85, v160, v85, vcc
	v_cmp_ngt_f32_e32 vcc, -1.0, v130
	v_pk_add_f32 v[98:99], v[92:93], v[98:99] neg_lo:[0,1] neg_hi:[0,1]
	v_mov_b32_e32 v116, v92
	v_cndmask_b32_e32 v85, v161, v85, vcc
	v_cmp_ngt_f32_e32 vcc, -1.0, v83
	v_pk_add_f32 v[88:89], v[88:89], v[98:99] neg_lo:[0,1] neg_hi:[0,1]
	s_nop 0
	v_cndmask_b32_e32 v84, v161, v84, vcc
	v_cmp_neq_f32_e32 vcc, -1.0, v83
	v_pk_add_f32 v[100:101], v[90:91], v[88:89]
	v_mov_b32_e32 v99, v89
	v_cndmask_b32_e32 v84, v162, v84, vcc
	v_cmp_neq_f32_e32 vcc, -1.0, v130
	v_mov_b32_e32 v91, v101
	v_mov_b32_e32 v89, v93
	v_cndmask_b32_e32 v85, v162, v85, vcc
	v_cmp_lt_f32_e64 vcc, |v83|, s9
	v_cndmask_b32_e64 v85, v85, v130, s[0:1]
	v_pk_add_f32 v[88:89], v[90:91], v[88:89]
	v_cndmask_b32_e32 v84, v84, v83, vcc
	v_pk_add_f32 v[78:79], v[78:79], v[84:85]
; __device__ __forceinline__ float softplusf(float x) { return fmaxf(x, 0.f) + log1pf(__expf(-fabsf(x))); }
; __device__ void phaseA_tile(const Params& p, int l, int mt, int nt, char* smem) {
;     ...
;                     const float4 db = *(const float4*)(p.dt_bias + l * 32 + c);
;                     const f32x4 v = acc[i][j];
;                     *(float4*)(p.dtb + (size_t)row * 32 + c) =
;                         make_float4(softplusf(v[0] + db.x), softplusf(v[1] + db.y), softplusf(v[2] + db.z), softplusf(v[3] + db.w));
	v_cvt_f32_i32_e32 v85, v134
	v_cvt_f32_i32_e32 v84, v132
	v_pk_add_f32 v[90:91], v[92:93], v[100:101]
	v_cmp_neq_f32_e32 vcc, s8, v131
	v_mov_b32_e32 v114, v90
	v_pk_mul_f32 v[86:87], v[84:85], s[12:13] op_sel_hi:[1,0]
	v_mov_b32_e32 v119, v91
	v_pk_fma_f32 v[94:95], v[84:85], s[12:13], v[86:87] op_sel_hi:[1,0,1] neg_lo:[0,0,1] neg_hi:[0,0,1]
	v_mov_b32_e32 v98, v86
	v_pk_fma_f32 v[84:85], v[84:85], s[14:15], v[94:95] op_sel_hi:[1,0,1]
	v_cmp_lt_f32_e64 s[0:1], |v133|, s9
	v_pk_add_f32 v[94:95], v[86:87], v[84:85]
	v_mov_b32_e32 v112, v84
	v_pk_add_f32 v[102:103], v[94:95], v[90:91]
	v_mov_b32_e32 v117, v95
	v_mov_b32_e32 v115, v103
	v_pk_add_f32 v[114:115], v[114:115], v[116:117] neg_lo:[0,1] neg_hi:[0,1]
	v_pk_add_f32 v[98:99], v[98:99], v[112:113]
	v_mov_b32_e32 v110, v102
	v_mov_b32_e32 v111, v95
	v_mov_b32_e32 v112, v94
	v_mov_b32_e32 v113, v87
	v_mov_b32_e32 v116, v94
	v_mov_b32_e32 v117, v103
	v_mov_b32_e32 v87, v115
	v_pk_add_f32 v[110:111], v[110:111], v[112:113] neg_lo:[0,1] neg_hi:[0,1]
	v_mov_b32_e32 v112, v90
	v_mov_b32_e32 v113, v85
	v_pk_add_f32 v[86:87], v[116:117], v[86:87] neg_lo:[0,1] neg_hi:[0,1]
	v_pk_add_f32 v[112:113], v[112:113], v[110:111] neg_lo:[0,1] neg_hi:[0,1]
	v_mov_b32_e32 v116, v86
	v_mov_b32_e32 v117, v111
	v_mov_b32_e32 v118, v102
	v_mov_b32_e32 v111, v93
	v_pk_add_f32 v[116:117], v[84:85], v[116:117] neg_lo:[0,1] neg_hi:[0,1]
	v_pk_add_f32 v[110:111], v[118:119], v[110:111] neg_lo:[0,1] neg_hi:[0,1]
	v_mov_b32_e32 v85, v95
	v_pk_add_f32 v[90:91], v[90:91], v[92:93] neg_lo:[0,1] neg_hi:[0,1]
	v_pk_add_f32 v[92:93], v[98:99], v[110:111] neg_lo:[0,1] neg_hi:[0,1]
	v_pk_add_f32 v[84:85], v[84:85], v[86:87] neg_lo:[0,1] neg_hi:[0,1]
	v_pk_add_f32 v[86:87], v[88:89], v[114:115] neg_lo:[0,1] neg_hi:[0,1]
	v_pk_add_f32 v[94:95], v[112:113], v[92:93]
	v_pk_add_f32 v[88:89], v[86:87], v[84:85]
	v_mov_b32_e32 v85, v113
	v_mov_b32_e32 v87, v93
	v_pk_add_f32 v[86:87], v[84:85], v[86:87]
	v_mov_b32_e32 v92, v88
	v_pk_add_f32 v[86:87], v[86:87], v[116:117] neg_lo:[0,1] neg_hi:[0,1]
	v_mov_b32_e32 v93, v95
	v_pk_add_f32 v[90:91], v[100:101], v[90:91] neg_lo:[0,1] neg_hi:[0,1]
	v_pk_add_f32 v[92:93], v[92:93], v[86:87] neg_lo:[0,1] neg_hi:[0,1]
	v_pk_add_f32 v[86:87], v[90:91], v[86:87] neg_lo:[0,1] neg_hi:[0,1]
	v_pk_add_f32 v[84:85], v[84:85], v[92:93] neg_lo:[0,1] neg_hi:[0,1]
	s_nop 0
	v_pk_add_f32 v[84:85], v[86:87], v[84:85]
	v_pk_add_f32 v[86:87], v[94:95], v[88:89]
	s_nop 0
	v_pk_add_f32 v[88:89], v[102:103], v[86:87]
	s_nop 0
	v_pk_add_f32 v[90:91], v[88:89], v[102:103] neg_lo:[0,1] neg_hi:[0,1]
	s_nop 0
	v_pk_add_f32 v[86:87], v[86:87], v[90:91] neg_lo:[0,1] neg_hi:[0,1]
	s_nop 0
	v_pk_add_f32 v[84:85], v[84:85], v[86:87]
	s_nop 0
	v_pk_add_f32 v[84:85], v[88:89], v[84:85]
	s_nop 0
	v_cndmask_b32_e32 v83, v160, v84, vcc
	v_cmp_neq_f32_e32 vcc, s8, v133
	s_nop 1
	v_cndmask_b32_e32 v84, v160, v85, vcc
	v_cmp_ngt_f32_e32 vcc, -1.0, v133
	s_nop 1
	v_cndmask_b32_e32 v84, v161, v84, vcc
	v_cmp_ngt_f32_e32 vcc, -1.0, v131
	s_nop 1
	v_cndmask_b32_e32 v83, v161, v83, vcc
	v_cmp_neq_f32_e32 vcc, -1.0, v131
	s_nop 1
	v_cndmask_b32_e32 v83, v162, v83, vcc
	v_cmp_neq_f32_e32 vcc, -1.0, v133
	s_nop 1
	v_cndmask_b32_e32 v84, v162, v84, vcc
	v_cmp_lt_f32_e64 vcc, |v131|, s9
	v_cndmask_b32_e64 v85, v84, v133, s[0:1]
	s_nop 0
	v_cndmask_b32_e32 v84, v83, v131, vcc
	v_pk_add_f32 v[80:81], v[80:81], v[84:85]
	global_store_dwordx4 v[76:77], v[78:81], off
	global_load_dwordx4 v[78:81], v0, s[74:75] offset:64
	s_waitcnt vmcnt(0)
	v_add_f32_e32 v83, v26, v78
	v_max_f32_e32 v78, 0, v83
	v_mul_f32_e64 v83, |v83|, s2
	v_exp_f32_e32 v83, v83
	s_nop 0
	v_add_f32_e32 v86, 1.0, v83
	v_add_f32_e32 v84, -1.0, v86
	v_sub_f32_e32 v85, v84, v86
	v_add_f32_e32 v85, 1.0, v85
	v_sub_f32_e32 v84, v83, v84
	v_add_f32_e32 v87, v84, v85
	v_frexp_mant_f32_e32 v84, v86
	v_cmp_gt_f32_e32 vcc, s26, v84
	v_cvt_f64_f32_e32 v[84:85], v86
	v_frexp_exp_i32_f64_e32 v84, v[84:85]
	v_subbrev_co_u32_e32 v97, vcc, 0, v84, vcc
	v_sub_u32_e32 v85, 0, v97
	v_ldexp_f32 v84, v86, v85
	v_ldexp_f32 v86, v87, v85
	v_add_f32_e32 v85, v27, v79
	v_max_f32_e32 v79, 0, v85
	v_mul_f32_e64 v85, |v85|, s2
	v_exp_f32_e32 v130, v85
	s_nop 0
	v_add_f32_e32 v85, 1.0, v130
	v_add_f32_e32 v87, -1.0, v85
	v_sub_f32_e32 v88, v87, v85
	v_add_f32_e32 v88, 1.0, v88
	v_sub_f32_e32 v87, v130, v87
	v_add_f32_e32 v87, v87, v88
	v_frexp_mant_f32_e32 v88, v85
	v_cmp_gt_f32_e32 vcc, s26, v88
	v_cvt_f64_f32_e32 v[88:89], v85
	v_frexp_exp_i32_f64_e32 v88, v[88:89]
	v_subbrev_co_u32_e32 v122, vcc, 0, v88, vcc
	v_sub_u32_e32 v88, 0, v122
	v_ldexp_f32 v85, v85, v88
	v_ldexp_f32 v87, v87, v88
	v_pk_add_f32 v[88:89], v[84:85], 1.0 op_sel_hi:[1,0]
	v_pk_add_f32 v[98:99], v[84:85], -1.0 op_sel_hi:[1,0]
	v_pk_add_f32 v[90:91], v[88:89], -1.0 op_sel_hi:[1,0]
	v_pk_add_f32 v[100:101], v[98:99], 1.0 op_sel_hi:[1,0]
	v_pk_add_f32 v[90:91], v[84:85], v[90:91] neg_lo:[0,1] neg_hi:[0,1]
	v_pk_add_f32 v[84:85], v[84:85], v[100:101] neg_lo:[0,1] neg_hi:[0,1]
	v_pk_add_f32 v[90:91], v[86:87], v[90:91]
	v_pk_add_f32 v[84:85], v[86:87], v[84:85]
	v_pk_add_f32 v[92:93], v[88:89], v[90:91]
	v_pk_add_f32 v[86:87], v[98:99], v[84:85]
	v_rcp_f32_e32 v94, v92
	v_rcp_f32_e32 v95, v93
	v_pk_add_f32 v[88:89], v[92:93], v[88:89] neg_lo:[0,1] neg_hi:[0,1]
	v_pk_add_f32 v[98:99], v[86:87], v[98:99] neg_lo:[0,1] neg_hi:[0,1]
	v_pk_add_f32 v[88:89], v[90:91], v[88:89] neg_lo:[0,1] neg_hi:[0,1]
	v_pk_mul_f32 v[90:91], v[86:87], v[94:95]
	v_pk_add_f32 v[84:85], v[84:85], v[98:99] neg_lo:[0,1] neg_hi:[0,1]
	v_pk_mul_f32 v[98:99], v[92:93], v[90:91]
	v_cmp_lt_f32_e64 s[0:1], |v130|, s9
	v_pk_fma_f32 v[100:101], v[90:91], v[92:93], v[98:99] neg_lo:[0,0,1] neg_hi:[0,0,1]
; __device__ __forceinline__ float softplusf(float x) { return fmaxf(x, 0.f) + log1pf(__expf(-fabsf(x))); }
; __device__ void phaseA_tile(const Params& p, int l, int mt, int nt, char* smem) {
;     ...
;                     const f32x4 v = acc[i][j];
;                     *(float4*)(p.dtb + (size_t)row * 32 + c) =
;                         make_float4(softplusf(v[0] + db.x), softplusf(v[1] + db.y), softplusf(v[2] + db.z), softplusf(v[3] + db.w));
	s_nop 0
	v_pk_fma_f32 v[100:101], v[90:91], v[88:89], v[100:101]
	s_nop 0
	v_pk_add_f32 v[102:103], v[98:99], v[100:101]
	s_nop 0
	v_pk_add_f32 v[110:111], v[86:87], v[102:103] neg_lo:[0,1] neg_hi:[0,1]
	v_pk_add_f32 v[98:99], v[102:103], v[98:99] neg_lo:[0,1] neg_hi:[0,1]
	v_pk_add_f32 v[86:87], v[86:87], v[110:111] neg_lo:[0,1] neg_hi:[0,1]
	s_nop 0
	v_pk_add_f32 v[86:87], v[86:87], v[102:103] neg_lo:[0,1] neg_hi:[0,1]
	s_nop 0
	v_pk_add_f32 v[84:85], v[84:85], v[86:87]
	v_pk_add_f32 v[86:87], v[98:99], v[100:101] neg_lo:[0,1] neg_hi:[0,1]
	s_nop 0
	v_pk_add_f32 v[84:85], v[86:87], v[84:85]
	s_nop 0
	v_pk_add_f32 v[86:87], v[110:111], v[84:85]
	s_nop 0
	v_pk_mul_f32 v[98:99], v[94:95], v[86:87]
	s_nop 0
	v_pk_mul_f32 v[100:101], v[92:93], v[98:99]
	s_nop 0
	v_pk_fma_f32 v[92:93], v[98:99], v[92:93], v[100:101] neg_lo:[0,0,1] neg_hi:[0,0,1]
	s_nop 0
	v_pk_fma_f32 v[88:89], v[98:99], v[88:89], v[92:93]
	v_pk_add_f32 v[92:93], v[110:111], v[86:87] neg_lo:[0,1] neg_hi:[0,1]
	s_nop 0
	v_pk_add_f32 v[84:85], v[84:85], v[92:93]
	v_pk_add_f32 v[92:93], v[100:101], v[88:89]
	s_nop 0
	v_pk_add_f32 v[102:103], v[86:87], v[92:93] neg_lo:[0,1] neg_hi:[0,1]
	v_pk_add_f32 v[100:101], v[92:93], v[100:101] neg_lo:[0,1] neg_hi:[0,1]
	v_pk_add_f32 v[86:87], v[86:87], v[102:103] neg_lo:[0,1] neg_hi:[0,1]
	s_nop 0
	v_pk_add_f32 v[86:87], v[86:87], v[92:93] neg_lo:[0,1] neg_hi:[0,1]
	s_nop 0
	v_pk_add_f32 v[84:85], v[84:85], v[86:87]
	v_pk_add_f32 v[86:87], v[100:101], v[88:89] neg_lo:[0,1] neg_hi:[0,1]
	s_nop 0
	v_pk_add_f32 v[84:85], v[86:87], v[84:85]
	v_pk_add_f32 v[86:87], v[90:91], v[98:99]
	v_pk_add_f32 v[84:85], v[102:103], v[84:85]
	v_pk_add_f32 v[88:89], v[86:87], v[90:91] neg_lo:[0,1] neg_hi:[0,1]
	v_pk_mul_f32 v[84:85], v[94:95], v[84:85]
	v_pk_add_f32 v[88:89], v[98:99], v[88:89] neg_lo:[0,1] neg_hi:[0,1]
	s_nop 0
	v_pk_add_f32 v[84:85], v[88:89], v[84:85]
	s_nop 0
	v_pk_add_f32 v[88:89], v[86:87], v[84:85]
	s_nop 0
	v_pk_add_f32 v[86:87], v[88:89], v[86:87] neg_lo:[0,1] neg_hi:[0,1]
	v_pk_mul_f32 v[90:91], v[88:89], v[88:89]
	v_pk_add_f32 v[84:85], v[84:85], v[86:87] neg_lo:[0,1] neg_hi:[0,1]
	v_pk_fma_f32 v[92:93], v[90:91], s[28:29], v[66:67] op_sel_hi:[1,0,0]
	v_ldexp_f32 v95, v85, 1
	v_add_f32_e32 v85, v28, v80
	v_max_f32_e32 v80, 0, v85
	v_mul_f32_e64 v85, |v85|, s2
	v_exp_f32_e32 v131, v85
	v_ldexp_f32 v86, v88, 1
	v_pk_fma_f32 v[92:93], v[90:91], v[92:93], s[30:31] op_sel_hi:[1,1,0]
	v_ldexp_f32 v87, v89, 1
	v_add_f32_e32 v85, 1.0, v131
	v_pk_mul_f32 v[88:89], v[88:89], v[90:91]
	v_add_f32_e32 v90, -1.0, v85
	v_sub_f32_e32 v91, v90, v85
	v_add_f32_e32 v91, 1.0, v91
	v_sub_f32_e32 v90, v131, v90
	v_add_f32_e32 v94, v90, v91
	v_frexp_mant_f32_e32 v90, v85
	v_cmp_gt_f32_e32 vcc, s26, v90
	v_cvt_f64_f32_e32 v[90:91], v85
	v_frexp_exp_i32_f64_e32 v90, v[90:91]
	v_subbrev_co_u32_e32 v132, vcc, 0, v90, vcc
	v_sub_u32_e32 v91, 0, v132
	v_ldexp_f32 v90, v85, v91
	v_add_f32_e32 v85, v29, v81
	v_max_f32_e32 v81, 0, v85
	v_mul_f32_e64 v85, |v85|, s2
	v_exp_f32_e32 v133, v85
	v_ldexp_f32 v98, v94, v91
	v_pk_mul_f32 v[88:89], v[88:89], v[92:93]
	v_ldexp_f32 v84, v84, 1
	v_add_f32_e32 v85, 1.0, v133
	v_add_f32_e32 v91, -1.0, v85
	v_sub_f32_e32 v94, v91, v85
	v_add_f32_e32 v94, 1.0, v94
	v_sub_f32_e32 v91, v133, v91
	v_add_f32_e32 v94, v91, v94
	v_frexp_mant_f32_e32 v91, v85
	v_cvt_f64_f32_e32 v[100:101], v85
	v_cmp_gt_f32_e32 vcc, s26, v91
	v_frexp_exp_i32_f64_e32 v91, v[100:101]
	v_pk_add_f32 v[92:93], v[86:87], v[88:89]
	v_subbrev_co_u32_e32 v134, vcc, 0, v91, vcc
	v_sub_u32_e32 v99, 0, v134
	v_ldexp_f32 v91, v85, v99
	v_pk_add_f32 v[100:101], v[90:91], 1.0 op_sel_hi:[1,0]
	v_ldexp_f32 v99, v94, v99
	v_pk_add_f32 v[102:103], v[100:101], -1.0 op_sel_hi:[1,0]
	v_pk_add_f32 v[114:115], v[90:91], -1.0 op_sel_hi:[1,0]
	v_pk_add_f32 v[102:103], v[90:91], v[102:103] neg_lo:[0,1] neg_hi:[0,1]
	v_pk_add_f32 v[116:117], v[114:115], 1.0 op_sel_hi:[1,0]
	v_pk_add_f32 v[102:103], v[98:99], v[102:103]
	v_pk_add_f32 v[90:91], v[90:91], v[116:117] neg_lo:[0,1] neg_hi:[0,1]
	v_pk_add_f32 v[110:111], v[100:101], v[102:103]
	v_pk_add_f32 v[90:91], v[98:99], v[90:91]
	v_rcp_f32_e32 v112, v110
	v_rcp_f32_e32 v113, v111
	v_pk_add_f32 v[98:99], v[114:115], v[90:91]
	v_pk_add_f32 v[100:101], v[110:111], v[100:101] neg_lo:[0,1] neg_hi:[0,1]
	v_pk_add_f32 v[114:115], v[98:99], v[114:115] neg_lo:[0,1] neg_hi:[0,1]
	v_pk_add_f32 v[100:101], v[102:103], v[100:101] neg_lo:[0,1] neg_hi:[0,1]
	v_pk_mul_f32 v[102:103], v[98:99], v[112:113]
	v_pk_add_f32 v[90:91], v[90:91], v[114:115] neg_lo:[0,1] neg_hi:[0,1]
	v_pk_mul_f32 v[114:115], v[110:111], v[102:103]
	v_pk_add_f32 v[86:87], v[92:93], v[86:87] neg_lo:[0,1] neg_hi:[0,1]
	v_pk_fma_f32 v[116:117], v[102:103], v[110:111], v[114:115] neg_lo:[0,0,1] neg_hi:[0,0,1]
	v_pk_add_f32 v[86:87], v[88:89], v[86:87] neg_lo:[0,1] neg_hi:[0,1]
	v_pk_fma_f32 v[116:117], v[102:103], v[100:101], v[116:117]
	v_mov_b32_e32 v89, v87
	v_pk_add_f32 v[118:119], v[114:115], v[116:117]
	v_mov_b32_e32 v85, v95
	v_pk_add_f32 v[120:121], v[98:99], v[118:119] neg_lo:[0,1] neg_hi:[0,1]
	v_pk_add_f32 v[114:115], v[118:119], v[114:115] neg_lo:[0,1] neg_hi:[0,1]
	v_pk_add_f32 v[98:99], v[98:99], v[120:121] neg_lo:[0,1] neg_hi:[0,1]
	v_mov_b32_e32 v126, v92
	v_pk_add_f32 v[98:99], v[98:99], v[118:119] neg_lo:[0,1] neg_hi:[0,1]
	v_cmp_neq_f32_e32 vcc, s8, v83
	v_pk_add_f32 v[90:91], v[90:91], v[98:99]
	v_pk_add_f32 v[98:99], v[114:115], v[116:117] neg_lo:[0,1] neg_hi:[0,1]
	s_nop 0
	v_pk_add_f32 v[90:91], v[98:99], v[90:91]
	s_nop 0
	v_pk_add_f32 v[98:99], v[120:121], v[90:91]
	s_nop 0
	v_pk_mul_f32 v[114:115], v[112:113], v[98:99]
	s_nop 0
; __device__ __forceinline__ float softplusf(float x) { return fmaxf(x, 0.f) + log1pf(__expf(-fabsf(x))); }
; __device__ void phaseA_tile(const Params& p, int l, int mt, int nt, char* smem) {
;     ...
;                     const f32x4 v = acc[i][j];
;                     *(float4*)(p.dtb + (size_t)row * 32 + c) =
;                         make_float4(softplusf(v[0] + db.x), softplusf(v[1] + db.y), softplusf(v[2] + db.z), softplusf(v[3] + db.w));
	v_pk_mul_f32 v[116:117], v[110:111], v[114:115]
	s_nop 0
	v_pk_fma_f32 v[110:111], v[114:115], v[110:111], v[116:117] neg_lo:[0,0,1] neg_hi:[0,0,1]
	s_nop 0
	v_pk_fma_f32 v[100:101], v[114:115], v[100:101], v[110:111]
	v_pk_add_f32 v[110:111], v[120:121], v[98:99] neg_lo:[0,1] neg_hi:[0,1]
	s_nop 0
	v_pk_add_f32 v[90:91], v[90:91], v[110:111]
	v_pk_add_f32 v[110:111], v[116:117], v[100:101]
	s_nop 0
	v_pk_add_f32 v[118:119], v[98:99], v[110:111] neg_lo:[0,1] neg_hi:[0,1]
	v_pk_add_f32 v[116:117], v[110:111], v[116:117] neg_lo:[0,1] neg_hi:[0,1]
	v_pk_add_f32 v[98:99], v[98:99], v[118:119] neg_lo:[0,1] neg_hi:[0,1]
	s_nop 0
	v_pk_add_f32 v[98:99], v[98:99], v[110:111] neg_lo:[0,1] neg_hi:[0,1]
	s_nop 0
	v_pk_add_f32 v[90:91], v[90:91], v[98:99]
	v_pk_add_f32 v[98:99], v[116:117], v[100:101] neg_lo:[0,1] neg_hi:[0,1]
	s_nop 0
	v_pk_add_f32 v[90:91], v[98:99], v[90:91]
	v_pk_add_f32 v[98:99], v[102:103], v[114:115]
	v_pk_add_f32 v[90:91], v[118:119], v[90:91]
	v_pk_add_f32 v[100:101], v[98:99], v[102:103] neg_lo:[0,1] neg_hi:[0,1]
	v_pk_mul_f32 v[90:91], v[112:113], v[90:91]
	v_pk_add_f32 v[100:101], v[114:115], v[100:101] neg_lo:[0,1] neg_hi:[0,1]
	s_nop 0
	v_pk_add_f32 v[90:91], v[100:101], v[90:91]
	s_nop 0
	v_pk_add_f32 v[100:101], v[98:99], v[90:91]
	s_nop 0
	v_pk_mul_f32 v[102:103], v[100:101], v[100:101]
	v_pk_add_f32 v[98:99], v[100:101], v[98:99] neg_lo:[0,1] neg_hi:[0,1]
	v_pk_fma_f32 v[110:111], v[102:103], s[28:29], v[66:67] op_sel_hi:[1,0,0]
	v_pk_add_f32 v[90:91], v[90:91], v[98:99] neg_lo:[0,1] neg_hi:[0,1]
	v_ldexp_f32 v98, v100, 1
	v_pk_fma_f32 v[110:111], v[102:103], v[110:111], s[30:31] op_sel_hi:[1,1,0]
	v_ldexp_f32 v99, v101, 1
	v_pk_mul_f32 v[100:101], v[100:101], v[102:103]
	v_cvt_f32_i32_e32 v103, v122
	v_cvt_f32_i32_e32 v102, v97
	v_ldexp_f32 v113, v91, 1
	v_ldexp_f32 v90, v90, 1
	v_mov_b32_e32 v91, v113
	v_pk_mul_f32 v[114:115], v[102:103], s[12:13] op_sel_hi:[1,0]
	s_nop 0
	v_pk_fma_f32 v[116:117], v[102:103], s[12:13], v[114:115] op_sel_hi:[1,0,1] neg_lo:[0,0,1] neg_hi:[0,0,1]
	v_mov_b32_e32 v88, v114
	v_pk_fma_f32 v[102:103], v[102:103], s[14:15], v[116:117] op_sel_hi:[1,0,1]
	v_mov_b32_e32 v123, v115
	v_mov_b32_e32 v94, v102
	v_pk_add_f32 v[88:89], v[88:89], v[94:95]
	v_pk_add_f32 v[94:95], v[84:85], v[86:87]
	v_mov_b32_e32 v87, v93
	v_mov_b32_e32 v85, v95
	v_pk_add_f32 v[116:117], v[114:115], v[102:103]
	v_pk_add_f32 v[84:85], v[84:85], v[86:87]
	v_pk_add_f32 v[86:87], v[92:93], v[94:95]
	v_mov_b32_e32 v127, v117
	v_pk_add_f32 v[118:119], v[116:117], v[86:87]
	v_mov_b32_e32 v124, v86
	v_mov_b32_e32 v125, v119
	v_pk_add_f32 v[124:125], v[124:125], v[126:127] neg_lo:[0,1] neg_hi:[0,1]
	v_mov_b32_e32 v120, v118
	v_mov_b32_e32 v121, v117
	v_mov_b32_e32 v122, v116
	v_mov_b32_e32 v126, v116
	v_mov_b32_e32 v127, v119
	v_mov_b32_e32 v115, v125
	v_pk_add_f32 v[120:121], v[120:121], v[122:123] neg_lo:[0,1] neg_hi:[0,1]
	v_mov_b32_e32 v122, v86
	v_mov_b32_e32 v123, v103
	v_pk_add_f32 v[114:115], v[126:127], v[114:115] neg_lo:[0,1] neg_hi:[0,1]
	v_pk_add_f32 v[122:123], v[122:123], v[120:121] neg_lo:[0,1] neg_hi:[0,1]
	v_mov_b32_e32 v126, v114
	v_mov_b32_e32 v127, v121
	v_mov_b32_e32 v128, v118
	v_mov_b32_e32 v129, v87
	v_mov_b32_e32 v121, v93
	v_pk_add_f32 v[126:127], v[102:103], v[126:127] neg_lo:[0,1] neg_hi:[0,1]
	v_pk_add_f32 v[120:121], v[128:129], v[120:121] neg_lo:[0,1] neg_hi:[0,1]
	v_mov_b32_e32 v103, v117
	v_pk_add_f32 v[86:87], v[86:87], v[92:93] neg_lo:[0,1] neg_hi:[0,1]
	v_pk_add_f32 v[88:89], v[88:89], v[120:121] neg_lo:[0,1] neg_hi:[0,1]
	v_pk_add_f32 v[92:93], v[102:103], v[114:115] neg_lo:[0,1] neg_hi:[0,1]
	v_pk_add_f32 v[84:85], v[84:85], v[124:125] neg_lo:[0,1] neg_hi:[0,1]
	v_pk_add_f32 v[86:87], v[94:95], v[86:87] neg_lo:[0,1] neg_hi:[0,1]
	v_pk_add_f32 v[94:95], v[84:85], v[92:93]
	v_mov_b32_e32 v93, v123
	v_mov_b32_e32 v85, v89
	v_pk_add_f32 v[102:103], v[122:123], v[88:89]
	v_pk_add_f32 v[84:85], v[92:93], v[84:85]
	v_mov_b32_e32 v88, v94
	v_pk_add_f32 v[84:85], v[84:85], v[126:127] neg_lo:[0,1] neg_hi:[0,1]
	v_mov_b32_e32 v89, v103
	v_pk_add_f32 v[88:89], v[88:89], v[84:85] neg_lo:[0,1] neg_hi:[0,1]
	v_pk_add_f32 v[84:85], v[86:87], v[84:85] neg_lo:[0,1] neg_hi:[0,1]
	v_pk_add_f32 v[88:89], v[92:93], v[88:89] neg_lo:[0,1] neg_hi:[0,1]
	v_pk_add_f32 v[86:87], v[102:103], v[94:95]
	v_pk_add_f32 v[84:85], v[84:85], v[88:89]
	v_pk_add_f32 v[88:89], v[118:119], v[86:87]
	s_nop 0
	v_pk_add_f32 v[92:93], v[88:89], v[118:119] neg_lo:[0,1] neg_hi:[0,1]
	s_nop 0
	v_pk_add_f32 v[86:87], v[86:87], v[92:93] neg_lo:[0,1] neg_hi:[0,1]
	s_nop 0
	v_pk_add_f32 v[84:85], v[84:85], v[86:87]
	s_nop 0
	v_pk_add_f32 v[84:85], v[88:89], v[84:85]
	v_pk_mul_f32 v[88:89], v[100:101], v[110:111]
	v_cndmask_b32_e32 v84, v160, v84, vcc
	v_cmp_neq_f32_e32 vcc, s8, v130
	v_pk_add_f32 v[92:93], v[98:99], v[88:89]
	s_nop 0
	v_cndmask_b32_e32 v85, v160, v85, vcc
	v_cmp_ngt_f32_e32 vcc, -1.0, v130
	v_pk_add_f32 v[98:99], v[92:93], v[98:99] neg_lo:[0,1] neg_hi:[0,1]
	v_mov_b32_e32 v116, v92
	v_cndmask_b32_e32 v85, v161, v85, vcc
	v_cmp_ngt_f32_e32 vcc, -1.0, v83
	v_pk_add_f32 v[88:89], v[88:89], v[98:99] neg_lo:[0,1] neg_hi:[0,1]
	s_nop 0
	v_cndmask_b32_e32 v84, v161, v84, vcc
	v_cmp_neq_f32_e32 vcc, -1.0, v83
	v_pk_add_f32 v[100:101], v[90:91], v[88:89]
	v_mov_b32_e32 v99, v89
	v_cndmask_b32_e32 v84, v162, v84, vcc
	v_cmp_neq_f32_e32 vcc, -1.0, v130
	v_mov_b32_e32 v91, v101
	v_mov_b32_e32 v89, v93
	v_cndmask_b32_e32 v85, v162, v85, vcc
	v_cmp_lt_f32_e64 vcc, |v83|, s9
	v_cndmask_b32_e64 v85, v85, v130, s[0:1]
	v_pk_add_f32 v[88:89], v[90:91], v[88:89]
	v_cndmask_b32_e32 v84, v84, v83, vcc
	v_pk_add_f32 v[78:79], v[78:79], v[84:85]
; __device__ __forceinline__ float softplusf(float x) { return fmaxf(x, 0.f) + log1pf(__expf(-fabsf(x))); }
; __device__ __forceinline__ float logsigf(float x) { return fminf(x, 0.f) - log1pf(__expf(-fabsf(x))); }
; __device__ void phaseA_tile(const Params& p, int l, int mt, int nt, char* smem) {
;     ...
;                     *(float4*)(p.dtb + (size_t)row * 32 + c) =
;                         make_float4(softplusf(v[0] + db.x), softplusf(v[1] + db.y), softplusf(v[2] + db.z), softplusf(v[3] + db.w));
;                 }
;                 {
;                     const int c = g4 * 4;
;                     const float4 fb = *(const float4*)(p.b_f + l * 16 + c);
;                     const f32x4 v = acc[i][2];
;                     float4 lf = make_float4(logsigf(v[0] + fb.x), logsigf(v[1] + fb.y), logsigf(v[2] + fb.z), logsigf(v[3] + fb.w));
	v_cvt_f32_i32_e32 v85, v134
	v_cvt_f32_i32_e32 v84, v132
	v_pk_add_f32 v[90:91], v[92:93], v[100:101]
	v_cmp_neq_f32_e32 vcc, s8, v131
	v_mov_b32_e32 v114, v90
	v_pk_mul_f32 v[86:87], v[84:85], s[12:13] op_sel_hi:[1,0]
	v_mov_b32_e32 v119, v91
	v_pk_fma_f32 v[94:95], v[84:85], s[12:13], v[86:87] op_sel_hi:[1,0,1] neg_lo:[0,0,1] neg_hi:[0,0,1]
	v_mov_b32_e32 v98, v86
	v_pk_fma_f32 v[84:85], v[84:85], s[14:15], v[94:95] op_sel_hi:[1,0,1]
	v_cmp_lt_f32_e64 s[0:1], |v133|, s9
	v_pk_add_f32 v[94:95], v[86:87], v[84:85]
	v_mov_b32_e32 v112, v84
	v_pk_add_f32 v[102:103], v[94:95], v[90:91]
	v_mov_b32_e32 v117, v95
	v_mov_b32_e32 v115, v103
	v_pk_add_f32 v[114:115], v[114:115], v[116:117] neg_lo:[0,1] neg_hi:[0,1]
	v_pk_add_f32 v[98:99], v[98:99], v[112:113]
	v_mov_b32_e32 v110, v102
	v_mov_b32_e32 v111, v95
	v_mov_b32_e32 v112, v94
	v_mov_b32_e32 v113, v87
	v_mov_b32_e32 v116, v94
	v_mov_b32_e32 v117, v103
	v_mov_b32_e32 v87, v115
	v_pk_add_f32 v[110:111], v[110:111], v[112:113] neg_lo:[0,1] neg_hi:[0,1]
	v_mov_b32_e32 v112, v90
	v_mov_b32_e32 v113, v85
	v_pk_add_f32 v[86:87], v[116:117], v[86:87] neg_lo:[0,1] neg_hi:[0,1]
	v_pk_add_f32 v[112:113], v[112:113], v[110:111] neg_lo:[0,1] neg_hi:[0,1]
	v_mov_b32_e32 v116, v86
	v_mov_b32_e32 v117, v111
	v_mov_b32_e32 v118, v102
	v_mov_b32_e32 v111, v93
	v_pk_add_f32 v[116:117], v[84:85], v[116:117] neg_lo:[0,1] neg_hi:[0,1]
	v_pk_add_f32 v[110:111], v[118:119], v[110:111] neg_lo:[0,1] neg_hi:[0,1]
	v_mov_b32_e32 v85, v95
	v_pk_add_f32 v[90:91], v[90:91], v[92:93] neg_lo:[0,1] neg_hi:[0,1]
	v_pk_add_f32 v[92:93], v[98:99], v[110:111] neg_lo:[0,1] neg_hi:[0,1]
	v_pk_add_f32 v[84:85], v[84:85], v[86:87] neg_lo:[0,1] neg_hi:[0,1]
	v_pk_add_f32 v[86:87], v[88:89], v[114:115] neg_lo:[0,1] neg_hi:[0,1]
	v_pk_add_f32 v[94:95], v[112:113], v[92:93]
	v_pk_add_f32 v[88:89], v[86:87], v[84:85]
	v_mov_b32_e32 v85, v113
	v_mov_b32_e32 v87, v93
	v_pk_add_f32 v[86:87], v[84:85], v[86:87]
	v_mov_b32_e32 v92, v88
	v_pk_add_f32 v[86:87], v[86:87], v[116:117] neg_lo:[0,1] neg_hi:[0,1]
	v_mov_b32_e32 v93, v95
	v_pk_add_f32 v[90:91], v[100:101], v[90:91] neg_lo:[0,1] neg_hi:[0,1]
	v_pk_add_f32 v[92:93], v[92:93], v[86:87] neg_lo:[0,1] neg_hi:[0,1]
	v_pk_add_f32 v[86:87], v[90:91], v[86:87] neg_lo:[0,1] neg_hi:[0,1]
	v_pk_add_f32 v[84:85], v[84:85], v[92:93] neg_lo:[0,1] neg_hi:[0,1]
	s_nop 0
	v_pk_add_f32 v[84:85], v[86:87], v[84:85]
	v_pk_add_f32 v[86:87], v[94:95], v[88:89]
	s_nop 0
	v_pk_add_f32 v[88:89], v[102:103], v[86:87]
	s_nop 0
	v_pk_add_f32 v[90:91], v[88:89], v[102:103] neg_lo:[0,1] neg_hi:[0,1]
	s_nop 0
	v_pk_add_f32 v[86:87], v[86:87], v[90:91] neg_lo:[0,1] neg_hi:[0,1]
	s_nop 0
	v_pk_add_f32 v[84:85], v[84:85], v[86:87]
	s_nop 0
	v_pk_add_f32 v[84:85], v[88:89], v[84:85]
	s_nop 0
	v_cndmask_b32_e32 v83, v160, v84, vcc
	v_cmp_neq_f32_e32 vcc, s8, v133
	s_nop 1
	v_cndmask_b32_e32 v84, v160, v85, vcc
	v_cmp_ngt_f32_e32 vcc, -1.0, v133
	s_nop 1
	v_cndmask_b32_e32 v84, v161, v84, vcc
	v_cmp_ngt_f32_e32 vcc, -1.0, v131
	s_nop 1
	v_cndmask_b32_e32 v83, v161, v83, vcc
	v_cmp_neq_f32_e32 vcc, -1.0, v131
	s_nop 1
	v_cndmask_b32_e32 v83, v162, v83, vcc
	v_cmp_neq_f32_e32 vcc, -1.0, v133
	s_nop 1
	v_cndmask_b32_e32 v84, v162, v84, vcc
	v_cmp_lt_f32_e64 vcc, |v131|, s9
	v_cndmask_b32_e64 v85, v84, v133, s[0:1]
	s_nop 0
	v_cndmask_b32_e32 v84, v83, v131, vcc
	v_pk_add_f32 v[80:81], v[80:81], v[84:85]
	global_store_dwordx4 v[76:77], v[78:81], off offset:64
	global_load_dwordx4 v[76:79], v0, s[78:79]
	s_waitcnt vmcnt(0)
	v_add_f32_e32 v80, v22, v76
	v_min_f32_e32 v76, 0, v80
	v_mul_f32_e64 v80, |v80|, s2
	v_exp_f32_e32 v83, v80
	s_nop 0
	v_add_f32_e32 v84, 1.0, v83
	v_add_f32_e32 v80, -1.0, v84
	v_sub_f32_e32 v81, v80, v84
	v_add_f32_e32 v81, 1.0, v81
	v_sub_f32_e32 v80, v83, v80
	v_add_f32_e32 v85, v80, v81
	v_frexp_mant_f32_e32 v80, v84
	v_cmp_gt_f32_e32 vcc, s26, v80
	v_cvt_f64_f32_e32 v[80:81], v84
	v_frexp_exp_i32_f64_e32 v80, v[80:81]
	v_subbrev_co_u32_e32 v97, vcc, 0, v80, vcc
	v_sub_u32_e32 v81, 0, v97
	v_ldexp_f32 v80, v84, v81
	v_ldexp_f32 v84, v85, v81
	v_add_f32_e32 v81, v23, v77
	v_min_f32_e32 v77, 0, v81
	v_mul_f32_e64 v81, |v81|, s2
	v_exp_f32_e32 v128, v81
	s_nop 0
	v_add_f32_e32 v81, 1.0, v128
	v_add_f32_e32 v85, -1.0, v81
	v_sub_f32_e32 v86, v85, v81
	v_add_f32_e32 v86, 1.0, v86
	v_sub_f32_e32 v85, v128, v85
	v_add_f32_e32 v85, v85, v86
	v_frexp_mant_f32_e32 v86, v81
	v_cmp_gt_f32_e32 vcc, s26, v86
	v_cvt_f64_f32_e32 v[86:87], v81
	v_frexp_exp_i32_f64_e32 v86, v[86:87]
	v_subbrev_co_u32_e32 v120, vcc, 0, v86, vcc
	v_sub_u32_e32 v86, 0, v120
	v_ldexp_f32 v81, v81, v86
	v_ldexp_f32 v85, v85, v86
	v_pk_add_f32 v[86:87], v[80:81], 1.0 op_sel_hi:[1,0]
	v_pk_add_f32 v[94:95], v[80:81], -1.0 op_sel_hi:[1,0]
	v_pk_add_f32 v[88:89], v[86:87], -1.0 op_sel_hi:[1,0]
	v_pk_add_f32 v[98:99], v[94:95], 1.0 op_sel_hi:[1,0]
	v_pk_add_f32 v[88:89], v[80:81], v[88:89] neg_lo:[0,1] neg_hi:[0,1]
	v_pk_add_f32 v[80:81], v[80:81], v[98:99] neg_lo:[0,1] neg_hi:[0,1]
	v_pk_add_f32 v[88:89], v[84:85], v[88:89]
	v_pk_add_f32 v[80:81], v[84:85], v[80:81]
	v_pk_add_f32 v[90:91], v[86:87], v[88:89]
	v_pk_add_f32 v[84:85], v[94:95], v[80:81]
	v_rcp_f32_e32 v92, v90
	v_rcp_f32_e32 v93, v91
	v_pk_add_f32 v[86:87], v[90:91], v[86:87] neg_lo:[0,1] neg_hi:[0,1]
	v_pk_add_f32 v[94:95], v[84:85], v[94:95] neg_lo:[0,1] neg_hi:[0,1]
	v_pk_add_f32 v[86:87], v[88:89], v[86:87] neg_lo:[0,1] neg_hi:[0,1]
	v_pk_mul_f32 v[88:89], v[84:85], v[92:93]
	v_pk_add_f32 v[80:81], v[80:81], v[94:95] neg_lo:[0,1] neg_hi:[0,1]
	v_pk_mul_f32 v[94:95], v[90:91], v[88:89]
	v_cmp_lt_f32_e64 s[0:1], |v128|, s9
	v_pk_fma_f32 v[98:99], v[88:89], v[90:91], v[94:95] neg_lo:[0,0,1] neg_hi:[0,0,1]
; __device__ __forceinline__ float logsigf(float x) { return fminf(x, 0.f) - log1pf(__expf(-fabsf(x))); }
; __device__ void phaseA_tile(const Params& p, int l, int mt, int nt, char* smem) {
;     ...
;                     const float4 fb = *(const float4*)(p.b_f + l * 16 + c);
;                     const f32x4 v = acc[i][2];
;                     float4 lf = make_float4(logsigf(v[0] + fb.x), logsigf(v[1] + fb.y), logsigf(v[2] + fb.z), logsigf(v[3] + fb.w));
;                     float* o = samp ? (p.out + O_LFS + ((size_t)l * TSM + (row - TP)) * 16 + c)
	s_nop 0
	v_pk_fma_f32 v[98:99], v[88:89], v[86:87], v[98:99]
	s_nop 0
	v_pk_add_f32 v[100:101], v[94:95], v[98:99]
	s_nop 0
	v_pk_add_f32 v[102:103], v[84:85], v[100:101] neg_lo:[0,1] neg_hi:[0,1]
	v_pk_add_f32 v[94:95], v[100:101], v[94:95] neg_lo:[0,1] neg_hi:[0,1]
	v_pk_add_f32 v[84:85], v[84:85], v[102:103] neg_lo:[0,1] neg_hi:[0,1]
	s_nop 0
	v_pk_add_f32 v[84:85], v[84:85], v[100:101] neg_lo:[0,1] neg_hi:[0,1]
	s_nop 0
	v_pk_add_f32 v[80:81], v[80:81], v[84:85]
	v_pk_add_f32 v[84:85], v[94:95], v[98:99] neg_lo:[0,1] neg_hi:[0,1]
	s_nop 0
	v_pk_add_f32 v[80:81], v[84:85], v[80:81]
	s_nop 0
	v_pk_add_f32 v[84:85], v[102:103], v[80:81]
	s_nop 0
	v_pk_mul_f32 v[94:95], v[92:93], v[84:85]
	s_nop 0
	v_pk_mul_f32 v[98:99], v[90:91], v[94:95]
	s_nop 0
	v_pk_fma_f32 v[90:91], v[94:95], v[90:91], v[98:99] neg_lo:[0,0,1] neg_hi:[0,0,1]
	s_nop 0
	v_pk_fma_f32 v[86:87], v[94:95], v[86:87], v[90:91]
	v_pk_add_f32 v[90:91], v[102:103], v[84:85] neg_lo:[0,1] neg_hi:[0,1]
	s_nop 0
	v_pk_add_f32 v[80:81], v[80:81], v[90:91]
	v_pk_add_f32 v[90:91], v[98:99], v[86:87]
	s_nop 0
	v_pk_add_f32 v[100:101], v[84:85], v[90:91] neg_lo:[0,1] neg_hi:[0,1]
	v_pk_add_f32 v[98:99], v[90:91], v[98:99] neg_lo:[0,1] neg_hi:[0,1]
	v_pk_add_f32 v[84:85], v[84:85], v[100:101] neg_lo:[0,1] neg_hi:[0,1]
	s_nop 0
	v_pk_add_f32 v[84:85], v[84:85], v[90:91] neg_lo:[0,1] neg_hi:[0,1]
	s_nop 0
	v_pk_add_f32 v[80:81], v[80:81], v[84:85]
	v_pk_add_f32 v[84:85], v[98:99], v[86:87] neg_lo:[0,1] neg_hi:[0,1]
	s_nop 0
	v_pk_add_f32 v[80:81], v[84:85], v[80:81]
	v_pk_add_f32 v[84:85], v[88:89], v[94:95]
	v_pk_add_f32 v[80:81], v[100:101], v[80:81]
	v_pk_add_f32 v[86:87], v[84:85], v[88:89] neg_lo:[0,1] neg_hi:[0,1]
	v_pk_mul_f32 v[80:81], v[92:93], v[80:81]
	v_pk_add_f32 v[86:87], v[94:95], v[86:87] neg_lo:[0,1] neg_hi:[0,1]
	s_nop 0
	v_pk_add_f32 v[80:81], v[86:87], v[80:81]
	s_nop 0
	v_pk_add_f32 v[86:87], v[84:85], v[80:81]
	s_nop 0
	v_pk_add_f32 v[84:85], v[86:87], v[84:85] neg_lo:[0,1] neg_hi:[0,1]
	v_pk_mul_f32 v[88:89], v[86:87], v[86:87]
	v_pk_add_f32 v[80:81], v[80:81], v[84:85] neg_lo:[0,1] neg_hi:[0,1]
	v_pk_fma_f32 v[90:91], v[88:89], s[28:29], v[66:67] op_sel_hi:[1,0,0]
	v_ldexp_f32 v93, v81, 1
	v_add_f32_e32 v81, v24, v78
	v_min_f32_e32 v78, 0, v81
	v_mul_f32_e64 v81, |v81|, s2
	v_exp_f32_e32 v129, v81
	v_ldexp_f32 v84, v86, 1
	v_pk_fma_f32 v[90:91], v[88:89], v[90:91], s[30:31] op_sel_hi:[1,1,0]
	v_ldexp_f32 v85, v87, 1
	v_add_f32_e32 v81, 1.0, v129
	v_pk_mul_f32 v[86:87], v[86:87], v[88:89]
	v_add_f32_e32 v88, -1.0, v81
	v_sub_f32_e32 v89, v88, v81
	v_add_f32_e32 v89, 1.0, v89
	v_sub_f32_e32 v88, v129, v88
	v_add_f32_e32 v92, v88, v89
	v_frexp_mant_f32_e32 v88, v81
	v_cmp_gt_f32_e32 vcc, s26, v88
	v_cvt_f64_f32_e32 v[88:89], v81
	v_frexp_exp_i32_f64_e32 v88, v[88:89]
	v_subbrev_co_u32_e32 v130, vcc, 0, v88, vcc
	v_sub_u32_e32 v89, 0, v130
	v_ldexp_f32 v88, v81, v89
	v_add_f32_e32 v81, v25, v79
	v_min_f32_e32 v79, 0, v81
	v_mul_f32_e64 v81, |v81|, s2
	v_exp_f32_e32 v131, v81
	v_ldexp_f32 v94, v92, v89
	v_pk_mul_f32 v[86:87], v[86:87], v[90:91]
	v_ldexp_f32 v80, v80, 1
	v_add_f32_e32 v81, 1.0, v131
	v_add_f32_e32 v89, -1.0, v81
	v_sub_f32_e32 v92, v89, v81
	v_add_f32_e32 v92, 1.0, v92
	v_sub_f32_e32 v89, v131, v89
	v_add_f32_e32 v92, v89, v92
	v_frexp_mant_f32_e32 v89, v81
	v_cvt_f64_f32_e32 v[98:99], v81
	v_cmp_gt_f32_e32 vcc, s26, v89
	v_frexp_exp_i32_f64_e32 v89, v[98:99]
	v_pk_add_f32 v[90:91], v[84:85], v[86:87]
	v_subbrev_co_u32_e32 v132, vcc, 0, v89, vcc
	v_sub_u32_e32 v95, 0, v132
	v_ldexp_f32 v89, v81, v95
	v_pk_add_f32 v[98:99], v[88:89], 1.0 op_sel_hi:[1,0]
	v_ldexp_f32 v95, v92, v95
	v_pk_add_f32 v[100:101], v[98:99], -1.0 op_sel_hi:[1,0]
	v_pk_add_f32 v[112:113], v[88:89], -1.0 op_sel_hi:[1,0]
	v_pk_add_f32 v[100:101], v[88:89], v[100:101] neg_lo:[0,1] neg_hi:[0,1]
	v_pk_add_f32 v[114:115], v[112:113], 1.0 op_sel_hi:[1,0]
	v_pk_add_f32 v[100:101], v[94:95], v[100:101]
	v_pk_add_f32 v[88:89], v[88:89], v[114:115] neg_lo:[0,1] neg_hi:[0,1]
	v_pk_add_f32 v[102:103], v[98:99], v[100:101]
	v_pk_add_f32 v[88:89], v[94:95], v[88:89]
	v_rcp_f32_e32 v110, v102
	v_rcp_f32_e32 v111, v103
	v_pk_add_f32 v[94:95], v[112:113], v[88:89]
	v_pk_add_f32 v[98:99], v[102:103], v[98:99] neg_lo:[0,1] neg_hi:[0,1]
	v_pk_add_f32 v[112:113], v[94:95], v[112:113] neg_lo:[0,1] neg_hi:[0,1]
	v_pk_add_f32 v[98:99], v[100:101], v[98:99] neg_lo:[0,1] neg_hi:[0,1]
	v_pk_mul_f32 v[100:101], v[94:95], v[110:111]
	v_pk_add_f32 v[88:89], v[88:89], v[112:113] neg_lo:[0,1] neg_hi:[0,1]
	v_pk_mul_f32 v[112:113], v[102:103], v[100:101]
	v_pk_add_f32 v[84:85], v[90:91], v[84:85] neg_lo:[0,1] neg_hi:[0,1]
	v_pk_fma_f32 v[114:115], v[100:101], v[102:103], v[112:113] neg_lo:[0,0,1] neg_hi:[0,0,1]
	v_add_u32_e32 v81, 0xffff8000, v68
	v_pk_fma_f32 v[114:115], v[100:101], v[98:99], v[114:115]
	v_pk_add_f32 v[84:85], v[86:87], v[84:85] neg_lo:[0,1] neg_hi:[0,1]
	v_pk_add_f32 v[116:117], v[112:113], v[114:115]
	v_cndmask_b32_e64 v68, v68, v81, s[60:61]
	v_pk_add_f32 v[118:119], v[94:95], v[116:117] neg_lo:[0,1] neg_hi:[0,1]
	v_pk_add_f32 v[112:113], v[116:117], v[112:113] neg_lo:[0,1] neg_hi:[0,1]
	v_pk_add_f32 v[94:95], v[94:95], v[118:119] neg_lo:[0,1] neg_hi:[0,1]
	v_mov_b32_e32 v87, v85
	v_pk_add_f32 v[94:95], v[94:95], v[116:117] neg_lo:[0,1] neg_hi:[0,1]
	v_mov_b32_e32 v124, v90
	v_pk_add_f32 v[88:89], v[88:89], v[94:95]
	v_pk_add_f32 v[94:95], v[112:113], v[114:115] neg_lo:[0,1] neg_hi:[0,1]
	v_cmp_neq_f32_e32 vcc, s8, v83
	v_pk_add_f32 v[88:89], v[94:95], v[88:89]
	s_nop 0
	v_pk_add_f32 v[94:95], v[118:119], v[88:89]
	s_nop 0
	v_pk_mul_f32 v[112:113], v[110:111], v[94:95]
	s_nop 0
; __device__ __forceinline__ float logsigf(float x) { return fminf(x, 0.f) - log1pf(__expf(-fabsf(x))); }
; __device__ void phaseA_tile(const Params& p, int l, int mt, int nt, char* smem) {
;     ...
;                     float4 lf = make_float4(logsigf(v[0] + fb.x), logsigf(v[1] + fb.y), logsigf(v[2] + fb.z), logsigf(v[3] + fb.w));
;                     float* o = samp ? (p.out + O_LFS + ((size_t)l * TSM + (row - TP)) * 16 + c)
;                                     : (p.out + O_LFP + ((size_t)l * TP + row) * 16 + c);
;                     *(float4*)o = lf;
	v_pk_mul_f32 v[114:115], v[102:103], v[112:113]
	s_nop 0
	v_pk_fma_f32 v[102:103], v[112:113], v[102:103], v[114:115] neg_lo:[0,0,1] neg_hi:[0,0,1]
	s_nop 0
	v_pk_fma_f32 v[98:99], v[112:113], v[98:99], v[102:103]
	v_pk_add_f32 v[102:103], v[118:119], v[94:95] neg_lo:[0,1] neg_hi:[0,1]
	s_nop 0
	v_pk_add_f32 v[88:89], v[88:89], v[102:103]
	v_pk_add_f32 v[102:103], v[114:115], v[98:99]
	s_nop 0
	v_pk_add_f32 v[116:117], v[94:95], v[102:103] neg_lo:[0,1] neg_hi:[0,1]
	v_pk_add_f32 v[114:115], v[102:103], v[114:115] neg_lo:[0,1] neg_hi:[0,1]
	v_pk_add_f32 v[94:95], v[94:95], v[116:117] neg_lo:[0,1] neg_hi:[0,1]
	s_nop 0
	v_pk_add_f32 v[94:95], v[94:95], v[102:103] neg_lo:[0,1] neg_hi:[0,1]
	s_nop 0
	v_pk_add_f32 v[88:89], v[88:89], v[94:95]
	v_pk_add_f32 v[94:95], v[114:115], v[98:99] neg_lo:[0,1] neg_hi:[0,1]
	s_nop 0
	v_pk_add_f32 v[88:89], v[94:95], v[88:89]
	v_pk_add_f32 v[94:95], v[100:101], v[112:113]
	v_pk_add_f32 v[88:89], v[116:117], v[88:89]
	v_pk_add_f32 v[98:99], v[94:95], v[100:101] neg_lo:[0,1] neg_hi:[0,1]
	v_pk_mul_f32 v[88:89], v[110:111], v[88:89]
	v_pk_add_f32 v[98:99], v[112:113], v[98:99] neg_lo:[0,1] neg_hi:[0,1]
	s_nop 0
	v_pk_add_f32 v[88:89], v[98:99], v[88:89]
	s_nop 0
	v_pk_add_f32 v[98:99], v[94:95], v[88:89]
	s_nop 0
	v_pk_mul_f32 v[100:101], v[98:99], v[98:99]
	v_pk_add_f32 v[94:95], v[98:99], v[94:95] neg_lo:[0,1] neg_hi:[0,1]
	v_pk_fma_f32 v[102:103], v[100:101], s[28:29], v[66:67] op_sel_hi:[1,0,0]
	v_pk_add_f32 v[88:89], v[88:89], v[94:95] neg_lo:[0,1] neg_hi:[0,1]
	v_ldexp_f32 v94, v98, 1
	v_pk_fma_f32 v[102:103], v[100:101], v[102:103], s[30:31] op_sel_hi:[1,1,0]
	v_ldexp_f32 v95, v99, 1
	v_pk_mul_f32 v[98:99], v[98:99], v[100:101]
	v_cvt_f32_i32_e32 v101, v120
	v_cvt_f32_i32_e32 v100, v97
	v_ldexp_f32 v111, v89, 1
	v_ashrrev_i32_e32 v89, 31, v81
	v_mov_b32_e32 v81, v93
	v_pk_mul_f32 v[112:113], v[100:101], s[12:13] op_sel_hi:[1,0]
	v_ldexp_f32 v88, v88, 1
	v_pk_fma_f32 v[114:115], v[100:101], s[12:13], v[112:113] op_sel_hi:[1,0,1] neg_lo:[0,0,1] neg_hi:[0,0,1]
	v_mov_b32_e32 v86, v112
	v_pk_fma_f32 v[100:101], v[100:101], s[14:15], v[114:115] op_sel_hi:[1,0,1]
	v_mov_b32_e32 v121, v113
	v_mov_b32_e32 v92, v100
	v_pk_add_f32 v[86:87], v[86:87], v[92:93]
	v_pk_add_f32 v[92:93], v[80:81], v[84:85]
	v_mov_b32_e32 v85, v91
	v_mov_b32_e32 v81, v93
	v_pk_add_f32 v[114:115], v[112:113], v[100:101]
	v_pk_add_f32 v[80:81], v[80:81], v[84:85]
	v_pk_add_f32 v[84:85], v[90:91], v[92:93]
	v_mov_b32_e32 v125, v115
	v_pk_add_f32 v[116:117], v[114:115], v[84:85]
	v_mov_b32_e32 v122, v84
	v_mov_b32_e32 v123, v117
	v_pk_add_f32 v[122:123], v[122:123], v[124:125] neg_lo:[0,1] neg_hi:[0,1]
	v_mov_b32_e32 v118, v116
	v_mov_b32_e32 v119, v115
	v_mov_b32_e32 v120, v114
	v_mov_b32_e32 v124, v114
	v_mov_b32_e32 v125, v117
	v_mov_b32_e32 v113, v123
	v_pk_add_f32 v[118:119], v[118:119], v[120:121] neg_lo:[0,1] neg_hi:[0,1]
	v_mov_b32_e32 v120, v84
	v_mov_b32_e32 v121, v101
	v_pk_add_f32 v[112:113], v[124:125], v[112:113] neg_lo:[0,1] neg_hi:[0,1]
	v_pk_add_f32 v[120:121], v[120:121], v[118:119] neg_lo:[0,1] neg_hi:[0,1]
	v_mov_b32_e32 v124, v112
	v_mov_b32_e32 v125, v119
	v_mov_b32_e32 v126, v116
	v_mov_b32_e32 v127, v85
	v_mov_b32_e32 v119, v91
	v_pk_add_f32 v[124:125], v[100:101], v[124:125] neg_lo:[0,1] neg_hi:[0,1]
	v_pk_add_f32 v[118:119], v[126:127], v[118:119] neg_lo:[0,1] neg_hi:[0,1]
	v_mov_b32_e32 v101, v115
	v_pk_add_f32 v[84:85], v[84:85], v[90:91] neg_lo:[0,1] neg_hi:[0,1]
	v_pk_add_f32 v[86:87], v[86:87], v[118:119] neg_lo:[0,1] neg_hi:[0,1]
	v_pk_add_f32 v[90:91], v[100:101], v[112:113] neg_lo:[0,1] neg_hi:[0,1]
	v_pk_add_f32 v[80:81], v[80:81], v[122:123] neg_lo:[0,1] neg_hi:[0,1]
	v_pk_add_f32 v[84:85], v[92:93], v[84:85] neg_lo:[0,1] neg_hi:[0,1]
	v_pk_add_f32 v[92:93], v[80:81], v[90:91]
	v_mov_b32_e32 v91, v121
	v_mov_b32_e32 v81, v87
	v_pk_add_f32 v[100:101], v[120:121], v[86:87]
	v_pk_add_f32 v[80:81], v[90:91], v[80:81]
	v_mov_b32_e32 v86, v92
	v_pk_add_f32 v[80:81], v[80:81], v[124:125] neg_lo:[0,1] neg_hi:[0,1]
	v_mov_b32_e32 v87, v101
	v_pk_add_f32 v[86:87], v[86:87], v[80:81] neg_lo:[0,1] neg_hi:[0,1]
	v_pk_add_f32 v[80:81], v[84:85], v[80:81] neg_lo:[0,1] neg_hi:[0,1]
	v_pk_add_f32 v[86:87], v[90:91], v[86:87] neg_lo:[0,1] neg_hi:[0,1]
	v_pk_add_f32 v[84:85], v[100:101], v[92:93]
	v_pk_add_f32 v[80:81], v[80:81], v[86:87]
	v_pk_add_f32 v[86:87], v[116:117], v[84:85]
	v_cndmask_b32_e64 v69, v69, v89, s[60:61]
	v_pk_add_f32 v[90:91], v[86:87], v[116:117] neg_lo:[0,1] neg_hi:[0,1]
	v_mov_b32_e32 v89, v111
	v_pk_add_f32 v[84:85], v[84:85], v[90:91] neg_lo:[0,1] neg_hi:[0,1]
	v_lshlrev_b64 v[68:69], 6, v[68:69]
	v_pk_add_f32 v[80:81], v[80:81], v[84:85]
	v_lshl_add_u64 v[68:69], s[6:7], 0, v[68:69]
	v_pk_add_f32 v[80:81], v[86:87], v[80:81]
	v_pk_mul_f32 v[86:87], v[98:99], v[102:103]
	v_cndmask_b32_e32 v80, v160, v80, vcc
	v_cmp_neq_f32_e32 vcc, s8, v128
	v_pk_add_f32 v[90:91], v[94:95], v[86:87]
	v_lshl_add_u64 v[68:69], v[68:69], 0, v[0:1]
	v_cndmask_b32_e32 v81, v160, v81, vcc
	v_cmp_ngt_f32_e32 vcc, -1.0, v128
	v_pk_add_f32 v[94:95], v[90:91], v[94:95] neg_lo:[0,1] neg_hi:[0,1]
	v_mov_b32_e32 v114, v90
	v_cndmask_b32_e32 v81, v161, v81, vcc
	v_cmp_ngt_f32_e32 vcc, -1.0, v83
	v_pk_add_f32 v[86:87], v[86:87], v[94:95] neg_lo:[0,1] neg_hi:[0,1]
	s_nop 0
	v_cndmask_b32_e32 v80, v161, v80, vcc
	v_cmp_neq_f32_e32 vcc, -1.0, v83
	v_pk_add_f32 v[98:99], v[88:89], v[86:87]
	v_mov_b32_e32 v95, v87
	v_cndmask_b32_e32 v80, v162, v80, vcc
	v_cmp_neq_f32_e32 vcc, -1.0, v128
	v_mov_b32_e32 v89, v99
	v_mov_b32_e32 v87, v91
	v_cndmask_b32_e32 v81, v162, v81, vcc
	v_cmp_lt_f32_e64 vcc, |v83|, s9
	v_cndmask_b32_e64 v81, v81, v128, s[0:1]
; __device__ __forceinline__ float softplusf(float x) { return fmaxf(x, 0.f) + log1pf(__expf(-fabsf(x))); }
; __device__ __forceinline__ float logsigf(float x) { return fminf(x, 0.f) - log1pf(__expf(-fabsf(x))); }
; __device__ void phaseA_tile(const Params& p, int l, int mt, int nt, char* smem) {
;     ...
;                     const float4 db = *(const float4*)(p.dt_bias + l * 32 + c);
;                     const f32x4 v = acc[i][j];
;                     *(float4*)(p.dtb + (size_t)row * 32 + c) =
;                         make_float4(softplusf(v[0] + db.x), softplusf(v[1] + db.y), softplusf(v[2] + db.z), softplusf(v[3] + db.w));
;     ...
;                     *(float4*)o = lf;
;                     *(float4*)(lf_s + rl * 16 + c) = lf;
	v_pk_add_f32 v[86:87], v[88:89], v[86:87]
	v_cndmask_b32_e32 v80, v80, v83, vcc
	v_pk_add_f32 v[76:77], v[76:77], v[80:81] neg_lo:[0,1] neg_hi:[0,1]
	v_cvt_f32_i32_e32 v81, v132
	v_cvt_f32_i32_e32 v80, v130
	v_pk_add_f32 v[88:89], v[90:91], v[98:99]
	v_cmp_neq_f32_e32 vcc, s8, v129
	v_mov_b32_e32 v112, v88
	v_pk_mul_f32 v[84:85], v[80:81], s[12:13] op_sel_hi:[1,0]
	v_mov_b32_e32 v117, v89
	v_pk_fma_f32 v[92:93], v[80:81], s[12:13], v[84:85] op_sel_hi:[1,0,1] neg_lo:[0,0,1] neg_hi:[0,0,1]
	v_mov_b32_e32 v94, v84
	v_pk_fma_f32 v[80:81], v[80:81], s[14:15], v[92:93] op_sel_hi:[1,0,1]
	v_cmp_lt_f32_e64 s[0:1], |v131|, s9
	v_pk_add_f32 v[92:93], v[84:85], v[80:81]
	v_mov_b32_e32 v110, v80
	v_pk_add_f32 v[100:101], v[92:93], v[88:89]
	v_mov_b32_e32 v115, v93
	v_mov_b32_e32 v113, v101
	v_pk_add_f32 v[112:113], v[112:113], v[114:115] neg_lo:[0,1] neg_hi:[0,1]
	v_pk_add_f32 v[94:95], v[94:95], v[110:111]
	v_mov_b32_e32 v102, v100
	v_mov_b32_e32 v103, v93
	v_mov_b32_e32 v110, v92
	v_mov_b32_e32 v111, v85
	v_mov_b32_e32 v114, v92
	v_mov_b32_e32 v115, v101
	v_mov_b32_e32 v85, v113
	v_pk_add_f32 v[102:103], v[102:103], v[110:111] neg_lo:[0,1] neg_hi:[0,1]
	v_mov_b32_e32 v110, v88
	v_mov_b32_e32 v111, v81
	v_pk_add_f32 v[84:85], v[114:115], v[84:85] neg_lo:[0,1] neg_hi:[0,1]
	v_pk_add_f32 v[110:111], v[110:111], v[102:103] neg_lo:[0,1] neg_hi:[0,1]
	v_mov_b32_e32 v114, v84
	v_mov_b32_e32 v115, v103
	v_mov_b32_e32 v116, v100
	v_mov_b32_e32 v103, v91
	v_pk_add_f32 v[114:115], v[80:81], v[114:115] neg_lo:[0,1] neg_hi:[0,1]
	v_pk_add_f32 v[102:103], v[116:117], v[102:103] neg_lo:[0,1] neg_hi:[0,1]
	v_mov_b32_e32 v81, v93
	v_pk_add_f32 v[88:89], v[88:89], v[90:91] neg_lo:[0,1] neg_hi:[0,1]
	v_pk_add_f32 v[90:91], v[94:95], v[102:103] neg_lo:[0,1] neg_hi:[0,1]
	v_pk_add_f32 v[80:81], v[80:81], v[84:85] neg_lo:[0,1] neg_hi:[0,1]
	v_pk_add_f32 v[84:85], v[86:87], v[112:113] neg_lo:[0,1] neg_hi:[0,1]
	v_pk_add_f32 v[92:93], v[110:111], v[90:91]
	v_pk_add_f32 v[86:87], v[84:85], v[80:81]
	v_mov_b32_e32 v81, v111
	v_mov_b32_e32 v85, v91
	v_pk_add_f32 v[84:85], v[80:81], v[84:85]
	v_mov_b32_e32 v90, v86
	v_pk_add_f32 v[84:85], v[84:85], v[114:115] neg_lo:[0,1] neg_hi:[0,1]
	v_mov_b32_e32 v91, v93
	v_pk_add_f32 v[88:89], v[98:99], v[88:89] neg_lo:[0,1] neg_hi:[0,1]
	v_pk_add_f32 v[90:91], v[90:91], v[84:85] neg_lo:[0,1] neg_hi:[0,1]
	v_pk_add_f32 v[84:85], v[88:89], v[84:85] neg_lo:[0,1] neg_hi:[0,1]
	v_pk_add_f32 v[80:81], v[80:81], v[90:91] neg_lo:[0,1] neg_hi:[0,1]
	s_nop 0
	v_pk_add_f32 v[80:81], v[84:85], v[80:81]
	v_pk_add_f32 v[84:85], v[92:93], v[86:87]
	s_nop 0
	v_pk_add_f32 v[86:87], v[100:101], v[84:85]
	s_nop 0
	v_pk_add_f32 v[88:89], v[86:87], v[100:101] neg_lo:[0,1] neg_hi:[0,1]
	s_nop 0
	v_pk_add_f32 v[84:85], v[84:85], v[88:89] neg_lo:[0,1] neg_hi:[0,1]
	s_nop 0
	v_pk_add_f32 v[80:81], v[80:81], v[84:85]
	s_nop 0
	v_pk_add_f32 v[80:81], v[86:87], v[80:81]
	s_nop 0
	v_cndmask_b32_e32 v80, v160, v80, vcc
	v_cmp_neq_f32_e32 vcc, s8, v131
	s_nop 1
	v_cndmask_b32_e32 v81, v160, v81, vcc
	v_cmp_ngt_f32_e32 vcc, -1.0, v131
	s_nop 1
	v_cndmask_b32_e32 v81, v161, v81, vcc
	v_cmp_ngt_f32_e32 vcc, -1.0, v129
	s_nop 1
	v_cndmask_b32_e32 v80, v161, v80, vcc
	v_cmp_neq_f32_e32 vcc, -1.0, v129
	s_nop 1
	v_cndmask_b32_e32 v80, v162, v80, vcc
	v_cmp_neq_f32_e32 vcc, -1.0, v131
	s_nop 1
	v_cndmask_b32_e32 v81, v162, v81, vcc
	v_cmp_lt_f32_e64 vcc, |v129|, s9
	v_cndmask_b32_e64 v81, v81, v131, s[0:1]
	s_nop 0
	v_cndmask_b32_e32 v80, v80, v129, vcc
	v_pk_add_f32 v[78:79], v[78:79], v[80:81] neg_lo:[0,1] neg_hi:[0,1]
	global_store_dwordx4 v[68:69], v[76:79], off
	v_lshl_or_b32 v68, v82, 6, v0
	ds_write_b128 v68, v[76:79]
	global_load_dwordx4 v[78:81], v0, s[74:75]
	v_add_u32_e32 v68, s54, v71
	v_ashrrev_i32_e32 v69, 31, v68
	v_lshlrev_b64 v[76:77], 7, v[68:69]
	v_lshl_add_u64 v[76:77], s[10:11], 0, v[76:77]
	v_lshl_add_u64 v[76:77], v[76:77], 0, v[0:1]
	s_waitcnt vmcnt(0)
	v_add_f32_e32 v82, v14, v78
	v_max_f32_e32 v78, 0, v82
	v_mul_f32_e64 v82, |v82|, s2
	v_exp_f32_e32 v97, v82
	s_nop 0
	v_add_f32_e32 v84, 1.0, v97
	v_add_f32_e32 v82, -1.0, v84
	v_sub_f32_e32 v83, v82, v84
	v_add_f32_e32 v83, 1.0, v83
	v_sub_f32_e32 v82, v97, v82
	v_add_f32_e32 v85, v82, v83
	v_frexp_mant_f32_e32 v82, v84
	v_cmp_gt_f32_e32 vcc, s26, v82
	v_cvt_f64_f32_e32 v[82:83], v84
	v_frexp_exp_i32_f64_e32 v82, v[82:83]
	v_subbrev_co_u32_e32 v120, vcc, 0, v82, vcc
	v_sub_u32_e32 v83, 0, v120
	v_ldexp_f32 v82, v84, v83
	v_ldexp_f32 v84, v85, v83
	v_add_f32_e32 v83, v15, v79
	v_max_f32_e32 v79, 0, v83
	v_mul_f32_e64 v83, |v83|, s2
	v_exp_f32_e32 v128, v83
	s_nop 0
	v_add_f32_e32 v83, 1.0, v128
	v_add_f32_e32 v85, -1.0, v83
	v_sub_f32_e32 v86, v85, v83
	v_add_f32_e32 v86, 1.0, v86
	v_sub_f32_e32 v85, v128, v85
	v_add_f32_e32 v85, v85, v86
	v_frexp_mant_f32_e32 v86, v83
	v_cmp_gt_f32_e32 vcc, s26, v86
	v_cvt_f64_f32_e32 v[86:87], v83
	v_frexp_exp_i32_f64_e32 v86, v[86:87]
	v_subbrev_co_u32_e32 v121, vcc, 0, v86, vcc
	v_sub_u32_e32 v86, 0, v121
	v_ldexp_f32 v83, v83, v86
	v_ldexp_f32 v85, v85, v86
	v_pk_add_f32 v[86:87], v[82:83], 1.0 op_sel_hi:[1,0]
	v_pk_add_f32 v[94:95], v[82:83], -1.0 op_sel_hi:[1,0]
	v_pk_add_f32 v[88:89], v[86:87], -1.0 op_sel_hi:[1,0]
	v_pk_add_f32 v[98:99], v[94:95], 1.0 op_sel_hi:[1,0]
	v_pk_add_f32 v[88:89], v[82:83], v[88:89] neg_lo:[0,1] neg_hi:[0,1]
	v_pk_add_f32 v[82:83], v[82:83], v[98:99] neg_lo:[0,1] neg_hi:[0,1]
	v_pk_add_f32 v[88:89], v[84:85], v[88:89]
	v_pk_add_f32 v[82:83], v[84:85], v[82:83]
	v_pk_add_f32 v[90:91], v[86:87], v[88:89]
	v_pk_add_f32 v[84:85], v[94:95], v[82:83]
	v_rcp_f32_e32 v92, v90
	v_rcp_f32_e32 v93, v91
	v_pk_add_f32 v[86:87], v[90:91], v[86:87] neg_lo:[0,1] neg_hi:[0,1]
; __device__ __forceinline__ float softplusf(float x) { return fmaxf(x, 0.f) + log1pf(__expf(-fabsf(x))); }
; __device__ void phaseA_tile(const Params& p, int l, int mt, int nt, char* smem) {
;     ...
;                     const f32x4 v = acc[i][j];
;                     *(float4*)(p.dtb + (size_t)row * 32 + c) =
;                         make_float4(softplusf(v[0] + db.x), softplusf(v[1] + db.y), softplusf(v[2] + db.z), softplusf(v[3] + db.w));
	v_pk_add_f32 v[94:95], v[84:85], v[94:95] neg_lo:[0,1] neg_hi:[0,1]
	v_pk_add_f32 v[86:87], v[88:89], v[86:87] neg_lo:[0,1] neg_hi:[0,1]
	v_pk_mul_f32 v[88:89], v[84:85], v[92:93]
	v_pk_add_f32 v[82:83], v[82:83], v[94:95] neg_lo:[0,1] neg_hi:[0,1]
	v_pk_mul_f32 v[94:95], v[90:91], v[88:89]
	v_cmp_lt_f32_e64 s[0:1], |v128|, s9
	v_pk_fma_f32 v[98:99], v[88:89], v[90:91], v[94:95] neg_lo:[0,0,1] neg_hi:[0,0,1]
	s_nop 0
	v_pk_fma_f32 v[98:99], v[88:89], v[86:87], v[98:99]
	s_nop 0
	v_pk_add_f32 v[100:101], v[94:95], v[98:99]
	s_nop 0
	v_pk_add_f32 v[102:103], v[84:85], v[100:101] neg_lo:[0,1] neg_hi:[0,1]
	v_pk_add_f32 v[94:95], v[100:101], v[94:95] neg_lo:[0,1] neg_hi:[0,1]
	v_pk_add_f32 v[84:85], v[84:85], v[102:103] neg_lo:[0,1] neg_hi:[0,1]
	s_nop 0
	v_pk_add_f32 v[84:85], v[84:85], v[100:101] neg_lo:[0,1] neg_hi:[0,1]
	s_nop 0
	v_pk_add_f32 v[82:83], v[82:83], v[84:85]
	v_pk_add_f32 v[84:85], v[94:95], v[98:99] neg_lo:[0,1] neg_hi:[0,1]
	s_nop 0
	v_pk_add_f32 v[82:83], v[84:85], v[82:83]
	s_nop 0
	v_pk_add_f32 v[84:85], v[102:103], v[82:83]
	s_nop 0
	v_pk_mul_f32 v[94:95], v[92:93], v[84:85]
	s_nop 0
	v_pk_mul_f32 v[98:99], v[90:91], v[94:95]
	s_nop 0
	v_pk_fma_f32 v[90:91], v[94:95], v[90:91], v[98:99] neg_lo:[0,0,1] neg_hi:[0,0,1]
	s_nop 0
	v_pk_fma_f32 v[86:87], v[94:95], v[86:87], v[90:91]
	v_pk_add_f32 v[90:91], v[102:103], v[84:85] neg_lo:[0,1] neg_hi:[0,1]
	s_nop 0
	v_pk_add_f32 v[82:83], v[82:83], v[90:91]
	v_pk_add_f32 v[90:91], v[98:99], v[86:87]
	s_nop 0
	v_pk_add_f32 v[100:101], v[84:85], v[90:91] neg_lo:[0,1] neg_hi:[0,1]
	v_pk_add_f32 v[98:99], v[90:91], v[98:99] neg_lo:[0,1] neg_hi:[0,1]
	v_pk_add_f32 v[84:85], v[84:85], v[100:101] neg_lo:[0,1] neg_hi:[0,1]
	s_nop 0
	v_pk_add_f32 v[84:85], v[84:85], v[90:91] neg_lo:[0,1] neg_hi:[0,1]
	s_nop 0
	v_pk_add_f32 v[82:83], v[82:83], v[84:85]
	v_pk_add_f32 v[84:85], v[98:99], v[86:87] neg_lo:[0,1] neg_hi:[0,1]
	s_nop 0
	v_pk_add_f32 v[82:83], v[84:85], v[82:83]
	v_pk_add_f32 v[84:85], v[88:89], v[94:95]
	v_pk_add_f32 v[82:83], v[100:101], v[82:83]
	v_pk_add_f32 v[86:87], v[84:85], v[88:89] neg_lo:[0,1] neg_hi:[0,1]
	v_pk_mul_f32 v[82:83], v[92:93], v[82:83]
	v_pk_add_f32 v[86:87], v[94:95], v[86:87] neg_lo:[0,1] neg_hi:[0,1]
	s_nop 0
	v_pk_add_f32 v[82:83], v[86:87], v[82:83]
	s_nop 0
	v_pk_add_f32 v[86:87], v[84:85], v[82:83]
	s_nop 0
	v_pk_add_f32 v[84:85], v[86:87], v[84:85] neg_lo:[0,1] neg_hi:[0,1]
	v_pk_mul_f32 v[88:89], v[86:87], v[86:87]
	v_pk_add_f32 v[82:83], v[82:83], v[84:85] neg_lo:[0,1] neg_hi:[0,1]
	v_pk_fma_f32 v[90:91], v[88:89], s[28:29], v[66:67] op_sel_hi:[1,0,0]
	v_ldexp_f32 v93, v83, 1
	v_add_f32_e32 v83, v16, v80
	v_max_f32_e32 v80, 0, v83
	v_mul_f32_e64 v83, |v83|, s2
	v_exp_f32_e32 v129, v83
	v_ldexp_f32 v84, v86, 1
	v_pk_fma_f32 v[90:91], v[88:89], v[90:91], s[30:31] op_sel_hi:[1,1,0]
	v_ldexp_f32 v85, v87, 1
	v_add_f32_e32 v83, 1.0, v129
	v_pk_mul_f32 v[86:87], v[86:87], v[88:89]
	v_add_f32_e32 v88, -1.0, v83
	v_sub_f32_e32 v89, v88, v83
	v_add_f32_e32 v89, 1.0, v89
	v_sub_f32_e32 v88, v129, v88
	v_add_f32_e32 v92, v88, v89
	v_frexp_mant_f32_e32 v88, v83
	v_cmp_gt_f32_e32 vcc, s26, v88
	v_cvt_f64_f32_e32 v[88:89], v83
	v_frexp_exp_i32_f64_e32 v88, v[88:89]
	v_subbrev_co_u32_e32 v130, vcc, 0, v88, vcc
	v_sub_u32_e32 v89, 0, v130
	v_ldexp_f32 v88, v83, v89
	v_add_f32_e32 v83, v17, v81
	v_max_f32_e32 v81, 0, v83
	v_mul_f32_e64 v83, |v83|, s2
	v_exp_f32_e32 v131, v83
	v_ldexp_f32 v94, v92, v89
	v_pk_mul_f32 v[86:87], v[86:87], v[90:91]
	v_ldexp_f32 v82, v82, 1
	v_add_f32_e32 v83, 1.0, v131
	v_add_f32_e32 v89, -1.0, v83
	v_sub_f32_e32 v92, v89, v83
	v_add_f32_e32 v92, 1.0, v92
	v_sub_f32_e32 v89, v131, v89
	v_add_f32_e32 v92, v89, v92
	v_frexp_mant_f32_e32 v89, v83
	v_cvt_f64_f32_e32 v[98:99], v83
	v_cmp_gt_f32_e32 vcc, s26, v89
	v_frexp_exp_i32_f64_e32 v89, v[98:99]
	v_pk_add_f32 v[90:91], v[84:85], v[86:87]
	v_subbrev_co_u32_e32 v132, vcc, 0, v89, vcc
	v_sub_u32_e32 v95, 0, v132
	v_ldexp_f32 v89, v83, v95
	v_pk_add_f32 v[98:99], v[88:89], 1.0 op_sel_hi:[1,0]
	v_ldexp_f32 v95, v92, v95
	v_pk_add_f32 v[100:101], v[98:99], -1.0 op_sel_hi:[1,0]
	v_pk_add_f32 v[112:113], v[88:89], -1.0 op_sel_hi:[1,0]
	v_pk_add_f32 v[100:101], v[88:89], v[100:101] neg_lo:[0,1] neg_hi:[0,1]
	v_pk_add_f32 v[114:115], v[112:113], 1.0 op_sel_hi:[1,0]
	v_pk_add_f32 v[100:101], v[94:95], v[100:101]
	v_pk_add_f32 v[88:89], v[88:89], v[114:115] neg_lo:[0,1] neg_hi:[0,1]
	v_pk_add_f32 v[102:103], v[98:99], v[100:101]
	v_pk_add_f32 v[88:89], v[94:95], v[88:89]
	v_rcp_f32_e32 v110, v102
	v_rcp_f32_e32 v111, v103
	v_pk_add_f32 v[94:95], v[112:113], v[88:89]
	v_pk_add_f32 v[98:99], v[102:103], v[98:99] neg_lo:[0,1] neg_hi:[0,1]
	v_pk_add_f32 v[112:113], v[94:95], v[112:113] neg_lo:[0,1] neg_hi:[0,1]
	v_pk_add_f32 v[98:99], v[100:101], v[98:99] neg_lo:[0,1] neg_hi:[0,1]
	v_pk_mul_f32 v[100:101], v[94:95], v[110:111]
	v_pk_add_f32 v[88:89], v[88:89], v[112:113] neg_lo:[0,1] neg_hi:[0,1]
	v_pk_mul_f32 v[112:113], v[102:103], v[100:101]
	v_pk_add_f32 v[84:85], v[90:91], v[84:85] neg_lo:[0,1] neg_hi:[0,1]
	v_pk_fma_f32 v[114:115], v[100:101], v[102:103], v[112:113] neg_lo:[0,0,1] neg_hi:[0,0,1]
	v_pk_add_f32 v[84:85], v[86:87], v[84:85] neg_lo:[0,1] neg_hi:[0,1]
	v_pk_fma_f32 v[114:115], v[100:101], v[98:99], v[114:115]
	v_mov_b32_e32 v87, v85
	v_pk_add_f32 v[116:117], v[112:113], v[114:115]
	v_mov_b32_e32 v83, v93
	v_pk_add_f32 v[118:119], v[94:95], v[116:117] neg_lo:[0,1] neg_hi:[0,1]
	v_pk_add_f32 v[112:113], v[116:117], v[112:113] neg_lo:[0,1] neg_hi:[0,1]
	v_pk_add_f32 v[94:95], v[94:95], v[118:119] neg_lo:[0,1] neg_hi:[0,1]
	v_mov_b32_e32 v124, v90
	v_pk_add_f32 v[94:95], v[94:95], v[116:117] neg_lo:[0,1] neg_hi:[0,1]
; __device__ __forceinline__ float softplusf(float x) { return fmaxf(x, 0.f) + log1pf(__expf(-fabsf(x))); }
; __device__ void phaseA_tile(const Params& p, int l, int mt, int nt, char* smem) {
;     ...
; #pragma unroll
;                 for (int j = 0; j < 2; ++j) {
;                     const int c = j * 16 + g4 * 4;
;                     const float4 db = *(const float4*)(p.dt_bias + l * 32 + c);
;                     const f32x4 v = acc[i][j];
;                     *(float4*)(p.dtb + (size_t)row * 32 + c) =
;                         make_float4(softplusf(v[0] + db.x), softplusf(v[1] + db.y), softplusf(v[2] + db.z), softplusf(v[3] + db.w));
	v_cmp_neq_f32_e32 vcc, s8, v97
	v_pk_add_f32 v[88:89], v[88:89], v[94:95]
	v_pk_add_f32 v[94:95], v[112:113], v[114:115] neg_lo:[0,1] neg_hi:[0,1]
	s_nop 0
	v_pk_add_f32 v[88:89], v[94:95], v[88:89]
	s_nop 0
	v_pk_add_f32 v[94:95], v[118:119], v[88:89]
	s_nop 0
	v_pk_mul_f32 v[112:113], v[110:111], v[94:95]
	s_nop 0
	v_pk_mul_f32 v[114:115], v[102:103], v[112:113]
	s_nop 0
	v_pk_fma_f32 v[102:103], v[112:113], v[102:103], v[114:115] neg_lo:[0,0,1] neg_hi:[0,0,1]
	s_nop 0
	v_pk_fma_f32 v[98:99], v[112:113], v[98:99], v[102:103]
	v_pk_add_f32 v[102:103], v[118:119], v[94:95] neg_lo:[0,1] neg_hi:[0,1]
	s_nop 0
	v_pk_add_f32 v[88:89], v[88:89], v[102:103]
	v_pk_add_f32 v[102:103], v[114:115], v[98:99]
	s_nop 0
	v_pk_add_f32 v[116:117], v[94:95], v[102:103] neg_lo:[0,1] neg_hi:[0,1]
	v_pk_add_f32 v[114:115], v[102:103], v[114:115] neg_lo:[0,1] neg_hi:[0,1]
	v_pk_add_f32 v[94:95], v[94:95], v[116:117] neg_lo:[0,1] neg_hi:[0,1]
	s_nop 0
	v_pk_add_f32 v[94:95], v[94:95], v[102:103] neg_lo:[0,1] neg_hi:[0,1]
	s_nop 0
	v_pk_add_f32 v[88:89], v[88:89], v[94:95]
	v_pk_add_f32 v[94:95], v[114:115], v[98:99] neg_lo:[0,1] neg_hi:[0,1]
	s_nop 0
	v_pk_add_f32 v[88:89], v[94:95], v[88:89]
	v_pk_add_f32 v[94:95], v[100:101], v[112:113]
	v_pk_add_f32 v[88:89], v[116:117], v[88:89]
	v_pk_add_f32 v[98:99], v[94:95], v[100:101] neg_lo:[0,1] neg_hi:[0,1]
	v_pk_mul_f32 v[88:89], v[110:111], v[88:89]
	v_pk_add_f32 v[98:99], v[112:113], v[98:99] neg_lo:[0,1] neg_hi:[0,1]
	s_nop 0
	v_pk_add_f32 v[88:89], v[98:99], v[88:89]
	s_nop 0
	v_pk_add_f32 v[98:99], v[94:95], v[88:89]
	s_nop 0
	v_pk_mul_f32 v[100:101], v[98:99], v[98:99]
	v_pk_add_f32 v[94:95], v[98:99], v[94:95] neg_lo:[0,1] neg_hi:[0,1]
	v_pk_fma_f32 v[102:103], v[100:101], s[28:29], v[66:67] op_sel_hi:[1,0,0]
	v_pk_add_f32 v[88:89], v[88:89], v[94:95] neg_lo:[0,1] neg_hi:[0,1]
	v_ldexp_f32 v94, v98, 1
	v_pk_fma_f32 v[102:103], v[100:101], v[102:103], s[30:31] op_sel_hi:[1,1,0]
	v_ldexp_f32 v95, v99, 1
	v_pk_mul_f32 v[98:99], v[98:99], v[100:101]
	v_cvt_f32_i32_e32 v101, v121
	v_cvt_f32_i32_e32 v100, v120
	v_ldexp_f32 v111, v89, 1
	v_ldexp_f32 v88, v88, 1
	v_mov_b32_e32 v89, v111
	v_pk_mul_f32 v[112:113], v[100:101], s[12:13] op_sel_hi:[1,0]
	s_nop 0
	v_pk_fma_f32 v[114:115], v[100:101], s[12:13], v[112:113] op_sel_hi:[1,0,1] neg_lo:[0,0,1] neg_hi:[0,0,1]
	v_mov_b32_e32 v86, v112
	v_pk_fma_f32 v[100:101], v[100:101], s[14:15], v[114:115] op_sel_hi:[1,0,1]
	v_mov_b32_e32 v121, v113
	v_mov_b32_e32 v92, v100
	v_pk_add_f32 v[86:87], v[86:87], v[92:93]
	v_pk_add_f32 v[92:93], v[82:83], v[84:85]
	v_mov_b32_e32 v85, v91
	v_mov_b32_e32 v83, v93
	v_pk_add_f32 v[114:115], v[112:113], v[100:101]
	v_pk_add_f32 v[82:83], v[82:83], v[84:85]
	v_pk_add_f32 v[84:85], v[90:91], v[92:93]
	v_mov_b32_e32 v125, v115
	v_pk_add_f32 v[116:117], v[114:115], v[84:85]
	v_mov_b32_e32 v122, v84
	v_mov_b32_e32 v123, v117
	v_pk_add_f32 v[122:123], v[122:123], v[124:125] neg_lo:[0,1] neg_hi:[0,1]
	v_mov_b32_e32 v118, v116
	v_mov_b32_e32 v119, v115
	v_mov_b32_e32 v120, v114
	v_mov_b32_e32 v124, v114
	v_mov_b32_e32 v125, v117
	v_mov_b32_e32 v113, v123
	v_pk_add_f32 v[118:119], v[118:119], v[120:121] neg_lo:[0,1] neg_hi:[0,1]
	v_mov_b32_e32 v120, v84
	v_mov_b32_e32 v121, v101
	v_pk_add_f32 v[112:113], v[124:125], v[112:113] neg_lo:[0,1] neg_hi:[0,1]
	v_pk_add_f32 v[120:121], v[120:121], v[118:119] neg_lo:[0,1] neg_hi:[0,1]
	v_mov_b32_e32 v124, v112
	v_mov_b32_e32 v125, v119
	v_mov_b32_e32 v126, v116
	v_mov_b32_e32 v127, v85
	v_mov_b32_e32 v119, v91
	v_pk_add_f32 v[124:125], v[100:101], v[124:125] neg_lo:[0,1] neg_hi:[0,1]
	v_pk_add_f32 v[118:119], v[126:127], v[118:119] neg_lo:[0,1] neg_hi:[0,1]
	v_mov_b32_e32 v101, v115
	v_pk_add_f32 v[84:85], v[84:85], v[90:91] neg_lo:[0,1] neg_hi:[0,1]
	v_pk_add_f32 v[86:87], v[86:87], v[118:119] neg_lo:[0,1] neg_hi:[0,1]
	v_pk_add_f32 v[90:91], v[100:101], v[112:113] neg_lo:[0,1] neg_hi:[0,1]
	v_pk_add_f32 v[82:83], v[82:83], v[122:123] neg_lo:[0,1] neg_hi:[0,1]
	v_pk_add_f32 v[84:85], v[92:93], v[84:85] neg_lo:[0,1] neg_hi:[0,1]
	v_pk_add_f32 v[92:93], v[82:83], v[90:91]
	v_mov_b32_e32 v91, v121
	v_mov_b32_e32 v83, v87
	v_pk_add_f32 v[100:101], v[120:121], v[86:87]
	v_pk_add_f32 v[82:83], v[90:91], v[82:83]
	v_mov_b32_e32 v86, v92
	v_pk_add_f32 v[82:83], v[82:83], v[124:125] neg_lo:[0,1] neg_hi:[0,1]
	v_mov_b32_e32 v87, v101
	v_pk_add_f32 v[86:87], v[86:87], v[82:83] neg_lo:[0,1] neg_hi:[0,1]
	v_pk_add_f32 v[82:83], v[84:85], v[82:83] neg_lo:[0,1] neg_hi:[0,1]
	v_pk_add_f32 v[86:87], v[90:91], v[86:87] neg_lo:[0,1] neg_hi:[0,1]
	v_pk_add_f32 v[84:85], v[100:101], v[92:93]
	v_pk_add_f32 v[82:83], v[82:83], v[86:87]
	v_pk_add_f32 v[86:87], v[116:117], v[84:85]
	s_nop 0
	v_pk_add_f32 v[90:91], v[86:87], v[116:117] neg_lo:[0,1] neg_hi:[0,1]
	s_nop 0
	v_pk_add_f32 v[84:85], v[84:85], v[90:91] neg_lo:[0,1] neg_hi:[0,1]
	s_nop 0
	v_pk_add_f32 v[82:83], v[82:83], v[84:85]
	s_nop 0
	v_pk_add_f32 v[82:83], v[86:87], v[82:83]
	v_pk_mul_f32 v[86:87], v[98:99], v[102:103]
	v_cndmask_b32_e32 v82, v160, v82, vcc
	v_cmp_neq_f32_e32 vcc, s8, v128
	v_pk_add_f32 v[90:91], v[94:95], v[86:87]
	s_nop 0
	v_cndmask_b32_e32 v83, v160, v83, vcc
	v_cmp_ngt_f32_e32 vcc, -1.0, v128
	v_pk_add_f32 v[94:95], v[90:91], v[94:95] neg_lo:[0,1] neg_hi:[0,1]
	v_mov_b32_e32 v114, v90
	v_cndmask_b32_e32 v83, v161, v83, vcc
	v_cmp_ngt_f32_e32 vcc, -1.0, v97
	v_pk_add_f32 v[86:87], v[86:87], v[94:95] neg_lo:[0,1] neg_hi:[0,1]
	s_nop 0
	v_cndmask_b32_e32 v82, v161, v82, vcc
	v_cmp_neq_f32_e32 vcc, -1.0, v97
	v_pk_add_f32 v[98:99], v[88:89], v[86:87]
	v_mov_b32_e32 v95, v87
	v_cndmask_b32_e32 v82, v162, v82, vcc
	v_cmp_neq_f32_e32 vcc, -1.0, v128
; __device__ __forceinline__ float softplusf(float x) { return fmaxf(x, 0.f) + log1pf(__expf(-fabsf(x))); }
; __device__ void phaseA_tile(const Params& p, int l, int mt, int nt, char* smem) {
;     ...
;                 for (int j = 0; j < 2; ++j) {
;                     const int c = j * 16 + g4 * 4;
;                     const float4 db = *(const float4*)(p.dt_bias + l * 32 + c);
;                     const f32x4 v = acc[i][j];
;                     *(float4*)(p.dtb + (size_t)row * 32 + c) =
;                         make_float4(softplusf(v[0] + db.x), softplusf(v[1] + db.y), softplusf(v[2] + db.z), softplusf(v[3] + db.w));
	v_mov_b32_e32 v89, v99
	v_mov_b32_e32 v87, v91
	v_cndmask_b32_e32 v83, v162, v83, vcc
	v_cmp_lt_f32_e64 vcc, |v97|, s9
	v_cndmask_b32_e64 v83, v83, v128, s[0:1]
	v_pk_add_f32 v[86:87], v[88:89], v[86:87]
	v_cndmask_b32_e32 v82, v82, v97, vcc
	v_pk_add_f32 v[78:79], v[78:79], v[82:83]
	v_cvt_f32_i32_e32 v83, v132
	v_cvt_f32_i32_e32 v82, v130
	v_pk_add_f32 v[88:89], v[90:91], v[98:99]
	v_cmp_neq_f32_e32 vcc, s8, v129
	v_mov_b32_e32 v112, v88
	v_pk_mul_f32 v[84:85], v[82:83], s[12:13] op_sel_hi:[1,0]
	v_mov_b32_e32 v117, v89
	v_pk_fma_f32 v[92:93], v[82:83], s[12:13], v[84:85] op_sel_hi:[1,0,1] neg_lo:[0,0,1] neg_hi:[0,0,1]
	v_mov_b32_e32 v94, v84
	v_pk_fma_f32 v[82:83], v[82:83], s[14:15], v[92:93] op_sel_hi:[1,0,1]
	v_cmp_lt_f32_e64 s[0:1], |v131|, s9
	v_pk_add_f32 v[92:93], v[84:85], v[82:83]
	v_mov_b32_e32 v110, v82
	v_pk_add_f32 v[100:101], v[92:93], v[88:89]
	v_mov_b32_e32 v115, v93
	v_mov_b32_e32 v113, v101
	v_pk_add_f32 v[112:113], v[112:113], v[114:115] neg_lo:[0,1] neg_hi:[0,1]
	v_pk_add_f32 v[94:95], v[94:95], v[110:111]
	v_mov_b32_e32 v102, v100
	v_mov_b32_e32 v103, v93
	v_mov_b32_e32 v110, v92
	v_mov_b32_e32 v111, v85
	v_mov_b32_e32 v114, v92
	v_mov_b32_e32 v115, v101
	v_mov_b32_e32 v85, v113
	v_pk_add_f32 v[102:103], v[102:103], v[110:111] neg_lo:[0,1] neg_hi:[0,1]
	v_mov_b32_e32 v110, v88
	v_mov_b32_e32 v111, v83
	v_pk_add_f32 v[84:85], v[114:115], v[84:85] neg_lo:[0,1] neg_hi:[0,1]
	v_pk_add_f32 v[110:111], v[110:111], v[102:103] neg_lo:[0,1] neg_hi:[0,1]
	v_mov_b32_e32 v114, v84
	v_mov_b32_e32 v115, v103
	v_mov_b32_e32 v116, v100
	v_mov_b32_e32 v103, v91
	v_pk_add_f32 v[114:115], v[82:83], v[114:115] neg_lo:[0,1] neg_hi:[0,1]
	v_pk_add_f32 v[102:103], v[116:117], v[102:103] neg_lo:[0,1] neg_hi:[0,1]
	v_mov_b32_e32 v83, v93
	v_pk_add_f32 v[88:89], v[88:89], v[90:91] neg_lo:[0,1] neg_hi:[0,1]
	v_pk_add_f32 v[90:91], v[94:95], v[102:103] neg_lo:[0,1] neg_hi:[0,1]
	v_pk_add_f32 v[82:83], v[82:83], v[84:85] neg_lo:[0,1] neg_hi:[0,1]
	v_pk_add_f32 v[84:85], v[86:87], v[112:113] neg_lo:[0,1] neg_hi:[0,1]
	v_pk_add_f32 v[92:93], v[110:111], v[90:91]
	v_pk_add_f32 v[86:87], v[84:85], v[82:83]
	v_mov_b32_e32 v83, v111
	v_mov_b32_e32 v85, v91
	v_pk_add_f32 v[84:85], v[82:83], v[84:85]
	v_mov_b32_e32 v90, v86
	v_pk_add_f32 v[84:85], v[84:85], v[114:115] neg_lo:[0,1] neg_hi:[0,1]
	v_mov_b32_e32 v91, v93
	v_pk_add_f32 v[88:89], v[98:99], v[88:89] neg_lo:[0,1] neg_hi:[0,1]
	v_pk_add_f32 v[90:91], v[90:91], v[84:85] neg_lo:[0,1] neg_hi:[0,1]
	v_pk_add_f32 v[84:85], v[88:89], v[84:85] neg_lo:[0,1] neg_hi:[0,1]
	v_pk_add_f32 v[82:83], v[82:83], v[90:91] neg_lo:[0,1] neg_hi:[0,1]
	s_nop 0
	v_pk_add_f32 v[82:83], v[84:85], v[82:83]
	v_pk_add_f32 v[84:85], v[92:93], v[86:87]
	s_nop 0
	v_pk_add_f32 v[86:87], v[100:101], v[84:85]
	s_nop 0
	v_pk_add_f32 v[88:89], v[86:87], v[100:101] neg_lo:[0,1] neg_hi:[0,1]
	s_nop 0
	v_pk_add_f32 v[84:85], v[84:85], v[88:89] neg_lo:[0,1] neg_hi:[0,1]
	s_nop 0
	v_pk_add_f32 v[82:83], v[82:83], v[84:85]
	s_nop 0
	v_pk_add_f32 v[82:83], v[86:87], v[82:83]
	s_nop 0
	v_cndmask_b32_e32 v82, v160, v82, vcc
	v_cmp_neq_f32_e32 vcc, s8, v131
	s_nop 1
	v_cndmask_b32_e32 v83, v160, v83, vcc
	v_cmp_ngt_f32_e32 vcc, -1.0, v131
	s_nop 1
	v_cndmask_b32_e32 v83, v161, v83, vcc
	v_cmp_ngt_f32_e32 vcc, -1.0, v129
	s_nop 1
	v_cndmask_b32_e32 v82, v161, v82, vcc
	v_cmp_neq_f32_e32 vcc, -1.0, v129
	s_nop 1
	v_cndmask_b32_e32 v82, v162, v82, vcc
	v_cmp_neq_f32_e32 vcc, -1.0, v131
	s_nop 1
	v_cndmask_b32_e32 v83, v162, v83, vcc
	v_cmp_lt_f32_e64 vcc, |v129|, s9
	v_cndmask_b32_e64 v83, v83, v131, s[0:1]
	s_nop 0
	v_cndmask_b32_e32 v82, v82, v129, vcc
	v_pk_add_f32 v[80:81], v[80:81], v[82:83]
	global_store_dwordx4 v[76:77], v[78:81], off
	global_load_dwordx4 v[78:81], v0, s[74:75] offset:64
	s_waitcnt vmcnt(0)
	v_add_f32_e32 v82, v10, v78
	v_max_f32_e32 v78, 0, v82
	v_mul_f32_e64 v82, |v82|, s2
	v_exp_f32_e32 v97, v82
	s_nop 0
	v_add_f32_e32 v84, 1.0, v97
	v_add_f32_e32 v82, -1.0, v84
	v_sub_f32_e32 v83, v82, v84
	v_add_f32_e32 v83, 1.0, v83
	v_sub_f32_e32 v82, v97, v82
	v_add_f32_e32 v85, v82, v83
	v_frexp_mant_f32_e32 v82, v84
	v_cmp_gt_f32_e32 vcc, s26, v82
	v_cvt_f64_f32_e32 v[82:83], v84
	v_frexp_exp_i32_f64_e32 v82, v[82:83]
	v_subbrev_co_u32_e32 v120, vcc, 0, v82, vcc
	v_sub_u32_e32 v83, 0, v120
	v_ldexp_f32 v82, v84, v83
	v_ldexp_f32 v84, v85, v83
	v_add_f32_e32 v83, v11, v79
	v_max_f32_e32 v79, 0, v83
	v_mul_f32_e64 v83, |v83|, s2
	v_exp_f32_e32 v128, v83
	s_nop 0
	v_add_f32_e32 v83, 1.0, v128
	v_add_f32_e32 v85, -1.0, v83
	v_sub_f32_e32 v86, v85, v83
	v_add_f32_e32 v86, 1.0, v86
	v_sub_f32_e32 v85, v128, v85
	v_add_f32_e32 v85, v85, v86
	v_frexp_mant_f32_e32 v86, v83
	v_cmp_gt_f32_e32 vcc, s26, v86
	v_cvt_f64_f32_e32 v[86:87], v83
	v_frexp_exp_i32_f64_e32 v86, v[86:87]
	v_subbrev_co_u32_e32 v121, vcc, 0, v86, vcc
	v_sub_u32_e32 v86, 0, v121
	v_ldexp_f32 v83, v83, v86
	v_ldexp_f32 v85, v85, v86
	v_pk_add_f32 v[86:87], v[82:83], 1.0 op_sel_hi:[1,0]
	v_pk_add_f32 v[94:95], v[82:83], -1.0 op_sel_hi:[1,0]
	v_pk_add_f32 v[88:89], v[86:87], -1.0 op_sel_hi:[1,0]
	v_pk_add_f32 v[98:99], v[94:95], 1.0 op_sel_hi:[1,0]
	v_pk_add_f32 v[88:89], v[82:83], v[88:89] neg_lo:[0,1] neg_hi:[0,1]
	v_pk_add_f32 v[82:83], v[82:83], v[98:99] neg_lo:[0,1] neg_hi:[0,1]
	v_pk_add_f32 v[88:89], v[84:85], v[88:89]
	v_pk_add_f32 v[82:83], v[84:85], v[82:83]
	v_pk_add_f32 v[90:91], v[86:87], v[88:89]
	v_pk_add_f32 v[84:85], v[94:95], v[82:83]
	v_rcp_f32_e32 v92, v90
	v_rcp_f32_e32 v93, v91
	v_pk_add_f32 v[86:87], v[90:91], v[86:87] neg_lo:[0,1] neg_hi:[0,1]
	v_pk_add_f32 v[94:95], v[84:85], v[94:95] neg_lo:[0,1] neg_hi:[0,1]
; __device__ __forceinline__ float softplusf(float x) { return fmaxf(x, 0.f) + log1pf(__expf(-fabsf(x))); }
; __device__ void phaseA_tile(const Params& p, int l, int mt, int nt, char* smem) {
;     ...
;                 for (int j = 0; j < 2; ++j) {
;                     const int c = j * 16 + g4 * 4;
;                     const float4 db = *(const float4*)(p.dt_bias + l * 32 + c);
;                     const f32x4 v = acc[i][j];
;                     *(float4*)(p.dtb + (size_t)row * 32 + c) =
;                         make_float4(softplusf(v[0] + db.x), softplusf(v[1] + db.y), softplusf(v[2] + db.z), softplusf(v[3] + db.w));
	v_pk_add_f32 v[86:87], v[88:89], v[86:87] neg_lo:[0,1] neg_hi:[0,1]
	v_pk_mul_f32 v[88:89], v[84:85], v[92:93]
	v_pk_add_f32 v[82:83], v[82:83], v[94:95] neg_lo:[0,1] neg_hi:[0,1]
	v_pk_mul_f32 v[94:95], v[90:91], v[88:89]
	v_cmp_lt_f32_e64 s[0:1], |v128|, s9
	v_pk_fma_f32 v[98:99], v[88:89], v[90:91], v[94:95] neg_lo:[0,0,1] neg_hi:[0,0,1]
	s_nop 0
	v_pk_fma_f32 v[98:99], v[88:89], v[86:87], v[98:99]
	s_nop 0
	v_pk_add_f32 v[100:101], v[94:95], v[98:99]
	s_nop 0
	v_pk_add_f32 v[102:103], v[84:85], v[100:101] neg_lo:[0,1] neg_hi:[0,1]
	v_pk_add_f32 v[94:95], v[100:101], v[94:95] neg_lo:[0,1] neg_hi:[0,1]
	v_pk_add_f32 v[84:85], v[84:85], v[102:103] neg_lo:[0,1] neg_hi:[0,1]
	s_nop 0
	v_pk_add_f32 v[84:85], v[84:85], v[100:101] neg_lo:[0,1] neg_hi:[0,1]
	s_nop 0
	v_pk_add_f32 v[82:83], v[82:83], v[84:85]
	v_pk_add_f32 v[84:85], v[94:95], v[98:99] neg_lo:[0,1] neg_hi:[0,1]
	s_nop 0
	v_pk_add_f32 v[82:83], v[84:85], v[82:83]
	s_nop 0
	v_pk_add_f32 v[84:85], v[102:103], v[82:83]
	s_nop 0
	v_pk_mul_f32 v[94:95], v[92:93], v[84:85]
	s_nop 0
	v_pk_mul_f32 v[98:99], v[90:91], v[94:95]
	s_nop 0
	v_pk_fma_f32 v[90:91], v[94:95], v[90:91], v[98:99] neg_lo:[0,0,1] neg_hi:[0,0,1]
	s_nop 0
	v_pk_fma_f32 v[86:87], v[94:95], v[86:87], v[90:91]
	v_pk_add_f32 v[90:91], v[102:103], v[84:85] neg_lo:[0,1] neg_hi:[0,1]
	s_nop 0
	v_pk_add_f32 v[82:83], v[82:83], v[90:91]
	v_pk_add_f32 v[90:91], v[98:99], v[86:87]
	s_nop 0
	v_pk_add_f32 v[100:101], v[84:85], v[90:91] neg_lo:[0,1] neg_hi:[0,1]
	v_pk_add_f32 v[98:99], v[90:91], v[98:99] neg_lo:[0,1] neg_hi:[0,1]
	v_pk_add_f32 v[84:85], v[84:85], v[100:101] neg_lo:[0,1] neg_hi:[0,1]
	s_nop 0
	v_pk_add_f32 v[84:85], v[84:85], v[90:91] neg_lo:[0,1] neg_hi:[0,1]
	s_nop 0
	v_pk_add_f32 v[82:83], v[82:83], v[84:85]
	v_pk_add_f32 v[84:85], v[98:99], v[86:87] neg_lo:[0,1] neg_hi:[0,1]
	s_nop 0
	v_pk_add_f32 v[82:83], v[84:85], v[82:83]
	v_pk_add_f32 v[84:85], v[88:89], v[94:95]
	v_pk_add_f32 v[82:83], v[100:101], v[82:83]
	v_pk_add_f32 v[86:87], v[84:85], v[88:89] neg_lo:[0,1] neg_hi:[0,1]
	v_pk_mul_f32 v[82:83], v[92:93], v[82:83]
	v_pk_add_f32 v[86:87], v[94:95], v[86:87] neg_lo:[0,1] neg_hi:[0,1]
	s_nop 0
	v_pk_add_f32 v[82:83], v[86:87], v[82:83]
	s_nop 0
	v_pk_add_f32 v[86:87], v[84:85], v[82:83]
	s_nop 0
	v_pk_add_f32 v[84:85], v[86:87], v[84:85] neg_lo:[0,1] neg_hi:[0,1]
	v_pk_mul_f32 v[88:89], v[86:87], v[86:87]
	v_pk_add_f32 v[82:83], v[82:83], v[84:85] neg_lo:[0,1] neg_hi:[0,1]
	v_pk_fma_f32 v[90:91], v[88:89], s[28:29], v[66:67] op_sel_hi:[1,0,0]
	v_ldexp_f32 v93, v83, 1
	v_add_f32_e32 v83, v12, v80
	v_max_f32_e32 v80, 0, v83
	v_mul_f32_e64 v83, |v83|, s2
	v_exp_f32_e32 v129, v83
	v_ldexp_f32 v84, v86, 1
	v_pk_fma_f32 v[90:91], v[88:89], v[90:91], s[30:31] op_sel_hi:[1,1,0]
	v_ldexp_f32 v85, v87, 1
	v_add_f32_e32 v83, 1.0, v129
	v_pk_mul_f32 v[86:87], v[86:87], v[88:89]
	v_add_f32_e32 v88, -1.0, v83
	v_sub_f32_e32 v89, v88, v83
	v_add_f32_e32 v89, 1.0, v89
	v_sub_f32_e32 v88, v129, v88
	v_add_f32_e32 v92, v88, v89
	v_frexp_mant_f32_e32 v88, v83
	v_cmp_gt_f32_e32 vcc, s26, v88
	v_cvt_f64_f32_e32 v[88:89], v83
	v_frexp_exp_i32_f64_e32 v88, v[88:89]
	v_subbrev_co_u32_e32 v130, vcc, 0, v88, vcc
	v_sub_u32_e32 v89, 0, v130
	v_ldexp_f32 v88, v83, v89
	v_add_f32_e32 v83, v13, v81
	v_max_f32_e32 v81, 0, v83
	v_mul_f32_e64 v83, |v83|, s2
	v_exp_f32_e32 v131, v83
	v_ldexp_f32 v94, v92, v89
	v_pk_mul_f32 v[86:87], v[86:87], v[90:91]
	v_ldexp_f32 v82, v82, 1
	v_add_f32_e32 v83, 1.0, v131
	v_add_f32_e32 v89, -1.0, v83
	v_sub_f32_e32 v92, v89, v83
	v_add_f32_e32 v92, 1.0, v92
	v_sub_f32_e32 v89, v131, v89
	v_add_f32_e32 v92, v89, v92
	v_frexp_mant_f32_e32 v89, v83
	v_cvt_f64_f32_e32 v[98:99], v83
	v_cmp_gt_f32_e32 vcc, s26, v89
	v_frexp_exp_i32_f64_e32 v89, v[98:99]
	v_pk_add_f32 v[90:91], v[84:85], v[86:87]
	v_subbrev_co_u32_e32 v132, vcc, 0, v89, vcc
	v_sub_u32_e32 v95, 0, v132
	v_ldexp_f32 v89, v83, v95
	v_pk_add_f32 v[98:99], v[88:89], 1.0 op_sel_hi:[1,0]
	v_ldexp_f32 v95, v92, v95
	v_pk_add_f32 v[100:101], v[98:99], -1.0 op_sel_hi:[1,0]
	v_pk_add_f32 v[112:113], v[88:89], -1.0 op_sel_hi:[1,0]
	v_pk_add_f32 v[100:101], v[88:89], v[100:101] neg_lo:[0,1] neg_hi:[0,1]
	v_pk_add_f32 v[114:115], v[112:113], 1.0 op_sel_hi:[1,0]
	v_pk_add_f32 v[100:101], v[94:95], v[100:101]
	v_pk_add_f32 v[88:89], v[88:89], v[114:115] neg_lo:[0,1] neg_hi:[0,1]
	v_pk_add_f32 v[102:103], v[98:99], v[100:101]
	v_pk_add_f32 v[88:89], v[94:95], v[88:89]
	v_rcp_f32_e32 v110, v102
	v_rcp_f32_e32 v111, v103
	v_pk_add_f32 v[94:95], v[112:113], v[88:89]
	v_pk_add_f32 v[98:99], v[102:103], v[98:99] neg_lo:[0,1] neg_hi:[0,1]
	v_pk_add_f32 v[112:113], v[94:95], v[112:113] neg_lo:[0,1] neg_hi:[0,1]
	v_pk_add_f32 v[98:99], v[100:101], v[98:99] neg_lo:[0,1] neg_hi:[0,1]
	v_pk_mul_f32 v[100:101], v[94:95], v[110:111]
	v_pk_add_f32 v[88:89], v[88:89], v[112:113] neg_lo:[0,1] neg_hi:[0,1]
	v_pk_mul_f32 v[112:113], v[102:103], v[100:101]
	v_pk_add_f32 v[84:85], v[90:91], v[84:85] neg_lo:[0,1] neg_hi:[0,1]
	v_pk_fma_f32 v[114:115], v[100:101], v[102:103], v[112:113] neg_lo:[0,0,1] neg_hi:[0,0,1]
	v_pk_add_f32 v[84:85], v[86:87], v[84:85] neg_lo:[0,1] neg_hi:[0,1]
	v_pk_fma_f32 v[114:115], v[100:101], v[98:99], v[114:115]
	v_mov_b32_e32 v87, v85
	v_pk_add_f32 v[116:117], v[112:113], v[114:115]
	v_mov_b32_e32 v83, v93
	v_pk_add_f32 v[118:119], v[94:95], v[116:117] neg_lo:[0,1] neg_hi:[0,1]
	v_pk_add_f32 v[112:113], v[116:117], v[112:113] neg_lo:[0,1] neg_hi:[0,1]
	v_pk_add_f32 v[94:95], v[94:95], v[118:119] neg_lo:[0,1] neg_hi:[0,1]
	v_mov_b32_e32 v124, v90
	v_pk_add_f32 v[94:95], v[94:95], v[116:117] neg_lo:[0,1] neg_hi:[0,1]
	v_cmp_neq_f32_e32 vcc, s8, v97
; __device__ __forceinline__ float softplusf(float x) { return fmaxf(x, 0.f) + log1pf(__expf(-fabsf(x))); }
; __device__ void phaseA_tile(const Params& p, int l, int mt, int nt, char* smem) {
;     ...
;                 for (int j = 0; j < 2; ++j) {
;                     const int c = j * 16 + g4 * 4;
;                     const float4 db = *(const float4*)(p.dt_bias + l * 32 + c);
;                     const f32x4 v = acc[i][j];
;                     *(float4*)(p.dtb + (size_t)row * 32 + c) =
;                         make_float4(softplusf(v[0] + db.x), softplusf(v[1] + db.y), softplusf(v[2] + db.z), softplusf(v[3] + db.w));
	v_pk_add_f32 v[88:89], v[88:89], v[94:95]
	v_pk_add_f32 v[94:95], v[112:113], v[114:115] neg_lo:[0,1] neg_hi:[0,1]
	s_nop 0
	v_pk_add_f32 v[88:89], v[94:95], v[88:89]
	s_nop 0
	v_pk_add_f32 v[94:95], v[118:119], v[88:89]
	s_nop 0
	v_pk_mul_f32 v[112:113], v[110:111], v[94:95]
	s_nop 0
	v_pk_mul_f32 v[114:115], v[102:103], v[112:113]
	s_nop 0
	v_pk_fma_f32 v[102:103], v[112:113], v[102:103], v[114:115] neg_lo:[0,0,1] neg_hi:[0,0,1]
	s_nop 0
	v_pk_fma_f32 v[98:99], v[112:113], v[98:99], v[102:103]
	v_pk_add_f32 v[102:103], v[118:119], v[94:95] neg_lo:[0,1] neg_hi:[0,1]
	s_nop 0
	v_pk_add_f32 v[88:89], v[88:89], v[102:103]
	v_pk_add_f32 v[102:103], v[114:115], v[98:99]
	s_nop 0
	v_pk_add_f32 v[116:117], v[94:95], v[102:103] neg_lo:[0,1] neg_hi:[0,1]
	v_pk_add_f32 v[114:115], v[102:103], v[114:115] neg_lo:[0,1] neg_hi:[0,1]
	v_pk_add_f32 v[94:95], v[94:95], v[116:117] neg_lo:[0,1] neg_hi:[0,1]
	s_nop 0
	v_pk_add_f32 v[94:95], v[94:95], v[102:103] neg_lo:[0,1] neg_hi:[0,1]
	s_nop 0
	v_pk_add_f32 v[88:89], v[88:89], v[94:95]
	v_pk_add_f32 v[94:95], v[114:115], v[98:99] neg_lo:[0,1] neg_hi:[0,1]
	s_nop 0
	v_pk_add_f32 v[88:89], v[94:95], v[88:89]
	v_pk_add_f32 v[94:95], v[100:101], v[112:113]
	v_pk_add_f32 v[88:89], v[116:117], v[88:89]
	v_pk_add_f32 v[98:99], v[94:95], v[100:101] neg_lo:[0,1] neg_hi:[0,1]
	v_pk_mul_f32 v[88:89], v[110:111], v[88:89]
	v_pk_add_f32 v[98:99], v[112:113], v[98:99] neg_lo:[0,1] neg_hi:[0,1]
	s_nop 0
	v_pk_add_f32 v[88:89], v[98:99], v[88:89]
	s_nop 0
	v_pk_add_f32 v[98:99], v[94:95], v[88:89]
	s_nop 0
	v_pk_mul_f32 v[100:101], v[98:99], v[98:99]
	v_pk_add_f32 v[94:95], v[98:99], v[94:95] neg_lo:[0,1] neg_hi:[0,1]
	v_pk_fma_f32 v[102:103], v[100:101], s[28:29], v[66:67] op_sel_hi:[1,0,0]
	v_pk_add_f32 v[88:89], v[88:89], v[94:95] neg_lo:[0,1] neg_hi:[0,1]
	v_ldexp_f32 v94, v98, 1
	v_pk_fma_f32 v[102:103], v[100:101], v[102:103], s[30:31] op_sel_hi:[1,1,0]
	v_ldexp_f32 v95, v99, 1
	v_pk_mul_f32 v[98:99], v[98:99], v[100:101]
	v_cvt_f32_i32_e32 v101, v121
	v_cvt_f32_i32_e32 v100, v120
	v_ldexp_f32 v111, v89, 1
	v_ldexp_f32 v88, v88, 1
	v_mov_b32_e32 v89, v111
	v_pk_mul_f32 v[112:113], v[100:101], s[12:13] op_sel_hi:[1,0]
	s_nop 0
	v_pk_fma_f32 v[114:115], v[100:101], s[12:13], v[112:113] op_sel_hi:[1,0,1] neg_lo:[0,0,1] neg_hi:[0,0,1]
	v_mov_b32_e32 v86, v112
	v_pk_fma_f32 v[100:101], v[100:101], s[14:15], v[114:115] op_sel_hi:[1,0,1]
	v_mov_b32_e32 v121, v113
	v_mov_b32_e32 v92, v100
	v_pk_add_f32 v[86:87], v[86:87], v[92:93]
	v_pk_add_f32 v[92:93], v[82:83], v[84:85]
	v_mov_b32_e32 v85, v91
	v_mov_b32_e32 v83, v93
	v_pk_add_f32 v[114:115], v[112:113], v[100:101]
	v_pk_add_f32 v[82:83], v[82:83], v[84:85]
	v_pk_add_f32 v[84:85], v[90:91], v[92:93]
	v_mov_b32_e32 v125, v115
	v_pk_add_f32 v[116:117], v[114:115], v[84:85]
	v_mov_b32_e32 v122, v84
	v_mov_b32_e32 v123, v117
	v_pk_add_f32 v[122:123], v[122:123], v[124:125] neg_lo:[0,1] neg_hi:[0,1]
	v_mov_b32_e32 v118, v116
	v_mov_b32_e32 v119, v115
	v_mov_b32_e32 v120, v114
	v_mov_b32_e32 v124, v114
	v_mov_b32_e32 v125, v117
	v_mov_b32_e32 v113, v123
	v_pk_add_f32 v[118:119], v[118:119], v[120:121] neg_lo:[0,1] neg_hi:[0,1]
	v_mov_b32_e32 v120, v84
	v_mov_b32_e32 v121, v101
	v_pk_add_f32 v[112:113], v[124:125], v[112:113] neg_lo:[0,1] neg_hi:[0,1]
	v_pk_add_f32 v[120:121], v[120:121], v[118:119] neg_lo:[0,1] neg_hi:[0,1]
	v_mov_b32_e32 v124, v112
	v_mov_b32_e32 v125, v119
	v_mov_b32_e32 v126, v116
	v_mov_b32_e32 v127, v85
	v_mov_b32_e32 v119, v91
	v_pk_add_f32 v[124:125], v[100:101], v[124:125] neg_lo:[0,1] neg_hi:[0,1]
	v_pk_add_f32 v[118:119], v[126:127], v[118:119] neg_lo:[0,1] neg_hi:[0,1]
	v_mov_b32_e32 v101, v115
	v_pk_add_f32 v[84:85], v[84:85], v[90:91] neg_lo:[0,1] neg_hi:[0,1]
	v_pk_add_f32 v[86:87], v[86:87], v[118:119] neg_lo:[0,1] neg_hi:[0,1]
	v_pk_add_f32 v[90:91], v[100:101], v[112:113] neg_lo:[0,1] neg_hi:[0,1]
	v_pk_add_f32 v[82:83], v[82:83], v[122:123] neg_lo:[0,1] neg_hi:[0,1]
	v_pk_add_f32 v[84:85], v[92:93], v[84:85] neg_lo:[0,1] neg_hi:[0,1]
	v_pk_add_f32 v[92:93], v[82:83], v[90:91]
	v_mov_b32_e32 v91, v121
	v_mov_b32_e32 v83, v87
	v_pk_add_f32 v[100:101], v[120:121], v[86:87]
	v_pk_add_f32 v[82:83], v[90:91], v[82:83]
	v_mov_b32_e32 v86, v92
	v_pk_add_f32 v[82:83], v[82:83], v[124:125] neg_lo:[0,1] neg_hi:[0,1]
	v_mov_b32_e32 v87, v101
	v_pk_add_f32 v[86:87], v[86:87], v[82:83] neg_lo:[0,1] neg_hi:[0,1]
	v_pk_add_f32 v[82:83], v[84:85], v[82:83] neg_lo:[0,1] neg_hi:[0,1]
	v_pk_add_f32 v[86:87], v[90:91], v[86:87] neg_lo:[0,1] neg_hi:[0,1]
	v_pk_add_f32 v[84:85], v[100:101], v[92:93]
	v_pk_add_f32 v[82:83], v[82:83], v[86:87]
	v_pk_add_f32 v[86:87], v[116:117], v[84:85]
	s_nop 0
	v_pk_add_f32 v[90:91], v[86:87], v[116:117] neg_lo:[0,1] neg_hi:[0,1]
	s_nop 0
	v_pk_add_f32 v[84:85], v[84:85], v[90:91] neg_lo:[0,1] neg_hi:[0,1]
	s_nop 0
	v_pk_add_f32 v[82:83], v[82:83], v[84:85]
	s_nop 0
	v_pk_add_f32 v[82:83], v[86:87], v[82:83]
	v_pk_mul_f32 v[86:87], v[98:99], v[102:103]
	v_cndmask_b32_e32 v82, v160, v82, vcc
	v_cmp_neq_f32_e32 vcc, s8, v128
	v_pk_add_f32 v[90:91], v[94:95], v[86:87]
	s_nop 0
	v_cndmask_b32_e32 v83, v160, v83, vcc
	v_cmp_ngt_f32_e32 vcc, -1.0, v128
	v_pk_add_f32 v[94:95], v[90:91], v[94:95] neg_lo:[0,1] neg_hi:[0,1]
	v_mov_b32_e32 v114, v90
	v_cndmask_b32_e32 v83, v161, v83, vcc
	v_cmp_ngt_f32_e32 vcc, -1.0, v97
	v_pk_add_f32 v[86:87], v[86:87], v[94:95] neg_lo:[0,1] neg_hi:[0,1]
	s_nop 0
	v_cndmask_b32_e32 v82, v161, v82, vcc
	v_cmp_neq_f32_e32 vcc, -1.0, v97
	v_pk_add_f32 v[98:99], v[88:89], v[86:87]
	v_mov_b32_e32 v95, v87
	v_cndmask_b32_e32 v82, v162, v82, vcc
	v_cmp_neq_f32_e32 vcc, -1.0, v128
	v_mov_b32_e32 v89, v99
; __device__ __forceinline__ float softplusf(float x) { return fmaxf(x, 0.f) + log1pf(__expf(-fabsf(x))); }
; __device__ __forceinline__ float logsigf(float x) { return fminf(x, 0.f) - log1pf(__expf(-fabsf(x))); }
; __device__ void phaseA_tile(const Params& p, int l, int mt, int nt, char* smem) {
;     ...
;                 for (int j = 0; j < 2; ++j) {
;                     const int c = j * 16 + g4 * 4;
;                     const float4 db = *(const float4*)(p.dt_bias + l * 32 + c);
;                     const f32x4 v = acc[i][j];
;                     *(float4*)(p.dtb + (size_t)row * 32 + c) =
;                         make_float4(softplusf(v[0] + db.x), softplusf(v[1] + db.y), softplusf(v[2] + db.z), softplusf(v[3] + db.w));
;                 }
;                 {
;                     const int c = g4 * 4;
;                     const float4 fb = *(const float4*)(p.b_f + l * 16 + c);
;                     const f32x4 v = acc[i][2];
;                     float4 lf = make_float4(logsigf(v[0] + fb.x), logsigf(v[1] + fb.y), logsigf(v[2] + fb.z), logsigf(v[3] + fb.w));
	v_mov_b32_e32 v87, v91
	v_cndmask_b32_e32 v83, v162, v83, vcc
	v_cmp_lt_f32_e64 vcc, |v97|, s9
	v_cndmask_b32_e64 v83, v83, v128, s[0:1]
	v_pk_add_f32 v[86:87], v[88:89], v[86:87]
	v_cndmask_b32_e32 v82, v82, v97, vcc
	v_pk_add_f32 v[78:79], v[78:79], v[82:83]
	v_cvt_f32_i32_e32 v83, v132
	v_cvt_f32_i32_e32 v82, v130
	v_pk_add_f32 v[88:89], v[90:91], v[98:99]
	v_cmp_neq_f32_e32 vcc, s8, v129
	v_mov_b32_e32 v112, v88
	v_pk_mul_f32 v[84:85], v[82:83], s[12:13] op_sel_hi:[1,0]
	v_mov_b32_e32 v117, v89
	v_pk_fma_f32 v[92:93], v[82:83], s[12:13], v[84:85] op_sel_hi:[1,0,1] neg_lo:[0,0,1] neg_hi:[0,0,1]
	v_mov_b32_e32 v94, v84
	v_pk_fma_f32 v[82:83], v[82:83], s[14:15], v[92:93] op_sel_hi:[1,0,1]
	v_cmp_lt_f32_e64 s[0:1], |v131|, s9
	v_pk_add_f32 v[92:93], v[84:85], v[82:83]
	v_mov_b32_e32 v110, v82
	v_pk_add_f32 v[100:101], v[92:93], v[88:89]
	v_mov_b32_e32 v115, v93
	v_mov_b32_e32 v113, v101
	v_pk_add_f32 v[112:113], v[112:113], v[114:115] neg_lo:[0,1] neg_hi:[0,1]
	v_pk_add_f32 v[94:95], v[94:95], v[110:111]
	v_mov_b32_e32 v102, v100
	v_mov_b32_e32 v103, v93
	v_mov_b32_e32 v110, v92
	v_mov_b32_e32 v111, v85
	v_mov_b32_e32 v114, v92
	v_mov_b32_e32 v115, v101
	v_mov_b32_e32 v85, v113
	v_pk_add_f32 v[102:103], v[102:103], v[110:111] neg_lo:[0,1] neg_hi:[0,1]
	v_mov_b32_e32 v110, v88
	v_mov_b32_e32 v111, v83
	v_pk_add_f32 v[84:85], v[114:115], v[84:85] neg_lo:[0,1] neg_hi:[0,1]
	v_pk_add_f32 v[110:111], v[110:111], v[102:103] neg_lo:[0,1] neg_hi:[0,1]
	v_mov_b32_e32 v114, v84
	v_mov_b32_e32 v115, v103
	v_mov_b32_e32 v116, v100
	v_mov_b32_e32 v103, v91
	v_pk_add_f32 v[114:115], v[82:83], v[114:115] neg_lo:[0,1] neg_hi:[0,1]
	v_pk_add_f32 v[102:103], v[116:117], v[102:103] neg_lo:[0,1] neg_hi:[0,1]
	v_mov_b32_e32 v83, v93
	v_pk_add_f32 v[88:89], v[88:89], v[90:91] neg_lo:[0,1] neg_hi:[0,1]
	v_pk_add_f32 v[90:91], v[94:95], v[102:103] neg_lo:[0,1] neg_hi:[0,1]
	v_pk_add_f32 v[82:83], v[82:83], v[84:85] neg_lo:[0,1] neg_hi:[0,1]
	v_pk_add_f32 v[84:85], v[86:87], v[112:113] neg_lo:[0,1] neg_hi:[0,1]
	v_pk_add_f32 v[92:93], v[110:111], v[90:91]
	v_pk_add_f32 v[86:87], v[84:85], v[82:83]
	v_mov_b32_e32 v83, v111
	v_mov_b32_e32 v85, v91
	v_pk_add_f32 v[84:85], v[82:83], v[84:85]
	v_mov_b32_e32 v90, v86
	v_pk_add_f32 v[84:85], v[84:85], v[114:115] neg_lo:[0,1] neg_hi:[0,1]
	v_mov_b32_e32 v91, v93
	v_pk_add_f32 v[88:89], v[98:99], v[88:89] neg_lo:[0,1] neg_hi:[0,1]
	v_pk_add_f32 v[90:91], v[90:91], v[84:85] neg_lo:[0,1] neg_hi:[0,1]
	v_pk_add_f32 v[84:85], v[88:89], v[84:85] neg_lo:[0,1] neg_hi:[0,1]
	v_pk_add_f32 v[82:83], v[82:83], v[90:91] neg_lo:[0,1] neg_hi:[0,1]
	s_nop 0
	v_pk_add_f32 v[82:83], v[84:85], v[82:83]
	v_pk_add_f32 v[84:85], v[92:93], v[86:87]
	s_nop 0
	v_pk_add_f32 v[86:87], v[100:101], v[84:85]
	s_nop 0
	v_pk_add_f32 v[88:89], v[86:87], v[100:101] neg_lo:[0,1] neg_hi:[0,1]
	s_nop 0
	v_pk_add_f32 v[84:85], v[84:85], v[88:89] neg_lo:[0,1] neg_hi:[0,1]
	s_nop 0
	v_pk_add_f32 v[82:83], v[82:83], v[84:85]
	s_nop 0
	v_pk_add_f32 v[82:83], v[86:87], v[82:83]
	s_nop 0
	v_cndmask_b32_e32 v82, v160, v82, vcc
	v_cmp_neq_f32_e32 vcc, s8, v131
	s_nop 1
	v_cndmask_b32_e32 v83, v160, v83, vcc
	v_cmp_ngt_f32_e32 vcc, -1.0, v131
	s_nop 1
	v_cndmask_b32_e32 v83, v161, v83, vcc
	v_cmp_ngt_f32_e32 vcc, -1.0, v129
	s_nop 1
	v_cndmask_b32_e32 v82, v161, v82, vcc
	v_cmp_neq_f32_e32 vcc, -1.0, v129
	s_nop 1
	v_cndmask_b32_e32 v82, v162, v82, vcc
	v_cmp_neq_f32_e32 vcc, -1.0, v131
	s_nop 1
	v_cndmask_b32_e32 v83, v162, v83, vcc
	v_cmp_lt_f32_e64 vcc, |v129|, s9
	v_cndmask_b32_e64 v83, v83, v131, s[0:1]
	s_nop 0
	v_cndmask_b32_e32 v82, v82, v129, vcc
	v_pk_add_f32 v[80:81], v[80:81], v[82:83]
	global_store_dwordx4 v[76:77], v[78:81], off offset:64
	global_load_dwordx4 v[76:79], v0, s[78:79]
	s_waitcnt vmcnt(0)
	v_add_f32_e32 v80, v6, v76
	v_min_f32_e32 v76, 0, v80
	v_mul_f32_e64 v80, |v80|, s2
	v_exp_f32_e32 v97, v80
	s_nop 0
	v_add_f32_e32 v82, 1.0, v97
	v_add_f32_e32 v80, -1.0, v82
	v_sub_f32_e32 v81, v80, v82
	v_add_f32_e32 v81, 1.0, v81
	v_sub_f32_e32 v80, v97, v80
	v_add_f32_e32 v83, v80, v81
	v_frexp_mant_f32_e32 v80, v82
	v_cmp_gt_f32_e32 vcc, s26, v80
	v_cvt_f64_f32_e32 v[80:81], v82
	v_frexp_exp_i32_f64_e32 v80, v[80:81]
	v_subbrev_co_u32_e32 v118, vcc, 0, v80, vcc
	v_sub_u32_e32 v81, 0, v118
	v_ldexp_f32 v80, v82, v81
	v_ldexp_f32 v82, v83, v81
	v_add_f32_e32 v81, v7, v77
	v_min_f32_e32 v77, 0, v81
	v_mul_f32_e64 v81, |v81|, s2
	v_exp_f32_e32 v124, v81
	s_nop 0
	v_add_f32_e32 v81, 1.0, v124
	v_add_f32_e32 v83, -1.0, v81
	v_sub_f32_e32 v84, v83, v81
	v_add_f32_e32 v84, 1.0, v84
	v_sub_f32_e32 v83, v124, v83
	v_add_f32_e32 v83, v83, v84
	v_frexp_mant_f32_e32 v84, v81
	v_cmp_gt_f32_e32 vcc, s26, v84
	v_cvt_f64_f32_e32 v[84:85], v81
	v_frexp_exp_i32_f64_e32 v84, v[84:85]
	v_subbrev_co_u32_e32 v119, vcc, 0, v84, vcc
	v_sub_u32_e32 v84, 0, v119
	v_ldexp_f32 v81, v81, v84
	v_ldexp_f32 v83, v83, v84
	v_pk_add_f32 v[84:85], v[80:81], 1.0 op_sel_hi:[1,0]
	v_pk_add_f32 v[92:93], v[80:81], -1.0 op_sel_hi:[1,0]
	v_pk_add_f32 v[86:87], v[84:85], -1.0 op_sel_hi:[1,0]
	v_pk_add_f32 v[94:95], v[92:93], 1.0 op_sel_hi:[1,0]
	v_pk_add_f32 v[86:87], v[80:81], v[86:87] neg_lo:[0,1] neg_hi:[0,1]
	v_pk_add_f32 v[80:81], v[80:81], v[94:95] neg_lo:[0,1] neg_hi:[0,1]
	v_pk_add_f32 v[86:87], v[82:83], v[86:87]
	v_pk_add_f32 v[80:81], v[82:83], v[80:81]
	v_pk_add_f32 v[88:89], v[84:85], v[86:87]
	v_pk_add_f32 v[82:83], v[92:93], v[80:81]
	v_rcp_f32_e32 v90, v88
	v_rcp_f32_e32 v91, v89
	v_pk_add_f32 v[84:85], v[88:89], v[84:85] neg_lo:[0,1] neg_hi:[0,1]
	v_pk_add_f32 v[92:93], v[82:83], v[92:93] neg_lo:[0,1] neg_hi:[0,1]
	v_pk_add_f32 v[84:85], v[86:87], v[84:85] neg_lo:[0,1] neg_hi:[0,1]
; __device__ __forceinline__ float logsigf(float x) { return fminf(x, 0.f) - log1pf(__expf(-fabsf(x))); }
; __device__ void phaseA_tile(const Params& p, int l, int mt, int nt, char* smem) {
;     ...
;                 {
;                     const int c = g4 * 4;
;                     const float4 fb = *(const float4*)(p.b_f + l * 16 + c);
;                     const f32x4 v = acc[i][2];
;                     float4 lf = make_float4(logsigf(v[0] + fb.x), logsigf(v[1] + fb.y), logsigf(v[2] + fb.z), logsigf(v[3] + fb.w));
	v_pk_mul_f32 v[86:87], v[82:83], v[90:91]
	v_pk_add_f32 v[80:81], v[80:81], v[92:93] neg_lo:[0,1] neg_hi:[0,1]
	v_pk_mul_f32 v[92:93], v[88:89], v[86:87]
	v_cmp_lt_f32_e64 s[0:1], |v124|, s9
	v_pk_fma_f32 v[94:95], v[86:87], v[88:89], v[92:93] neg_lo:[0,0,1] neg_hi:[0,0,1]
	s_nop 0
	v_pk_fma_f32 v[94:95], v[86:87], v[84:85], v[94:95]
	s_nop 0
	v_pk_add_f32 v[98:99], v[92:93], v[94:95]
	s_nop 0
	v_pk_add_f32 v[100:101], v[82:83], v[98:99] neg_lo:[0,1] neg_hi:[0,1]
	v_pk_add_f32 v[92:93], v[98:99], v[92:93] neg_lo:[0,1] neg_hi:[0,1]
	v_pk_add_f32 v[82:83], v[82:83], v[100:101] neg_lo:[0,1] neg_hi:[0,1]
	s_nop 0
	v_pk_add_f32 v[82:83], v[82:83], v[98:99] neg_lo:[0,1] neg_hi:[0,1]
	s_nop 0
	v_pk_add_f32 v[80:81], v[80:81], v[82:83]
	v_pk_add_f32 v[82:83], v[92:93], v[94:95] neg_lo:[0,1] neg_hi:[0,1]
	s_nop 0
	v_pk_add_f32 v[80:81], v[82:83], v[80:81]
	s_nop 0
	v_pk_add_f32 v[82:83], v[100:101], v[80:81]
	s_nop 0
	v_pk_mul_f32 v[92:93], v[90:91], v[82:83]
	s_nop 0
	v_pk_mul_f32 v[94:95], v[88:89], v[92:93]
	s_nop 0
	v_pk_fma_f32 v[88:89], v[92:93], v[88:89], v[94:95] neg_lo:[0,0,1] neg_hi:[0,0,1]
	s_nop 0
	v_pk_fma_f32 v[84:85], v[92:93], v[84:85], v[88:89]
	v_pk_add_f32 v[88:89], v[100:101], v[82:83] neg_lo:[0,1] neg_hi:[0,1]
	s_nop 0
	v_pk_add_f32 v[80:81], v[80:81], v[88:89]
	v_pk_add_f32 v[88:89], v[94:95], v[84:85]
	s_nop 0
	v_pk_add_f32 v[98:99], v[82:83], v[88:89] neg_lo:[0,1] neg_hi:[0,1]
	v_pk_add_f32 v[94:95], v[88:89], v[94:95] neg_lo:[0,1] neg_hi:[0,1]
	v_pk_add_f32 v[82:83], v[82:83], v[98:99] neg_lo:[0,1] neg_hi:[0,1]
	s_nop 0
	v_pk_add_f32 v[82:83], v[82:83], v[88:89] neg_lo:[0,1] neg_hi:[0,1]
	s_nop 0
	v_pk_add_f32 v[80:81], v[80:81], v[82:83]
	v_pk_add_f32 v[82:83], v[94:95], v[84:85] neg_lo:[0,1] neg_hi:[0,1]
	s_nop 0
	v_pk_add_f32 v[80:81], v[82:83], v[80:81]
	v_pk_add_f32 v[82:83], v[86:87], v[92:93]
	v_pk_add_f32 v[80:81], v[98:99], v[80:81]
	v_pk_add_f32 v[84:85], v[82:83], v[86:87] neg_lo:[0,1] neg_hi:[0,1]
	v_pk_mul_f32 v[80:81], v[90:91], v[80:81]
	v_pk_add_f32 v[84:85], v[92:93], v[84:85] neg_lo:[0,1] neg_hi:[0,1]
	s_nop 0
	v_pk_add_f32 v[80:81], v[84:85], v[80:81]
	s_nop 0
	v_pk_add_f32 v[84:85], v[82:83], v[80:81]
	s_nop 0
	v_pk_add_f32 v[82:83], v[84:85], v[82:83] neg_lo:[0,1] neg_hi:[0,1]
	v_pk_mul_f32 v[86:87], v[84:85], v[84:85]
	v_pk_add_f32 v[80:81], v[80:81], v[82:83] neg_lo:[0,1] neg_hi:[0,1]
	v_pk_fma_f32 v[88:89], v[86:87], s[28:29], v[66:67] op_sel_hi:[1,0,0]
	v_ldexp_f32 v91, v81, 1
	v_add_f32_e32 v81, v8, v78
	v_min_f32_e32 v78, 0, v81
	v_mul_f32_e64 v81, |v81|, s2
	v_exp_f32_e32 v125, v81
	v_ldexp_f32 v82, v84, 1
	v_pk_fma_f32 v[88:89], v[86:87], v[88:89], s[30:31] op_sel_hi:[1,1,0]
	v_ldexp_f32 v83, v85, 1
	v_add_f32_e32 v81, 1.0, v125
	v_pk_mul_f32 v[84:85], v[84:85], v[86:87]
	v_add_f32_e32 v86, -1.0, v81
	v_sub_f32_e32 v87, v86, v81
	v_add_f32_e32 v87, 1.0, v87
	v_sub_f32_e32 v86, v125, v86
	v_add_f32_e32 v90, v86, v87
	v_frexp_mant_f32_e32 v86, v81
	v_cmp_gt_f32_e32 vcc, s26, v86
	v_cvt_f64_f32_e32 v[86:87], v81
	v_frexp_exp_i32_f64_e32 v86, v[86:87]
	v_subbrev_co_u32_e32 v126, vcc, 0, v86, vcc
	v_sub_u32_e32 v87, 0, v126
	v_ldexp_f32 v86, v81, v87
	v_add_f32_e32 v81, v9, v79
	v_min_f32_e32 v79, 0, v81
	v_mul_f32_e64 v81, |v81|, s2
	v_exp_f32_e32 v127, v81
	v_ldexp_f32 v92, v90, v87
	v_pk_mul_f32 v[84:85], v[84:85], v[88:89]
	v_ldexp_f32 v80, v80, 1
	v_add_f32_e32 v81, 1.0, v127
	v_add_f32_e32 v87, -1.0, v81
	v_sub_f32_e32 v90, v87, v81
	v_add_f32_e32 v90, 1.0, v90
	v_sub_f32_e32 v87, v127, v87
	v_add_f32_e32 v90, v87, v90
	v_frexp_mant_f32_e32 v87, v81
	v_cvt_f64_f32_e32 v[94:95], v81
	v_cmp_gt_f32_e32 vcc, s26, v87
	v_frexp_exp_i32_f64_e32 v87, v[94:95]
	v_pk_add_f32 v[88:89], v[82:83], v[84:85]
	v_subbrev_co_u32_e32 v128, vcc, 0, v87, vcc
	v_sub_u32_e32 v93, 0, v128
	v_ldexp_f32 v87, v81, v93
	v_pk_add_f32 v[94:95], v[86:87], 1.0 op_sel_hi:[1,0]
	v_ldexp_f32 v93, v90, v93
	v_pk_add_f32 v[98:99], v[94:95], -1.0 op_sel_hi:[1,0]
	v_pk_add_f32 v[110:111], v[86:87], -1.0 op_sel_hi:[1,0]
	v_pk_add_f32 v[98:99], v[86:87], v[98:99] neg_lo:[0,1] neg_hi:[0,1]
	v_pk_add_f32 v[112:113], v[110:111], 1.0 op_sel_hi:[1,0]
	v_pk_add_f32 v[98:99], v[92:93], v[98:99]
	v_pk_add_f32 v[86:87], v[86:87], v[112:113] neg_lo:[0,1] neg_hi:[0,1]
	v_pk_add_f32 v[100:101], v[94:95], v[98:99]
	v_pk_add_f32 v[86:87], v[92:93], v[86:87]
	v_rcp_f32_e32 v102, v100
	v_rcp_f32_e32 v103, v101
	v_pk_add_f32 v[92:93], v[110:111], v[86:87]
	v_pk_add_f32 v[94:95], v[100:101], v[94:95] neg_lo:[0,1] neg_hi:[0,1]
	v_pk_add_f32 v[110:111], v[92:93], v[110:111] neg_lo:[0,1] neg_hi:[0,1]
	v_pk_add_f32 v[94:95], v[98:99], v[94:95] neg_lo:[0,1] neg_hi:[0,1]
	v_pk_mul_f32 v[98:99], v[92:93], v[102:103]
	v_pk_add_f32 v[86:87], v[86:87], v[110:111] neg_lo:[0,1] neg_hi:[0,1]
	v_pk_mul_f32 v[110:111], v[100:101], v[98:99]
	v_pk_add_f32 v[82:83], v[88:89], v[82:83] neg_lo:[0,1] neg_hi:[0,1]
	v_pk_fma_f32 v[112:113], v[98:99], v[100:101], v[110:111] neg_lo:[0,0,1] neg_hi:[0,0,1]
	v_pk_add_f32 v[82:83], v[84:85], v[82:83] neg_lo:[0,1] neg_hi:[0,1]
	v_pk_fma_f32 v[112:113], v[98:99], v[94:95], v[112:113]
	v_mov_b32_e32 v85, v83
	v_pk_add_f32 v[114:115], v[110:111], v[112:113]
	v_mov_b32_e32 v81, v91
	v_pk_add_f32 v[116:117], v[92:93], v[114:115] neg_lo:[0,1] neg_hi:[0,1]
	v_pk_add_f32 v[110:111], v[114:115], v[110:111] neg_lo:[0,1] neg_hi:[0,1]
	v_pk_add_f32 v[92:93], v[92:93], v[116:117] neg_lo:[0,1] neg_hi:[0,1]
	v_mov_b32_e32 v120, v88
	v_pk_add_f32 v[92:93], v[92:93], v[114:115] neg_lo:[0,1] neg_hi:[0,1]
	v_cmp_neq_f32_e32 vcc, s8, v97
	v_pk_add_f32 v[86:87], v[86:87], v[92:93]
	v_pk_add_f32 v[92:93], v[110:111], v[112:113] neg_lo:[0,1] neg_hi:[0,1]
; __device__ __forceinline__ float logsigf(float x) { return fminf(x, 0.f) - log1pf(__expf(-fabsf(x))); }
; __device__ void phaseA_tile(const Params& p, int l, int mt, int nt, char* smem) {
;     ...
;                 {
;                     const int c = g4 * 4;
;                     const float4 fb = *(const float4*)(p.b_f + l * 16 + c);
;                     const f32x4 v = acc[i][2];
;                     float4 lf = make_float4(logsigf(v[0] + fb.x), logsigf(v[1] + fb.y), logsigf(v[2] + fb.z), logsigf(v[3] + fb.w));
;                     float* o = samp ? (p.out + O_LFS + ((size_t)l * TSM + (row - TP)) * 16 + c)
;                                     : (p.out + O_LFP + ((size_t)l * TP + row) * 16 + c);
	s_nop 0
	v_pk_add_f32 v[86:87], v[92:93], v[86:87]
	s_nop 0
	v_pk_add_f32 v[92:93], v[116:117], v[86:87]
	s_nop 0
	v_pk_mul_f32 v[110:111], v[102:103], v[92:93]
	s_nop 0
	v_pk_mul_f32 v[112:113], v[100:101], v[110:111]
	s_nop 0
	v_pk_fma_f32 v[100:101], v[110:111], v[100:101], v[112:113] neg_lo:[0,0,1] neg_hi:[0,0,1]
	s_nop 0
	v_pk_fma_f32 v[94:95], v[110:111], v[94:95], v[100:101]
	v_pk_add_f32 v[100:101], v[116:117], v[92:93] neg_lo:[0,1] neg_hi:[0,1]
	s_nop 0
	v_pk_add_f32 v[86:87], v[86:87], v[100:101]
	v_pk_add_f32 v[100:101], v[112:113], v[94:95]
	s_nop 0
	v_pk_add_f32 v[114:115], v[92:93], v[100:101] neg_lo:[0,1] neg_hi:[0,1]
	v_pk_add_f32 v[112:113], v[100:101], v[112:113] neg_lo:[0,1] neg_hi:[0,1]
	v_pk_add_f32 v[92:93], v[92:93], v[114:115] neg_lo:[0,1] neg_hi:[0,1]
	s_nop 0
	v_pk_add_f32 v[92:93], v[92:93], v[100:101] neg_lo:[0,1] neg_hi:[0,1]
	s_nop 0
	v_pk_add_f32 v[86:87], v[86:87], v[92:93]
	v_pk_add_f32 v[92:93], v[112:113], v[94:95] neg_lo:[0,1] neg_hi:[0,1]
	s_nop 0
	v_pk_add_f32 v[86:87], v[92:93], v[86:87]
	v_pk_add_f32 v[92:93], v[98:99], v[110:111]
	v_pk_add_f32 v[86:87], v[114:115], v[86:87]
	v_pk_add_f32 v[94:95], v[92:93], v[98:99] neg_lo:[0,1] neg_hi:[0,1]
	v_pk_mul_f32 v[86:87], v[102:103], v[86:87]
	v_pk_add_f32 v[94:95], v[110:111], v[94:95] neg_lo:[0,1] neg_hi:[0,1]
	s_nop 0
	v_pk_add_f32 v[86:87], v[94:95], v[86:87]
	s_nop 0
	v_pk_add_f32 v[94:95], v[92:93], v[86:87]
	s_nop 0
	v_pk_mul_f32 v[98:99], v[94:95], v[94:95]
	v_pk_add_f32 v[92:93], v[94:95], v[92:93] neg_lo:[0,1] neg_hi:[0,1]
	v_pk_fma_f32 v[66:67], v[98:99], s[28:29], v[66:67] op_sel_hi:[1,0,0]
	v_pk_add_f32 v[86:87], v[86:87], v[92:93] neg_lo:[0,1] neg_hi:[0,1]
	v_pk_fma_f32 v[100:101], v[98:99], v[66:67], s[30:31] op_sel_hi:[1,1,0]
	v_add_u32_e32 v66, 0xffff8000, v68
	v_ashrrev_i32_e32 v67, 31, v66
	v_cndmask_b32_e64 v67, v69, v67, s[60:61]
	v_cndmask_b32_e64 v66, v68, v66, s[60:61]
	v_cvt_f32_i32_e32 v69, v119
	v_cvt_f32_i32_e32 v68, v118
	v_ldexp_f32 v92, v94, 1
	v_ldexp_f32 v93, v95, 1
	v_pk_mul_f32 v[94:95], v[94:95], v[98:99]
	v_pk_mul_f32 v[98:99], v[68:69], s[12:13] op_sel_hi:[1,0]
	v_ldexp_f32 v103, v87, 1
	v_pk_fma_f32 v[110:111], v[68:69], s[12:13], v[98:99] op_sel_hi:[1,0,1] neg_lo:[0,0,1] neg_hi:[0,0,1]
	v_mov_b32_e32 v84, v98
	v_pk_fma_f32 v[68:69], v[68:69], s[14:15], v[110:111] op_sel_hi:[1,0,1]
	v_mov_b32_e32 v117, v99
	v_mov_b32_e32 v90, v68
	v_pk_add_f32 v[84:85], v[84:85], v[90:91]
	v_pk_add_f32 v[90:91], v[80:81], v[82:83]
	v_mov_b32_e32 v83, v89
	v_mov_b32_e32 v81, v91
	v_pk_add_f32 v[110:111], v[98:99], v[68:69]
	v_pk_add_f32 v[80:81], v[80:81], v[82:83]
	v_pk_add_f32 v[82:83], v[88:89], v[90:91]
	v_mov_b32_e32 v121, v111
	v_pk_add_f32 v[112:113], v[110:111], v[82:83]
	v_mov_b32_e32 v118, v82
	v_mov_b32_e32 v119, v113
	v_pk_add_f32 v[118:119], v[118:119], v[120:121] neg_lo:[0,1] neg_hi:[0,1]
	v_mov_b32_e32 v114, v112
	v_mov_b32_e32 v115, v111
	v_mov_b32_e32 v116, v110
	v_mov_b32_e32 v120, v110
	v_mov_b32_e32 v121, v113
	v_mov_b32_e32 v99, v119
	v_pk_add_f32 v[114:115], v[114:115], v[116:117] neg_lo:[0,1] neg_hi:[0,1]
	v_mov_b32_e32 v116, v82
	v_mov_b32_e32 v117, v69
	v_pk_add_f32 v[98:99], v[120:121], v[98:99] neg_lo:[0,1] neg_hi:[0,1]
	v_pk_add_f32 v[116:117], v[116:117], v[114:115] neg_lo:[0,1] neg_hi:[0,1]
	v_mov_b32_e32 v120, v98
	v_mov_b32_e32 v121, v115
	v_mov_b32_e32 v122, v112
	v_mov_b32_e32 v123, v83
	v_mov_b32_e32 v115, v89
	v_pk_add_f32 v[120:121], v[68:69], v[120:121] neg_lo:[0,1] neg_hi:[0,1]
	v_pk_add_f32 v[114:115], v[122:123], v[114:115] neg_lo:[0,1] neg_hi:[0,1]
	v_mov_b32_e32 v69, v111
	v_pk_add_f32 v[84:85], v[84:85], v[114:115] neg_lo:[0,1] neg_hi:[0,1]
	v_pk_add_f32 v[68:69], v[68:69], v[98:99] neg_lo:[0,1] neg_hi:[0,1]
	v_pk_add_f32 v[80:81], v[80:81], v[118:119] neg_lo:[0,1] neg_hi:[0,1]
	v_pk_add_f32 v[82:83], v[82:83], v[88:89] neg_lo:[0,1] neg_hi:[0,1]
	v_pk_add_f32 v[88:89], v[80:81], v[68:69]
	v_mov_b32_e32 v69, v117
	v_mov_b32_e32 v81, v85
	v_pk_add_f32 v[82:83], v[90:91], v[82:83] neg_lo:[0,1] neg_hi:[0,1]
	v_pk_add_f32 v[90:91], v[116:117], v[84:85]
	v_pk_add_f32 v[80:81], v[68:69], v[80:81]
	v_mov_b32_e32 v84, v88
	v_pk_add_f32 v[80:81], v[80:81], v[120:121] neg_lo:[0,1] neg_hi:[0,1]
	v_mov_b32_e32 v85, v91
	v_pk_add_f32 v[84:85], v[84:85], v[80:81] neg_lo:[0,1] neg_hi:[0,1]
	v_pk_add_f32 v[80:81], v[82:83], v[80:81] neg_lo:[0,1] neg_hi:[0,1]
	v_pk_add_f32 v[68:69], v[68:69], v[84:85] neg_lo:[0,1] neg_hi:[0,1]
	v_ldexp_f32 v86, v86, 1
	v_pk_add_f32 v[68:69], v[80:81], v[68:69]
	v_pk_add_f32 v[80:81], v[90:91], v[88:89]
	v_mov_b32_e32 v87, v103
	v_pk_add_f32 v[82:83], v[112:113], v[80:81]
	v_lshlrev_b64 v[66:67], 6, v[66:67]
	v_pk_add_f32 v[84:85], v[82:83], v[112:113] neg_lo:[0,1] neg_hi:[0,1]
; __device__ void phaseA_tile(const Params& p, int l, int mt, int nt, char* smem) {
;     ...
;                     float* o = samp ? (p.out + O_LFS + ((size_t)l * TSM + (row - TP)) * 16 + c)
;                                     : (p.out + O_LFP + ((size_t)l * TP + row) * 16 + c);
;                     *(float4*)o = lf;
;                     *(float4*)(lf_s + rl * 16 + c) = lf;
	v_lshl_add_u64 v[66:67], s[6:7], 0, v[66:67]
	v_pk_add_f32 v[80:81], v[80:81], v[84:85] neg_lo:[0,1] neg_hi:[0,1]
	v_lshl_add_u64 v[66:67], v[66:67], 0, v[0:1]
	v_pk_add_f32 v[68:69], v[68:69], v[80:81]
	v_lshl_or_b32 v0, v71, 6, v0
	v_pk_add_f32 v[68:69], v[82:83], v[68:69]
	v_pk_mul_f32 v[82:83], v[94:95], v[100:101]
	v_cndmask_b32_e32 v68, v160, v68, vcc
	v_cmp_neq_f32_e32 vcc, s8, v124
	v_pk_add_f32 v[84:85], v[92:93], v[82:83]
	s_nop 0
	v_cndmask_b32_e32 v69, v160, v69, vcc
	v_cmp_ngt_f32_e32 vcc, -1.0, v124
	v_pk_add_f32 v[90:91], v[84:85], v[92:93] neg_lo:[0,1] neg_hi:[0,1]
	v_mov_b32_e32 v110, v84
	v_cndmask_b32_e32 v69, v161, v69, vcc
	v_cmp_ngt_f32_e32 vcc, -1.0, v97
	v_pk_add_f32 v[82:83], v[82:83], v[90:91] neg_lo:[0,1] neg_hi:[0,1]
	s_nop 0
	v_cndmask_b32_e32 v68, v161, v68, vcc
	v_cmp_neq_f32_e32 vcc, -1.0, v97
	v_pk_add_f32 v[92:93], v[86:87], v[82:83]
	v_mov_b32_e32 v91, v83
	v_cndmask_b32_e32 v68, v162, v68, vcc
	v_cmp_neq_f32_e32 vcc, -1.0, v124
	v_mov_b32_e32 v87, v93
	v_mov_b32_e32 v83, v85
	v_cndmask_b32_e32 v69, v162, v69, vcc
	v_cmp_lt_f32_e64 vcc, |v97|, s9
	v_cndmask_b32_e64 v69, v69, v124, s[0:1]
	v_pk_add_f32 v[82:83], v[86:87], v[82:83]
	v_cndmask_b32_e32 v68, v68, v97, vcc
	v_pk_add_f32 v[76:77], v[76:77], v[68:69] neg_lo:[0,1] neg_hi:[0,1]
	v_cvt_f32_i32_e32 v69, v128
	v_cvt_f32_i32_e32 v68, v126
	v_pk_add_f32 v[86:87], v[84:85], v[92:93]
	v_cmp_neq_f32_e32 vcc, s8, v125
	v_mov_b32_e32 v113, v87
	v_pk_mul_f32 v[80:81], v[68:69], s[12:13] op_sel_hi:[1,0]
	v_cmp_lt_f32_e64 s[0:1], |v127|, s9
	v_pk_fma_f32 v[88:89], v[68:69], s[12:13], v[80:81] op_sel_hi:[1,0,1] neg_lo:[0,0,1] neg_hi:[0,0,1]
	v_mov_b32_e32 v90, v80
	v_pk_fma_f32 v[68:69], v[68:69], s[14:15], v[88:89] op_sel_hi:[1,0,1]
	v_mov_b32_e32 v101, v81
	v_pk_add_f32 v[88:89], v[80:81], v[68:69]
	v_mov_b32_e32 v102, v68
	v_pk_add_f32 v[94:95], v[88:89], v[86:87]
	v_pk_add_f32 v[90:91], v[90:91], v[102:103]
	v_mov_b32_e32 v102, v86
	v_mov_b32_e32 v103, v95
	v_mov_b32_e32 v111, v89
	v_pk_add_f32 v[102:103], v[102:103], v[110:111] neg_lo:[0,1] neg_hi:[0,1]
	v_mov_b32_e32 v98, v94
	v_mov_b32_e32 v99, v89
	v_mov_b32_e32 v100, v88
	v_mov_b32_e32 v110, v88
	v_mov_b32_e32 v111, v95
	v_mov_b32_e32 v81, v103
	v_pk_add_f32 v[98:99], v[98:99], v[100:101] neg_lo:[0,1] neg_hi:[0,1]
	v_mov_b32_e32 v100, v86
	v_mov_b32_e32 v101, v69
	v_pk_add_f32 v[80:81], v[110:111], v[80:81] neg_lo:[0,1] neg_hi:[0,1]
	v_pk_add_f32 v[100:101], v[100:101], v[98:99] neg_lo:[0,1] neg_hi:[0,1]
	v_mov_b32_e32 v110, v80
	v_mov_b32_e32 v111, v99
	v_mov_b32_e32 v112, v94
	v_mov_b32_e32 v99, v85
	v_pk_add_f32 v[110:111], v[68:69], v[110:111] neg_lo:[0,1] neg_hi:[0,1]
	v_pk_add_f32 v[98:99], v[112:113], v[98:99] neg_lo:[0,1] neg_hi:[0,1]
	v_mov_b32_e32 v69, v89
	v_pk_add_f32 v[84:85], v[86:87], v[84:85] neg_lo:[0,1] neg_hi:[0,1]
	v_pk_add_f32 v[86:87], v[90:91], v[98:99] neg_lo:[0,1] neg_hi:[0,1]
	v_pk_add_f32 v[68:69], v[68:69], v[80:81] neg_lo:[0,1] neg_hi:[0,1]
	v_pk_add_f32 v[80:81], v[82:83], v[102:103] neg_lo:[0,1] neg_hi:[0,1]
	v_pk_add_f32 v[88:89], v[100:101], v[86:87]
	v_pk_add_f32 v[82:83], v[80:81], v[68:69]
	v_mov_b32_e32 v69, v101
	v_mov_b32_e32 v81, v87
	v_pk_add_f32 v[80:81], v[68:69], v[80:81]
	v_mov_b32_e32 v86, v82
	v_pk_add_f32 v[80:81], v[80:81], v[110:111] neg_lo:[0,1] neg_hi:[0,1]
	v_mov_b32_e32 v87, v89
	v_pk_add_f32 v[84:85], v[92:93], v[84:85] neg_lo:[0,1] neg_hi:[0,1]
	v_pk_add_f32 v[86:87], v[86:87], v[80:81] neg_lo:[0,1] neg_hi:[0,1]
	v_pk_add_f32 v[80:81], v[84:85], v[80:81] neg_lo:[0,1] neg_hi:[0,1]
	v_pk_add_f32 v[68:69], v[68:69], v[86:87] neg_lo:[0,1] neg_hi:[0,1]
	s_nop 0
	v_pk_add_f32 v[68:69], v[80:81], v[68:69]
	v_pk_add_f32 v[80:81], v[88:89], v[82:83]
	s_nop 0
	v_pk_add_f32 v[82:83], v[94:95], v[80:81]
	s_nop 0
	v_pk_add_f32 v[84:85], v[82:83], v[94:95] neg_lo:[0,1] neg_hi:[0,1]
	s_nop 0
	v_pk_add_f32 v[80:81], v[80:81], v[84:85] neg_lo:[0,1] neg_hi:[0,1]
	s_nop 0
	v_pk_add_f32 v[68:69], v[68:69], v[80:81]
	s_nop 0
	v_pk_add_f32 v[68:69], v[82:83], v[68:69]
	s_nop 0
	v_cndmask_b32_e32 v68, v160, v68, vcc
	v_cmp_neq_f32_e32 vcc, s8, v127
	s_nop 1
	v_cndmask_b32_e32 v69, v160, v69, vcc
	v_cmp_ngt_f32_e32 vcc, -1.0, v127
	s_nop 1
	v_cndmask_b32_e32 v69, v161, v69, vcc
	v_cmp_ngt_f32_e32 vcc, -1.0, v125
	s_nop 1
	v_cndmask_b32_e32 v68, v161, v68, vcc
	v_cmp_neq_f32_e32 vcc, -1.0, v125
	s_nop 1
	v_cndmask_b32_e32 v68, v162, v68, vcc
	v_cmp_neq_f32_e32 vcc, -1.0, v127
	s_nop 1
	v_cndmask_b32_e32 v69, v162, v69, vcc
	v_cmp_lt_f32_e64 vcc, |v125|, s9
	v_cndmask_b32_e64 v69, v69, v127, s[0:1]
	s_nop 0
	v_cndmask_b32_e32 v68, v68, v125, vcc
	v_pk_add_f32 v[78:79], v[78:79], v[68:69] neg_lo:[0,1] neg_hi:[0,1]
	global_store_dwordx4 v[66:67], v[76:79], off
	ds_write_b128 v0, v[76:79]
